# v13 with the GEMM template's per-MFMA-block s_setprio toggles removed (strategy: priority; per-segment toggling does not pay)
# speedup vs baseline: 1.0118x; 1.0118x over previous
; #define G_STAGE(bufoff, gbase, v0, v1) do { \
;     __builtin_amdgcn_global_load_lds((const unsigned*)((const char*)(gbase) + (v0)), (LAS unsigned*)(lds + (bufoff) + ldsw), 16, 0, 0); \
;     __builtin_amdgcn_global_load_lds((const unsigned*)((const char*)(gbase) + (v1)), (LAS unsigned*)(lds + (bufoff) + ldsw + 8192), 16, 0, 0); } while (0)
; #define G_LDA(dst, b, h) do { _Pragma("unroll") for (int m = 0; m < 4; ++m) _Pragma("unroll") for (int k = 0; k < 2; ++k) dst[m][k] = *(const LAS h8*)(lds + G_SA(b, h) + aoff + m * 2048 + k * 1024); } while (0)
; #define G_LDB(dst, b, h) do { _Pragma("unroll") for (int n = 0; n < 2; ++n) _Pragma("unroll") for (int k = 0; k < 2; ++k) dst[n][k] = *(const LAS h8*)(lds + G_SB(b, h) + boff + n * 2048 + k * 1024); } while (0)
; #define G_MMA(ai, bj, At, Bt) do { __builtin_amdgcn_s_setprio(1); _Pragma("unroll") for (int m = 0; m < 4; ++m) _Pragma("unroll") for (int n = 0; n < 2; ++n) _Pragma("unroll") for (int k = 0; k < 2; ++k) \
;     acc[ai][bj][m][n] = __builtin_amdgcn_mfma_f32_16x16x32_f16(Bt[n][k], At[m][k], acc[ai][bj][m][n], 0, 0, 0); __builtin_amdgcn_s_setprio(0); } while (0)
; #define G_WAIT_L(n) asm volatile("s_waitcnt lgkmcnt(" #n ")" ::: "memory")
; #define G_BAR __builtin_amdgcn_s_barrier()
; #define G_SCHED __builtin_amdgcn_sched_barrier(0)
; template <bool PERM, class Sched, class Epi>
; DI void gemm256(LAS unsigned char* lds, const Sched& S, const Epi& E, int wv_) {
;     ...
;       G_LDB(B0, 0, 0); G_SCHED; G_LDA(At, 0, 0); G_STAGE(G_SA(1, 1), a1 + chA, cvA0, cvA1);
;       G_WAIT_L(8); G_BAR; G_WAIT_L(0); G_MMA(0, 0, At, B0); G_BAR; G_SCHED;
;       G_LDB(B1, 0, 1); G_STAGE(G_SB(0, 0), b2, cvB0, cvB1);
;       G_BAR; G_WAIT_L(0); G_MMA(0, 1, At, B1); G_BAR;
;       G_LDA(At, 0, 1); G_STAGE(G_SA(0, 0), a2, cvA0, cvA1);
;       G_BAR; G_WAIT_L(0); G_MMA(1, 0, At, B0); G_BAR; G_SCHED;
.LBB0_1503:
	v_or_b32_e32 v146, 0x10000, v143
	v_add_u32_e32 v150, 0x10400, v143
	v_add_u32_e32 v154, 0x10800, v143
	v_add_u32_e32 v158, 0x10c00, v143
	s_add_i32 s91, s12, 2
	ds_read_b128 v[146:149], v146
	ds_read_b128 v[150:153], v150
	ds_read_b128 v[154:157], v154
	ds_read_b128 v[158:161], v158
	s_add_u32 s13, s10, 0xfffc0080
	s_addc_u32 s14, s11, -1
	s_cmp_eq_u32 s75, s12
	s_cselect_b32 s12, s90, s46
	s_cselect_b32 s15, s16, s14
	s_cselect_b32 s14, s17, s13
	s_cselect_b32 s13, s85, s74
	s_mov_b32 m0, s59
	v_lshl_add_u64 v[194:195], s[10:11], 0, v[138:139]
	ds_read_b128 v[162:165], v142
	ds_read_b128 v[166:169], v142 offset:1024
	ds_read_b128 v[170:173], v142 offset:2048
	ds_read_b128 v[174:177], v142 offset:3072
	ds_read_b128 v[178:181], v142 offset:4096
	ds_read_b128 v[182:185], v142 offset:5120
	ds_read_b128 v[186:189], v142 offset:6144
	ds_read_b128 v[190:193], v142 offset:7168
	global_load_lds_dwordx4 v[194:195], off
	v_lshl_add_u64 v[194:195], s[10:11], 0, v[140:141]
	s_mov_b32 m0, s60
	s_nop 0
	global_load_lds_dwordx4 v[194:195], off
	s_waitcnt lgkmcnt(8)
	s_barrier
	s_waitcnt lgkmcnt(0)
	s_waitcnt lgkmcnt(0)
	v_mfma_f32_16x16x32_f16 v[122:125], v[146:149], v[162:165], v[122:125]
	v_mfma_f32_16x16x32_f16 v[126:129], v[154:157], v[162:165], v[126:129]
	v_mfma_f32_16x16x32_f16 v[114:117], v[146:149], v[170:173], v[114:117]
	v_mfma_f32_16x16x32_f16 v[118:121], v[154:157], v[170:173], v[118:121]
	v_mfma_f32_16x16x32_f16 v[106:109], v[146:149], v[178:181], v[106:109]
	v_mfma_f32_16x16x32_f16 v[110:113], v[154:157], v[178:181], v[110:113]
	v_mfma_f32_16x16x32_f16 v[98:101], v[146:149], v[186:189], v[98:101]
	v_mfma_f32_16x16x32_f16 v[102:105], v[154:157], v[186:189], v[102:105]
	v_mfma_f32_16x16x32_f16 v[122:125], v[150:153], v[166:169], v[122:125]
	v_mfma_f32_16x16x32_f16 v[126:129], v[158:161], v[166:169], v[126:129]
	v_mfma_f32_16x16x32_f16 v[114:117], v[150:153], v[174:177], v[114:117]
	v_mfma_f32_16x16x32_f16 v[118:121], v[158:161], v[174:177], v[118:121]
	v_mfma_f32_16x16x32_f16 v[106:109], v[150:153], v[182:185], v[106:109]
	v_mfma_f32_16x16x32_f16 v[110:113], v[158:161], v[182:185], v[110:113]
	v_mfma_f32_16x16x32_f16 v[98:101], v[150:153], v[190:193], v[98:101]
	v_mfma_f32_16x16x32_f16 v[102:105], v[158:161], v[190:193], v[102:105]
	s_barrier
	s_mov_b32 m0, s20
	v_or_b32_e32 v194, 0x14000, v143
	v_add_u32_e32 v198, 0x14400, v143
	v_add_u32_e32 v202, 0x14800, v143
	v_add_u32_e32 v206, 0x14c00, v143
	v_lshl_add_u64 v[210:211], s[12:13], 0, v[132:133]
	ds_read_b128 v[194:197], v194
	ds_read_b128 v[198:201], v198
	ds_read_b128 v[202:205], v202
	ds_read_b128 v[206:209], v206
	global_load_lds_dwordx4 v[210:211], off
	v_lshl_add_u64 v[212:213], s[12:13], 0, v[136:137]
	s_mov_b32 m0, s21
	s_nop 0
	global_load_lds_dwordx4 v[212:213], off
	s_barrier
	s_waitcnt lgkmcnt(0)
	s_waitcnt lgkmcnt(0)
	v_mfma_f32_16x16x32_f16 v[58:61], v[194:197], v[162:165], v[58:61]
	v_mfma_f32_16x16x32_f16 v[62:65], v[202:205], v[162:165], v[62:65]
	v_mfma_f32_16x16x32_f16 v[50:53], v[194:197], v[170:173], v[50:53]
	v_mfma_f32_16x16x32_f16 v[54:57], v[202:205], v[170:173], v[54:57]
	v_mfma_f32_16x16x32_f16 v[42:45], v[194:197], v[178:181], v[42:45]
	v_mfma_f32_16x16x32_f16 v[46:49], v[202:205], v[178:181], v[46:49]
	v_mfma_f32_16x16x32_f16 v[34:37], v[194:197], v[186:189], v[34:37]
	v_mfma_f32_16x16x32_f16 v[38:41], v[202:205], v[186:189], v[38:41]
	v_mfma_f32_16x16x32_f16 v[58:61], v[198:201], v[166:169], v[58:61]
	v_mfma_f32_16x16x32_f16 v[62:65], v[206:209], v[166:169], v[62:65]
	v_mfma_f32_16x16x32_f16 v[50:53], v[198:201], v[174:177], v[50:53]
	v_mfma_f32_16x16x32_f16 v[54:57], v[206:209], v[174:177], v[54:57]
	v_mfma_f32_16x16x32_f16 v[42:45], v[198:201], v[182:185], v[42:45]
	v_mfma_f32_16x16x32_f16 v[46:49], v[206:209], v[182:185], v[46:49]
	v_mfma_f32_16x16x32_f16 v[34:37], v[198:201], v[190:193], v[34:37]
	v_mfma_f32_16x16x32_f16 v[38:41], v[206:209], v[190:193], v[38:41]
	s_mov_b32 m0, s19
	v_lshl_add_u64 v[214:215], s[14:15], 0, v[130:131]
	s_barrier
	ds_read_b128 v[162:165], v142 offset:16384
	ds_read_b128 v[166:169], v142 offset:17408
	ds_read_b128 v[170:173], v142 offset:18432
	ds_read_b128 v[174:177], v142 offset:19456
	ds_read_b128 v[178:181], v142 offset:20480
	ds_read_b128 v[182:185], v142 offset:21504
	ds_read_b128 v[186:189], v142 offset:22528
	ds_read_b128 v[190:193], v142 offset:23552
	global_load_lds_dwordx4 v[214:215], off
	v_lshl_add_u64 v[216:217], s[14:15], 0, v[134:135]
	s_mov_b32 m0, s22
	s_nop 0
	global_load_lds_dwordx4 v[216:217], off
	s_barrier
	s_waitcnt lgkmcnt(0)
	s_waitcnt lgkmcnt(0)
	v_mfma_f32_16x16x32_f16 v[90:93], v[146:149], v[162:165], v[90:93]
	v_mfma_f32_16x16x32_f16 v[94:97], v[154:157], v[162:165], v[94:97]
	v_mfma_f32_16x16x32_f16 v[82:85], v[146:149], v[170:173], v[82:85]
	v_mfma_f32_16x16x32_f16 v[86:89], v[154:157], v[170:173], v[86:89]
	v_mfma_f32_16x16x32_f16 v[74:77], v[146:149], v[178:181], v[74:77]
	v_mfma_f32_16x16x32_f16 v[78:81], v[154:157], v[178:181], v[78:81]
	v_mfma_f32_16x16x32_f16 v[66:69], v[146:149], v[186:189], v[66:69]
	v_mfma_f32_16x16x32_f16 v[70:73], v[154:157], v[186:189], v[70:73]
	v_mfma_f32_16x16x32_f16 v[90:93], v[150:153], v[166:169], v[90:93]
	v_mfma_f32_16x16x32_f16 v[94:97], v[158:161], v[166:169], v[94:97]
	v_mfma_f32_16x16x32_f16 v[82:85], v[150:153], v[174:177], v[82:85]
	v_mfma_f32_16x16x32_f16 v[86:89], v[158:161], v[174:177], v[86:89]
	v_mfma_f32_16x16x32_f16 v[74:77], v[150:153], v[182:185], v[74:77]
	v_mfma_f32_16x16x32_f16 v[78:81], v[158:161], v[182:185], v[78:81]
	v_mfma_f32_16x16x32_f16 v[66:69], v[150:153], v[190:193], v[66:69]
	v_mfma_f32_16x16x32_f16 v[70:73], v[158:161], v[190:193], v[70:73]
	s_barrier
; #define G_STAGE(bufoff, gbase, v0, v1) do { \
;     __builtin_amdgcn_global_load_lds((const unsigned*)((const char*)(gbase) + (v0)), (LAS unsigned*)(lds + (bufoff) + ldsw), 16, 0, 0); \
;     __builtin_amdgcn_global_load_lds((const unsigned*)((const char*)(gbase) + (v1)), (LAS unsigned*)(lds + (bufoff) + ldsw + 8192), 16, 0, 0); } while (0)
; #define G_LDA(dst, b, h) do { _Pragma("unroll") for (int m = 0; m < 4; ++m) _Pragma("unroll") for (int k = 0; k < 2; ++k) dst[m][k] = *(const LAS h8*)(lds + G_SA(b, h) + aoff + m * 2048 + k * 1024); } while (0)
; #define G_LDB(dst, b, h) do { _Pragma("unroll") for (int n = 0; n < 2; ++n) _Pragma("unroll") for (int k = 0; k < 2; ++k) dst[n][k] = *(const LAS h8*)(lds + G_SB(b, h) + boff + n * 2048 + k * 1024); } while (0)
; #define G_MMA(ai, bj, At, Bt) do { __builtin_amdgcn_s_setprio(1); _Pragma("unroll") for (int m = 0; m < 4; ++m) _Pragma("unroll") for (int n = 0; n < 2; ++n) _Pragma("unroll") for (int k = 0; k < 2; ++k) \
;     acc[ai][bj][m][n] = __builtin_amdgcn_mfma_f32_16x16x32_f16(Bt[n][k], At[m][k], acc[ai][bj][m][n], 0, 0, 0); __builtin_amdgcn_s_setprio(0); } while (0)
; #define G_WAIT_V(n) asm volatile("s_waitcnt vmcnt(" #n ")" ::: "memory")
; #define G_WAIT_L(n) asm volatile("s_waitcnt lgkmcnt(" #n ")" ::: "memory")
; #define G_BAR __builtin_amdgcn_s_barrier()
; #define G_SCHED __builtin_amdgcn_sched_barrier(0)
; template <bool PERM, class Sched, class Epi>
; DI void gemm256(LAS unsigned char* lds, const Sched& S, const Epi& E, int wv_) {
;     ...
;       G_STAGE(G_SB(0, 1), b2 + chB, cvB0, cvB1);
;       G_WAIT_V(6); G_BAR; G_MMA(1, 1, At, B1); G_BAR;
;       G_LDB(B0, 1, 0); G_SCHED; G_LDA(At, 1, 0); G_STAGE(G_SA(0, 1), a2 + chA, cvA0, cvA1);
;       G_WAIT_L(8); G_BAR; G_WAIT_L(0); G_MMA(0, 0, At, B0); G_BAR; G_SCHED;
;       G_LDB(B1, 1, 1); G_STAGE(G_SB(1, 0), b3, cvB0, cvB1);
	s_add_u32 vcc_lo, s12, 0x40000
	s_addc_u32 vcc_hi, s13, 0
	s_mov_b32 m0, s23
	v_lshl_add_u64 v[146:147], vcc, 0, v[132:133]
	global_load_lds_dwordx4 v[146:147], off
	v_lshl_add_u64 v[146:147], vcc, 0, v[136:137]
	s_mov_b32 m0, s24
	s_nop 0
	global_load_lds_dwordx4 v[146:147], off
	s_waitcnt vmcnt(6)
	s_barrier
	v_mfma_f32_16x16x32_f16 v[26:29], v[194:197], v[162:165], v[26:29]
	v_mfma_f32_16x16x32_f16 v[30:33], v[202:205], v[162:165], v[30:33]
	v_mfma_f32_16x16x32_f16 v[18:21], v[194:197], v[170:173], v[18:21]
	v_mfma_f32_16x16x32_f16 v[22:25], v[202:205], v[170:173], v[22:25]
	v_mfma_f32_16x16x32_f16 v[10:13], v[194:197], v[178:181], v[10:13]
	v_mfma_f32_16x16x32_f16 v[14:17], v[202:205], v[178:181], v[14:17]
	v_mfma_f32_16x16x32_f16 v[6:9], v[194:197], v[186:189], v[6:9]
	v_mfma_f32_16x16x32_f16 v[2:5], v[202:205], v[186:189], v[2:5]
	v_mfma_f32_16x16x32_f16 v[26:29], v[198:201], v[166:169], v[26:29]
	v_mfma_f32_16x16x32_f16 v[30:33], v[206:209], v[166:169], v[30:33]
	v_mfma_f32_16x16x32_f16 v[18:21], v[198:201], v[174:177], v[18:21]
	v_mfma_f32_16x16x32_f16 v[22:25], v[206:209], v[174:177], v[22:25]
	v_mfma_f32_16x16x32_f16 v[10:13], v[198:201], v[182:185], v[10:13]
	v_mfma_f32_16x16x32_f16 v[14:17], v[206:209], v[182:185], v[14:17]
	v_mfma_f32_16x16x32_f16 v[6:9], v[198:201], v[190:193], v[6:9]
	v_mfma_f32_16x16x32_f16 v[2:5], v[206:209], v[190:193], v[2:5]
	v_or_b32_e32 v146, 0x18000, v143
	v_add_u32_e32 v150, 0x18400, v143
	v_add_u32_e32 v154, 0x18800, v143
	v_add_u32_e32 v158, 0x18c00, v143
	s_barrier
	ds_read_b128 v[146:149], v146
	ds_read_b128 v[150:153], v150
	ds_read_b128 v[154:157], v154
	ds_read_b128 v[158:161], v158
	s_add_u32 s14, s14, 0x40000
	s_addc_u32 s15, s15, 0
	s_mov_b32 m0, s25
	v_lshl_add_u64 v[194:195], s[14:15], 0, v[130:131]
	ds_read_b128 v[162:165], v142 offset:32768
	ds_read_b128 v[166:169], v142 offset:33792
	ds_read_b128 v[170:173], v142 offset:34816
	ds_read_b128 v[174:177], v142 offset:35840
	ds_read_b128 v[178:181], v142 offset:36864
	ds_read_b128 v[182:185], v142 offset:37888
	ds_read_b128 v[186:189], v142 offset:38912
	ds_read_b128 v[190:193], v142 offset:39936
	global_load_lds_dwordx4 v[194:195], off
	v_lshl_add_u64 v[194:195], s[14:15], 0, v[134:135]
	s_mov_b32 m0, s26
	s_nop 0
	global_load_lds_dwordx4 v[194:195], off
	s_waitcnt lgkmcnt(8)
	s_barrier
	s_waitcnt lgkmcnt(0)
	s_waitcnt lgkmcnt(0)
	v_mfma_f32_16x16x32_f16 v[122:125], v[146:149], v[162:165], v[122:125]
	v_mfma_f32_16x16x32_f16 v[126:129], v[154:157], v[162:165], v[126:129]
	v_mfma_f32_16x16x32_f16 v[114:117], v[146:149], v[170:173], v[114:117]
	v_mfma_f32_16x16x32_f16 v[118:121], v[154:157], v[170:173], v[118:121]
	v_mfma_f32_16x16x32_f16 v[106:109], v[146:149], v[178:181], v[106:109]
	v_mfma_f32_16x16x32_f16 v[110:113], v[154:157], v[178:181], v[110:113]
	v_mfma_f32_16x16x32_f16 v[98:101], v[146:149], v[186:189], v[98:101]
	v_mfma_f32_16x16x32_f16 v[102:105], v[154:157], v[186:189], v[102:105]
	v_mfma_f32_16x16x32_f16 v[122:125], v[150:153], v[166:169], v[122:125]
	v_mfma_f32_16x16x32_f16 v[126:129], v[158:161], v[166:169], v[126:129]
	v_mfma_f32_16x16x32_f16 v[114:117], v[150:153], v[174:177], v[114:117]
	v_mfma_f32_16x16x32_f16 v[118:121], v[158:161], v[174:177], v[118:121]
	v_mfma_f32_16x16x32_f16 v[106:109], v[150:153], v[182:185], v[106:109]
	v_mfma_f32_16x16x32_f16 v[110:113], v[158:161], v[182:185], v[110:113]
	v_mfma_f32_16x16x32_f16 v[98:101], v[150:153], v[190:193], v[98:101]
	v_mfma_f32_16x16x32_f16 v[102:105], v[158:161], v[190:193], v[102:105]
	s_barrier
	s_mov_b32 m0, s29
	v_or_b32_e32 v194, 0x1c000, v143
	v_add_u32_e32 v198, 0x1c400, v143
	v_add_u32_e32 v202, 0x1c800, v143
	v_add_u32_e32 v206, 0x1cc00, v143
	v_lshl_add_u64 v[210:211], v[210:211], 0, s[86:87]
	ds_read_b128 v[194:197], v194
	ds_read_b128 v[198:201], v198
	ds_read_b128 v[202:205], v202
	ds_read_b128 v[206:209], v206
	global_load_lds_dwordx4 v[210:211], off
	v_lshl_add_u64 v[210:211], v[212:213], 0, s[86:87]
	s_mov_b32 m0, s30
	s_nop 0
	global_load_lds_dwordx4 v[210:211], off
	s_barrier
; #define G_STAGE(bufoff, gbase, v0, v1) do { \
;     __builtin_amdgcn_global_load_lds((const unsigned*)((const char*)(gbase) + (v0)), (LAS unsigned*)(lds + (bufoff) + ldsw), 16, 0, 0); \
;     __builtin_amdgcn_global_load_lds((const unsigned*)((const char*)(gbase) + (v1)), (LAS unsigned*)(lds + (bufoff) + ldsw + 8192), 16, 0, 0); } while (0)
; #define G_LDA(dst, b, h) do { _Pragma("unroll") for (int m = 0; m < 4; ++m) _Pragma("unroll") for (int k = 0; k < 2; ++k) dst[m][k] = *(const LAS h8*)(lds + G_SA(b, h) + aoff + m * 2048 + k * 1024); } while (0)
; #define G_LDB(dst, b, h) do { _Pragma("unroll") for (int n = 0; n < 2; ++n) _Pragma("unroll") for (int k = 0; k < 2; ++k) dst[n][k] = *(const LAS h8*)(lds + G_SB(b, h) + boff + n * 2048 + k * 1024); } while (0)
; #define G_MMA(ai, bj, At, Bt) do { __builtin_amdgcn_s_setprio(1); _Pragma("unroll") for (int m = 0; m < 4; ++m) _Pragma("unroll") for (int n = 0; n < 2; ++n) _Pragma("unroll") for (int k = 0; k < 2; ++k) \
;     acc[ai][bj][m][n] = __builtin_amdgcn_mfma_f32_16x16x32_f16(Bt[n][k], At[m][k], acc[ai][bj][m][n], 0, 0, 0); __builtin_amdgcn_s_setprio(0); } while (0)
; #define G_WAIT_V(n) asm volatile("s_waitcnt vmcnt(" #n ")" ::: "memory")
; #define G_WAIT_L(n) asm volatile("s_waitcnt lgkmcnt(" #n ")" ::: "memory")
; #define G_BAR __builtin_amdgcn_s_barrier()
; #define G_SCHED __builtin_amdgcn_sched_barrier(0)
; template <bool PERM, class Sched, class Epi>
; DI void gemm256(LAS unsigned char* lds, const Sched& S, const Epi& E, int wv_) {
;     ...
;       G_LDB(B1, 1, 1); G_STAGE(G_SB(1, 0), b3, cvB0, cvB1);
;       G_BAR; G_WAIT_L(0); G_MMA(0, 1, At, B1); G_BAR;
;       G_LDA(At, 1, 1); G_STAGE(G_SA(1, 0), a3, cvA0, cvA1);
;       G_BAR; G_WAIT_L(0); G_MMA(1, 0, At, B0); G_BAR; G_SCHED;
;       G_STAGE(G_SB(1, 1), b3 + chB, cvB0, cvB1);
;       G_WAIT_V(6); G_BAR; G_MMA(1, 1, At, B1); G_BAR;
;     }
	s_waitcnt lgkmcnt(0)
	s_waitcnt lgkmcnt(0)
	v_mfma_f32_16x16x32_f16 v[58:61], v[194:197], v[162:165], v[58:61]
	v_mfma_f32_16x16x32_f16 v[62:65], v[202:205], v[162:165], v[62:65]
	v_mfma_f32_16x16x32_f16 v[50:53], v[194:197], v[170:173], v[50:53]
	v_mfma_f32_16x16x32_f16 v[54:57], v[202:205], v[170:173], v[54:57]
	v_mfma_f32_16x16x32_f16 v[42:45], v[194:197], v[178:181], v[42:45]
	v_mfma_f32_16x16x32_f16 v[46:49], v[202:205], v[178:181], v[46:49]
	v_mfma_f32_16x16x32_f16 v[34:37], v[194:197], v[186:189], v[34:37]
	v_mfma_f32_16x16x32_f16 v[38:41], v[202:205], v[186:189], v[38:41]
	v_mfma_f32_16x16x32_f16 v[58:61], v[198:201], v[166:169], v[58:61]
	v_mfma_f32_16x16x32_f16 v[62:65], v[206:209], v[166:169], v[62:65]
	v_mfma_f32_16x16x32_f16 v[50:53], v[198:201], v[174:177], v[50:53]
	v_mfma_f32_16x16x32_f16 v[54:57], v[206:209], v[174:177], v[54:57]
	v_mfma_f32_16x16x32_f16 v[42:45], v[198:201], v[182:185], v[42:45]
	v_mfma_f32_16x16x32_f16 v[46:49], v[206:209], v[182:185], v[46:49]
	v_mfma_f32_16x16x32_f16 v[34:37], v[198:201], v[190:193], v[34:37]
	v_mfma_f32_16x16x32_f16 v[38:41], v[206:209], v[190:193], v[38:41]
	s_mov_b32 m0, s31
	v_lshl_add_u64 v[210:211], v[214:215], 0, s[86:87]
	s_barrier
	ds_read_b128 v[162:165], v142 offset:49152
	ds_read_b128 v[166:169], v142 offset:50176
	ds_read_b128 v[170:173], v142 offset:51200
	ds_read_b128 v[174:177], v142 offset:52224
	ds_read_b128 v[178:181], v142 offset:53248
	ds_read_b128 v[182:185], v142 offset:54272
	ds_read_b128 v[186:189], v142 offset:55296
	ds_read_b128 v[190:193], v142 offset:56320
	global_load_lds_dwordx4 v[210:211], off
	v_lshl_add_u64 v[210:211], v[216:217], 0, s[86:87]
	s_mov_b32 m0, s34
	s_nop 0
	global_load_lds_dwordx4 v[210:211], off
	s_barrier
	s_waitcnt lgkmcnt(0)
	s_waitcnt lgkmcnt(0)
	v_mfma_f32_16x16x32_f16 v[90:93], v[146:149], v[162:165], v[90:93]
	v_mfma_f32_16x16x32_f16 v[94:97], v[154:157], v[162:165], v[94:97]
	v_mfma_f32_16x16x32_f16 v[82:85], v[146:149], v[170:173], v[82:85]
	v_mfma_f32_16x16x32_f16 v[86:89], v[154:157], v[170:173], v[86:89]
	v_mfma_f32_16x16x32_f16 v[74:77], v[146:149], v[178:181], v[74:77]
	v_mfma_f32_16x16x32_f16 v[78:81], v[154:157], v[178:181], v[78:81]
	v_mfma_f32_16x16x32_f16 v[66:69], v[146:149], v[186:189], v[66:69]
	v_mfma_f32_16x16x32_f16 v[70:73], v[154:157], v[186:189], v[70:73]
	v_mfma_f32_16x16x32_f16 v[90:93], v[150:153], v[166:169], v[90:93]
	v_mfma_f32_16x16x32_f16 v[94:97], v[158:161], v[166:169], v[94:97]
	v_mfma_f32_16x16x32_f16 v[82:85], v[150:153], v[174:177], v[82:85]
	v_mfma_f32_16x16x32_f16 v[86:89], v[158:161], v[174:177], v[86:89]
	v_mfma_f32_16x16x32_f16 v[74:77], v[150:153], v[182:185], v[74:77]
	v_mfma_f32_16x16x32_f16 v[78:81], v[158:161], v[182:185], v[78:81]
	v_mfma_f32_16x16x32_f16 v[66:69], v[150:153], v[190:193], v[66:69]
	v_mfma_f32_16x16x32_f16 v[70:73], v[158:161], v[190:193], v[70:73]
	s_barrier
	s_add_u32 s12, s12, 0x40080
	s_addc_u32 s13, s13, 0
	s_mov_b32 m0, s35
	v_lshl_add_u64 v[146:147], s[12:13], 0, v[132:133]
	global_load_lds_dwordx4 v[146:147], off
	v_lshl_add_u64 v[146:147], s[12:13], 0, v[136:137]
	s_mov_b32 m0, s36
	s_nop 0
	global_load_lds_dwordx4 v[146:147], off
	s_waitcnt vmcnt(6)
	s_barrier
	v_mfma_f32_16x16x32_f16 v[26:29], v[194:197], v[162:165], v[26:29]
	v_mfma_f32_16x16x32_f16 v[30:33], v[202:205], v[162:165], v[30:33]
	v_mfma_f32_16x16x32_f16 v[18:21], v[194:197], v[170:173], v[18:21]
	v_mfma_f32_16x16x32_f16 v[22:25], v[202:205], v[170:173], v[22:25]
	v_mfma_f32_16x16x32_f16 v[10:13], v[194:197], v[178:181], v[10:13]
	v_mfma_f32_16x16x32_f16 v[14:17], v[202:205], v[178:181], v[14:17]
	v_mfma_f32_16x16x32_f16 v[6:9], v[194:197], v[186:189], v[6:9]
	v_mfma_f32_16x16x32_f16 v[2:5], v[202:205], v[186:189], v[2:5]
	v_mfma_f32_16x16x32_f16 v[26:29], v[198:201], v[166:169], v[26:29]
	v_mfma_f32_16x16x32_f16 v[30:33], v[206:209], v[166:169], v[30:33]
	v_mfma_f32_16x16x32_f16 v[18:21], v[198:201], v[174:177], v[18:21]
	v_mfma_f32_16x16x32_f16 v[22:25], v[206:209], v[174:177], v[22:25]
	v_mfma_f32_16x16x32_f16 v[10:13], v[198:201], v[182:185], v[10:13]
	v_mfma_f32_16x16x32_f16 v[14:17], v[206:209], v[182:185], v[14:17]
	v_mfma_f32_16x16x32_f16 v[6:9], v[198:201], v[190:193], v[6:9]
	v_mfma_f32_16x16x32_f16 v[2:5], v[206:209], v[190:193], v[2:5]
	s_add_u32 s10, s10, 0x100
	s_addc_u32 s11, s11, 0
	s_add_u32 s46, s46, 0x100
	s_addc_u32 s74, s74, 0
	s_cmp_ge_i32 s91, s7
	s_mov_b32 s12, s91
	s_barrier
	s_cbranch_scc0 .LBB0_1503
	v_readlane_b32 s91, v254, 47
	s_movk_i32 s85, 0x800
	s_xor_b64 s[8:9], s[8:9], -1
	s_cmp_lg_u32 s84, 0
	s_cbranch_scc0 .LBB0_1509

; #define G_STAGE(bufoff, gbase, v0, v1) do { \
;     __builtin_amdgcn_global_load_lds((const unsigned*)((const char*)(gbase) + (v0)), (LAS unsigned*)(lds + (bufoff) + ldsw), 16, 0, 0); \
;     __builtin_amdgcn_global_load_lds((const unsigned*)((const char*)(gbase) + (v1)), (LAS unsigned*)(lds + (bufoff) + ldsw + 8192), 16, 0, 0); } while (0)
; #define G_LDA(dst, b, h) do { _Pragma("unroll") for (int m = 0; m < 4; ++m) _Pragma("unroll") for (int k = 0; k < 2; ++k) dst[m][k] = *(const LAS h8*)(lds + G_SA(b, h) + aoff + m * 2048 + k * 1024); } while (0)
; #define G_LDB(dst, b, h) do { _Pragma("unroll") for (int n = 0; n < 2; ++n) _Pragma("unroll") for (int k = 0; k < 2; ++k) dst[n][k] = *(const LAS h8*)(lds + G_SB(b, h) + boff + n * 2048 + k * 1024); } while (0)
; #define G_MMA(ai, bj, At, Bt) do { __builtin_amdgcn_s_setprio(1); _Pragma("unroll") for (int m = 0; m < 4; ++m) _Pragma("unroll") for (int n = 0; n < 2; ++n) _Pragma("unroll") for (int k = 0; k < 2; ++k) \
;     acc[ai][bj][m][n] = __builtin_amdgcn_mfma_f32_16x16x32_f16(Bt[n][k], At[m][k], acc[ai][bj][m][n], 0, 0, 0); __builtin_amdgcn_s_setprio(0); } while (0)
; #define G_WAIT_L(n) asm volatile("s_waitcnt lgkmcnt(" #n ")" ::: "memory")
; #define G_BAR __builtin_amdgcn_s_barrier()
; #define G_SCHED __builtin_amdgcn_sched_barrier(0)
; template <bool PERM, class Sched, class Epi>
; DI void gemm256(LAS unsigned char* lds, const Sched& S, const Epi& E, int wv_) {
;     ...
;     for (int t = 0; t < nt; t += 2) {
;       const bool last = (t == nt - 2);
;       const char* a1 = cA + (size_t)(t + 1) * kstep;
;       const char* a2 = last ? nA : cA + (size_t)(t + 2) * kstep;
;       const char* b2 = last ? nB : cB + (size_t)(t + 2) * kstep;
;       const char* a3 = a2 + kstep;
;       const char* b3 = b2 + kstep;
;       G_LDB(B0, 0, 0); G_SCHED; G_LDA(At, 0, 0); G_STAGE(G_SA(1, 1), a1 + chA, cvA0, cvA1);
;       G_WAIT_L(8); G_BAR; G_WAIT_L(0); G_MMA(0, 0, At, B0); G_BAR; G_SCHED;
;       G_LDB(B1, 0, 1); G_STAGE(G_SB(0, 0), b2, cvB0, cvB1);
;       G_BAR; G_WAIT_L(0); G_MMA(0, 1, At, B1); G_BAR;
;       G_LDA(At, 0, 1); G_STAGE(G_SA(0, 0), a2, cvA0, cvA1);
;       G_BAR; G_WAIT_L(0); G_MMA(1, 0, At, B0); G_BAR; G_SCHED;
.LBB0_1718:
	v_or_b32_e32 v144, 0x10000, v142
	v_add_u32_e32 v148, 0x10400, v142
	v_add_u32_e32 v152, 0x10800, v142
	v_add_u32_e32 v156, 0x10c00, v142
	s_add_i32 s74, s12, 2
	ds_read_b128 v[144:147], v144
	ds_read_b128 v[148:151], v148
	ds_read_b128 v[152:155], v152
	ds_read_b128 v[156:159], v156
	s_add_u32 s13, s10, 0xfffea080
	s_addc_u32 s14, s11, -1
	s_cmp_eq_u32 vcc_lo, s12
	s_cselect_b32 s12, s93, s75
	s_cselect_b32 s15, s84, s14
	s_cselect_b32 s14, s85, s13
	s_cselect_b32 s13, s90, s46
	v_lshl_add_u64 v[192:193], s[10:11], 0, v[138:139]
	s_add_i32 m0, s19, 0xc000
	ds_read_b128 v[160:163], v1
	ds_read_b128 v[164:167], v1 offset:1024
	ds_read_b128 v[168:171], v1 offset:2048
	ds_read_b128 v[172:175], v1 offset:3072
	ds_read_b128 v[176:179], v1 offset:4096
	ds_read_b128 v[180:183], v1 offset:5120
	ds_read_b128 v[184:187], v1 offset:6144
	ds_read_b128 v[188:191], v1 offset:7168
	global_load_lds_dwordx4 v[192:193], off
	v_lshl_add_u64 v[192:193], s[10:11], 0, v[140:141]
	s_add_i32 m0, s19, 0xe000
	s_nop 0
	global_load_lds_dwordx4 v[192:193], off
	s_waitcnt lgkmcnt(8)
	s_barrier
	s_waitcnt lgkmcnt(0)
	s_waitcnt lgkmcnt(0)
	v_mfma_f32_16x16x32_f16 v[122:125], v[144:147], v[160:163], v[122:125]
	v_mfma_f32_16x16x32_f16 v[126:129], v[152:155], v[160:163], v[126:129]
	v_mfma_f32_16x16x32_f16 v[114:117], v[144:147], v[168:171], v[114:117]
	v_mfma_f32_16x16x32_f16 v[118:121], v[152:155], v[168:171], v[118:121]
	v_mfma_f32_16x16x32_f16 v[106:109], v[144:147], v[176:179], v[106:109]
	v_mfma_f32_16x16x32_f16 v[110:113], v[152:155], v[176:179], v[110:113]
	v_mfma_f32_16x16x32_f16 v[98:101], v[144:147], v[184:187], v[98:101]
	v_mfma_f32_16x16x32_f16 v[102:105], v[152:155], v[184:187], v[102:105]
	v_mfma_f32_16x16x32_f16 v[122:125], v[148:151], v[164:167], v[122:125]
	v_mfma_f32_16x16x32_f16 v[126:129], v[156:159], v[164:167], v[126:129]
	v_mfma_f32_16x16x32_f16 v[114:117], v[148:151], v[172:175], v[114:117]
	v_mfma_f32_16x16x32_f16 v[118:121], v[156:159], v[172:175], v[118:121]
	v_mfma_f32_16x16x32_f16 v[106:109], v[148:151], v[180:183], v[106:109]
	v_mfma_f32_16x16x32_f16 v[110:113], v[156:159], v[180:183], v[110:113]
	v_mfma_f32_16x16x32_f16 v[98:101], v[148:151], v[188:191], v[98:101]
	v_mfma_f32_16x16x32_f16 v[102:105], v[156:159], v[188:191], v[102:105]
	s_barrier
	s_mov_b32 m0, s20
	v_or_b32_e32 v192, 0x14000, v142
	v_add_u32_e32 v196, 0x14400, v142
	v_add_u32_e32 v200, 0x14800, v142
	v_add_u32_e32 v204, 0x14c00, v142
	v_lshl_add_u64 v[208:209], s[12:13], 0, v[132:133]
	ds_read_b128 v[192:195], v192
	ds_read_b128 v[196:199], v196
	ds_read_b128 v[200:203], v200
	ds_read_b128 v[204:207], v204
	global_load_lds_dwordx4 v[208:209], off
	v_lshl_add_u64 v[210:211], s[12:13], 0, v[136:137]
	s_mov_b32 m0, s21
	s_nop 0
	global_load_lds_dwordx4 v[210:211], off
	s_barrier
	s_waitcnt lgkmcnt(0)
	s_waitcnt lgkmcnt(0)
	v_mfma_f32_16x16x32_f16 v[58:61], v[192:195], v[160:163], v[58:61]
	v_mfma_f32_16x16x32_f16 v[62:65], v[200:203], v[160:163], v[62:65]
	v_mfma_f32_16x16x32_f16 v[50:53], v[192:195], v[168:171], v[50:53]
	v_mfma_f32_16x16x32_f16 v[54:57], v[200:203], v[168:171], v[54:57]
	v_mfma_f32_16x16x32_f16 v[42:45], v[192:195], v[176:179], v[42:45]
	v_mfma_f32_16x16x32_f16 v[46:49], v[200:203], v[176:179], v[46:49]
	v_mfma_f32_16x16x32_f16 v[34:37], v[192:195], v[184:187], v[34:37]
	v_mfma_f32_16x16x32_f16 v[38:41], v[200:203], v[184:187], v[38:41]
	v_mfma_f32_16x16x32_f16 v[58:61], v[196:199], v[164:167], v[58:61]
	v_mfma_f32_16x16x32_f16 v[62:65], v[204:207], v[164:167], v[62:65]
	v_mfma_f32_16x16x32_f16 v[50:53], v[196:199], v[172:175], v[50:53]
	v_mfma_f32_16x16x32_f16 v[54:57], v[204:207], v[172:175], v[54:57]
	v_mfma_f32_16x16x32_f16 v[42:45], v[196:199], v[180:183], v[42:45]
	v_mfma_f32_16x16x32_f16 v[46:49], v[204:207], v[180:183], v[46:49]
	v_mfma_f32_16x16x32_f16 v[34:37], v[196:199], v[188:191], v[34:37]
	v_mfma_f32_16x16x32_f16 v[38:41], v[204:207], v[188:191], v[38:41]
	s_mov_b32 m0, s19
	v_lshl_add_u64 v[212:213], s[14:15], 0, v[130:131]
	s_barrier
	ds_read_b128 v[160:163], v1 offset:16384
	ds_read_b128 v[164:167], v1 offset:17408
	ds_read_b128 v[168:171], v1 offset:18432
	ds_read_b128 v[172:175], v1 offset:19456
	ds_read_b128 v[176:179], v1 offset:20480
	ds_read_b128 v[180:183], v1 offset:21504
	ds_read_b128 v[184:187], v1 offset:22528
	ds_read_b128 v[188:191], v1 offset:23552
	global_load_lds_dwordx4 v[212:213], off
	v_lshl_add_u64 v[214:215], s[14:15], 0, v[134:135]
	s_mov_b32 m0, s22
	s_nop 0
	global_load_lds_dwordx4 v[214:215], off
	s_barrier
	s_waitcnt lgkmcnt(0)
	s_waitcnt lgkmcnt(0)
	v_mfma_f32_16x16x32_f16 v[90:93], v[144:147], v[160:163], v[90:93]
	v_mfma_f32_16x16x32_f16 v[94:97], v[152:155], v[160:163], v[94:97]
	v_mfma_f32_16x16x32_f16 v[82:85], v[144:147], v[168:171], v[82:85]
	v_mfma_f32_16x16x32_f16 v[86:89], v[152:155], v[168:171], v[86:89]
	v_mfma_f32_16x16x32_f16 v[74:77], v[144:147], v[176:179], v[74:77]
	v_mfma_f32_16x16x32_f16 v[78:81], v[152:155], v[176:179], v[78:81]
	v_mfma_f32_16x16x32_f16 v[66:69], v[144:147], v[184:187], v[66:69]
	v_mfma_f32_16x16x32_f16 v[70:73], v[152:155], v[184:187], v[70:73]
	v_mfma_f32_16x16x32_f16 v[90:93], v[148:151], v[164:167], v[90:93]
	v_mfma_f32_16x16x32_f16 v[94:97], v[156:159], v[164:167], v[94:97]
	v_mfma_f32_16x16x32_f16 v[82:85], v[148:151], v[172:175], v[82:85]
	v_mfma_f32_16x16x32_f16 v[86:89], v[156:159], v[172:175], v[86:89]
	v_mfma_f32_16x16x32_f16 v[74:77], v[148:151], v[180:183], v[74:77]
	v_mfma_f32_16x16x32_f16 v[78:81], v[156:159], v[180:183], v[78:81]
	v_mfma_f32_16x16x32_f16 v[66:69], v[148:151], v[188:191], v[66:69]
	v_mfma_f32_16x16x32_f16 v[70:73], v[156:159], v[188:191], v[70:73]
	s_barrier
; #define G_STAGE(bufoff, gbase, v0, v1) do { \
;     __builtin_amdgcn_global_load_lds((const unsigned*)((const char*)(gbase) + (v0)), (LAS unsigned*)(lds + (bufoff) + ldsw), 16, 0, 0); \
;     __builtin_amdgcn_global_load_lds((const unsigned*)((const char*)(gbase) + (v1)), (LAS unsigned*)(lds + (bufoff) + ldsw + 8192), 16, 0, 0); } while (0)
; #define G_LDA(dst, b, h) do { _Pragma("unroll") for (int m = 0; m < 4; ++m) _Pragma("unroll") for (int k = 0; k < 2; ++k) dst[m][k] = *(const LAS h8*)(lds + G_SA(b, h) + aoff + m * 2048 + k * 1024); } while (0)
; #define G_LDB(dst, b, h) do { _Pragma("unroll") for (int n = 0; n < 2; ++n) _Pragma("unroll") for (int k = 0; k < 2; ++k) dst[n][k] = *(const LAS h8*)(lds + G_SB(b, h) + boff + n * 2048 + k * 1024); } while (0)
; #define G_MMA(ai, bj, At, Bt) do { __builtin_amdgcn_s_setprio(1); _Pragma("unroll") for (int m = 0; m < 4; ++m) _Pragma("unroll") for (int n = 0; n < 2; ++n) _Pragma("unroll") for (int k = 0; k < 2; ++k) \
;     acc[ai][bj][m][n] = __builtin_amdgcn_mfma_f32_16x16x32_f16(Bt[n][k], At[m][k], acc[ai][bj][m][n], 0, 0, 0); __builtin_amdgcn_s_setprio(0); } while (0)
; #define G_WAIT_V(n) asm volatile("s_waitcnt vmcnt(" #n ")" ::: "memory")
; #define G_WAIT_L(n) asm volatile("s_waitcnt lgkmcnt(" #n ")" ::: "memory")
; #define G_BAR __builtin_amdgcn_s_barrier()
; #define G_SCHED __builtin_amdgcn_sched_barrier(0)
; template <bool PERM, class Sched, class Epi>
; DI void gemm256(LAS unsigned char* lds, const Sched& S, const Epi& E, int wv_) {
;     ...
;       G_STAGE(G_SB(0, 1), b2 + chB, cvB0, cvB1);
;       G_WAIT_V(6); G_BAR; G_MMA(1, 1, At, B1); G_BAR;
;       G_LDB(B0, 1, 0); G_SCHED; G_LDA(At, 1, 0); G_STAGE(G_SA(0, 1), a2 + chA, cvA0, cvA1);
;       G_WAIT_L(8); G_BAR; G_WAIT_L(0); G_MMA(0, 0, At, B0); G_BAR; G_SCHED;
;       G_LDB(B1, 1, 1); G_STAGE(G_SB(1, 0), b3, cvB0, cvB1);
	s_add_u32 s68, s12, 0x10000
	s_addc_u32 s69, s13, 0
	s_mov_b32 m0, s23
	v_lshl_add_u64 v[144:145], s[68:69], 0, v[132:133]
	global_load_lds_dwordx4 v[144:145], off
	v_lshl_add_u64 v[144:145], s[68:69], 0, v[136:137]
	s_mov_b32 m0, s24
	s_nop 0
	global_load_lds_dwordx4 v[144:145], off
	s_waitcnt vmcnt(6)
	s_barrier
	v_mfma_f32_16x16x32_f16 v[26:29], v[192:195], v[160:163], v[26:29]
	v_mfma_f32_16x16x32_f16 v[30:33], v[200:203], v[160:163], v[30:33]
	v_mfma_f32_16x16x32_f16 v[18:21], v[192:195], v[168:171], v[18:21]
	v_mfma_f32_16x16x32_f16 v[22:25], v[200:203], v[168:171], v[22:25]
	v_mfma_f32_16x16x32_f16 v[10:13], v[192:195], v[176:179], v[10:13]
	v_mfma_f32_16x16x32_f16 v[14:17], v[200:203], v[176:179], v[14:17]
	v_mfma_f32_16x16x32_f16 v[6:9], v[192:195], v[184:187], v[6:9]
	v_mfma_f32_16x16x32_f16 v[2:5], v[200:203], v[184:187], v[2:5]
	v_mfma_f32_16x16x32_f16 v[26:29], v[196:199], v[164:167], v[26:29]
	v_mfma_f32_16x16x32_f16 v[30:33], v[204:207], v[164:167], v[30:33]
	v_mfma_f32_16x16x32_f16 v[18:21], v[196:199], v[172:175], v[18:21]
	v_mfma_f32_16x16x32_f16 v[22:25], v[204:207], v[172:175], v[22:25]
	v_mfma_f32_16x16x32_f16 v[10:13], v[196:199], v[180:183], v[10:13]
	v_mfma_f32_16x16x32_f16 v[14:17], v[204:207], v[180:183], v[14:17]
	v_mfma_f32_16x16x32_f16 v[6:9], v[196:199], v[188:191], v[6:9]
	v_mfma_f32_16x16x32_f16 v[2:5], v[204:207], v[188:191], v[2:5]
	v_or_b32_e32 v144, 0x18000, v142
	v_add_u32_e32 v148, 0x18400, v142
	v_add_u32_e32 v152, 0x18800, v142
	v_add_u32_e32 v156, 0x18c00, v142
	s_barrier
	ds_read_b128 v[144:147], v144
	ds_read_b128 v[148:151], v148
	ds_read_b128 v[152:155], v152
	ds_read_b128 v[156:159], v156
	s_add_u32 s14, s14, 0x16000
	s_addc_u32 s15, s15, 0
	s_mov_b32 m0, s25
	v_lshl_add_u64 v[192:193], s[14:15], 0, v[130:131]
	ds_read_b128 v[160:163], v1 offset:32768
	ds_read_b128 v[164:167], v1 offset:33792
	ds_read_b128 v[168:171], v1 offset:34816
	ds_read_b128 v[172:175], v1 offset:35840
	ds_read_b128 v[176:179], v1 offset:36864
	ds_read_b128 v[180:183], v1 offset:37888
	ds_read_b128 v[184:187], v1 offset:38912
	ds_read_b128 v[188:191], v1 offset:39936
	global_load_lds_dwordx4 v[192:193], off
	v_lshl_add_u64 v[192:193], s[14:15], 0, v[134:135]
	s_mov_b32 m0, s26
	s_nop 0
	global_load_lds_dwordx4 v[192:193], off
	s_waitcnt lgkmcnt(8)
	s_barrier
	s_waitcnt lgkmcnt(0)
	s_waitcnt lgkmcnt(0)
	v_mfma_f32_16x16x32_f16 v[122:125], v[144:147], v[160:163], v[122:125]
	v_mfma_f32_16x16x32_f16 v[126:129], v[152:155], v[160:163], v[126:129]
	v_mfma_f32_16x16x32_f16 v[114:117], v[144:147], v[168:171], v[114:117]
	v_mfma_f32_16x16x32_f16 v[118:121], v[152:155], v[168:171], v[118:121]
	v_mfma_f32_16x16x32_f16 v[106:109], v[144:147], v[176:179], v[106:109]
	v_mfma_f32_16x16x32_f16 v[110:113], v[152:155], v[176:179], v[110:113]
	v_mfma_f32_16x16x32_f16 v[98:101], v[144:147], v[184:187], v[98:101]
	v_mfma_f32_16x16x32_f16 v[102:105], v[152:155], v[184:187], v[102:105]
	v_mfma_f32_16x16x32_f16 v[122:125], v[148:151], v[164:167], v[122:125]
	v_mfma_f32_16x16x32_f16 v[126:129], v[156:159], v[164:167], v[126:129]
	v_mfma_f32_16x16x32_f16 v[114:117], v[148:151], v[172:175], v[114:117]
	v_mfma_f32_16x16x32_f16 v[118:121], v[156:159], v[172:175], v[118:121]
	v_mfma_f32_16x16x32_f16 v[106:109], v[148:151], v[180:183], v[106:109]
	v_mfma_f32_16x16x32_f16 v[110:113], v[156:159], v[180:183], v[110:113]
	v_mfma_f32_16x16x32_f16 v[98:101], v[148:151], v[188:191], v[98:101]
	v_mfma_f32_16x16x32_f16 v[102:105], v[156:159], v[188:191], v[102:105]
	s_barrier
	s_mov_b32 m0, s29
	v_or_b32_e32 v192, 0x1c000, v142
	v_add_u32_e32 v196, 0x1c400, v142
	v_add_u32_e32 v200, 0x1c800, v142
	v_add_u32_e32 v204, 0x1cc00, v142
	v_lshl_add_u64 v[208:209], v[208:209], 0, s[86:87]
	ds_read_b128 v[192:195], v192
	ds_read_b128 v[196:199], v196
	ds_read_b128 v[200:203], v200
	ds_read_b128 v[204:207], v204
	global_load_lds_dwordx4 v[208:209], off
	v_lshl_add_u64 v[208:209], v[210:211], 0, s[86:87]
	s_mov_b32 m0, s30
	s_nop 0
	global_load_lds_dwordx4 v[208:209], off
	s_barrier
; #define G_STAGE(bufoff, gbase, v0, v1) do { \
;     __builtin_amdgcn_global_load_lds((const unsigned*)((const char*)(gbase) + (v0)), (LAS unsigned*)(lds + (bufoff) + ldsw), 16, 0, 0); \
;     __builtin_amdgcn_global_load_lds((const unsigned*)((const char*)(gbase) + (v1)), (LAS unsigned*)(lds + (bufoff) + ldsw + 8192), 16, 0, 0); } while (0)
; #define G_LDA(dst, b, h) do { _Pragma("unroll") for (int m = 0; m < 4; ++m) _Pragma("unroll") for (int k = 0; k < 2; ++k) dst[m][k] = *(const LAS h8*)(lds + G_SA(b, h) + aoff + m * 2048 + k * 1024); } while (0)
; #define G_LDB(dst, b, h) do { _Pragma("unroll") for (int n = 0; n < 2; ++n) _Pragma("unroll") for (int k = 0; k < 2; ++k) dst[n][k] = *(const LAS h8*)(lds + G_SB(b, h) + boff + n * 2048 + k * 1024); } while (0)
; #define G_MMA(ai, bj, At, Bt) do { __builtin_amdgcn_s_setprio(1); _Pragma("unroll") for (int m = 0; m < 4; ++m) _Pragma("unroll") for (int n = 0; n < 2; ++n) _Pragma("unroll") for (int k = 0; k < 2; ++k) \
;     acc[ai][bj][m][n] = __builtin_amdgcn_mfma_f32_16x16x32_f16(Bt[n][k], At[m][k], acc[ai][bj][m][n], 0, 0, 0); __builtin_amdgcn_s_setprio(0); } while (0)
; #define G_WAIT_V(n) asm volatile("s_waitcnt vmcnt(" #n ")" ::: "memory")
; #define G_WAIT_L(n) asm volatile("s_waitcnt lgkmcnt(" #n ")" ::: "memory")
; #define G_BAR __builtin_amdgcn_s_barrier()
; #define G_SCHED __builtin_amdgcn_sched_barrier(0)
; template <bool PERM, class Sched, class Epi>
; DI void gemm256(LAS unsigned char* lds, const Sched& S, const Epi& E, int wv_) {
;     ...
;       G_LDB(B1, 1, 1); G_STAGE(G_SB(1, 0), b3, cvB0, cvB1);
;       G_BAR; G_WAIT_L(0); G_MMA(0, 1, At, B1); G_BAR;
;       G_LDA(At, 1, 1); G_STAGE(G_SA(1, 0), a3, cvA0, cvA1);
;       G_BAR; G_WAIT_L(0); G_MMA(1, 0, At, B0); G_BAR; G_SCHED;
;       G_STAGE(G_SB(1, 1), b3 + chB, cvB0, cvB1);
;       G_WAIT_V(6); G_BAR; G_MMA(1, 1, At, B1); G_BAR;
;     }
	s_waitcnt lgkmcnt(0)
	s_waitcnt lgkmcnt(0)
	v_mfma_f32_16x16x32_f16 v[58:61], v[192:195], v[160:163], v[58:61]
	v_mfma_f32_16x16x32_f16 v[62:65], v[200:203], v[160:163], v[62:65]
	v_mfma_f32_16x16x32_f16 v[50:53], v[192:195], v[168:171], v[50:53]
	v_mfma_f32_16x16x32_f16 v[54:57], v[200:203], v[168:171], v[54:57]
	v_mfma_f32_16x16x32_f16 v[42:45], v[192:195], v[176:179], v[42:45]
	v_mfma_f32_16x16x32_f16 v[46:49], v[200:203], v[176:179], v[46:49]
	v_mfma_f32_16x16x32_f16 v[34:37], v[192:195], v[184:187], v[34:37]
	v_mfma_f32_16x16x32_f16 v[38:41], v[200:203], v[184:187], v[38:41]
	v_mfma_f32_16x16x32_f16 v[58:61], v[196:199], v[164:167], v[58:61]
	v_mfma_f32_16x16x32_f16 v[62:65], v[204:207], v[164:167], v[62:65]
	v_mfma_f32_16x16x32_f16 v[50:53], v[196:199], v[172:175], v[50:53]
	v_mfma_f32_16x16x32_f16 v[54:57], v[204:207], v[172:175], v[54:57]
	v_mfma_f32_16x16x32_f16 v[42:45], v[196:199], v[180:183], v[42:45]
	v_mfma_f32_16x16x32_f16 v[46:49], v[204:207], v[180:183], v[46:49]
	v_mfma_f32_16x16x32_f16 v[34:37], v[196:199], v[188:191], v[34:37]
	v_mfma_f32_16x16x32_f16 v[38:41], v[204:207], v[188:191], v[38:41]
	s_mov_b32 m0, s31
	v_lshl_add_u64 v[208:209], v[212:213], 0, s[86:87]
	s_barrier
	ds_read_b128 v[160:163], v1 offset:49152
	ds_read_b128 v[164:167], v1 offset:50176
	ds_read_b128 v[168:171], v1 offset:51200
	ds_read_b128 v[172:175], v1 offset:52224
	ds_read_b128 v[176:179], v1 offset:53248
	ds_read_b128 v[180:183], v1 offset:54272
	ds_read_b128 v[184:187], v1 offset:55296
	ds_read_b128 v[188:191], v1 offset:56320
	global_load_lds_dwordx4 v[208:209], off
	v_lshl_add_u64 v[208:209], v[214:215], 0, s[86:87]
	s_mov_b32 m0, s34
	s_nop 0
	global_load_lds_dwordx4 v[208:209], off
	s_barrier
	s_waitcnt lgkmcnt(0)
	s_waitcnt lgkmcnt(0)
	v_mfma_f32_16x16x32_f16 v[90:93], v[144:147], v[160:163], v[90:93]
	v_mfma_f32_16x16x32_f16 v[94:97], v[152:155], v[160:163], v[94:97]
	v_mfma_f32_16x16x32_f16 v[82:85], v[144:147], v[168:171], v[82:85]
	v_mfma_f32_16x16x32_f16 v[86:89], v[152:155], v[168:171], v[86:89]
	v_mfma_f32_16x16x32_f16 v[74:77], v[144:147], v[176:179], v[74:77]
	v_mfma_f32_16x16x32_f16 v[78:81], v[152:155], v[176:179], v[78:81]
	v_mfma_f32_16x16x32_f16 v[66:69], v[144:147], v[184:187], v[66:69]
	v_mfma_f32_16x16x32_f16 v[70:73], v[152:155], v[184:187], v[70:73]
	v_mfma_f32_16x16x32_f16 v[90:93], v[148:151], v[164:167], v[90:93]
	v_mfma_f32_16x16x32_f16 v[94:97], v[156:159], v[164:167], v[94:97]
	v_mfma_f32_16x16x32_f16 v[82:85], v[148:151], v[172:175], v[82:85]
	v_mfma_f32_16x16x32_f16 v[86:89], v[156:159], v[172:175], v[86:89]
	v_mfma_f32_16x16x32_f16 v[74:77], v[148:151], v[180:183], v[74:77]
	v_mfma_f32_16x16x32_f16 v[78:81], v[156:159], v[180:183], v[78:81]
	v_mfma_f32_16x16x32_f16 v[66:69], v[148:151], v[188:191], v[66:69]
	v_mfma_f32_16x16x32_f16 v[70:73], v[156:159], v[188:191], v[70:73]
	s_barrier
	s_add_u32 s12, s12, 0x10080
	s_addc_u32 s13, s13, 0
	s_mov_b32 m0, s35
	v_lshl_add_u64 v[144:145], s[12:13], 0, v[132:133]
	global_load_lds_dwordx4 v[144:145], off
	v_lshl_add_u64 v[144:145], s[12:13], 0, v[136:137]
	s_mov_b32 m0, s37
	s_nop 0
	global_load_lds_dwordx4 v[144:145], off
	s_waitcnt vmcnt(6)
	s_barrier
	v_mfma_f32_16x16x32_f16 v[26:29], v[192:195], v[160:163], v[26:29]
	v_mfma_f32_16x16x32_f16 v[30:33], v[200:203], v[160:163], v[30:33]
	v_mfma_f32_16x16x32_f16 v[18:21], v[192:195], v[168:171], v[18:21]
	v_mfma_f32_16x16x32_f16 v[22:25], v[200:203], v[168:171], v[22:25]
	v_mfma_f32_16x16x32_f16 v[10:13], v[192:195], v[176:179], v[10:13]
	v_mfma_f32_16x16x32_f16 v[14:17], v[200:203], v[176:179], v[14:17]
	v_mfma_f32_16x16x32_f16 v[6:9], v[192:195], v[184:187], v[6:9]
	v_mfma_f32_16x16x32_f16 v[2:5], v[200:203], v[184:187], v[2:5]
	v_mfma_f32_16x16x32_f16 v[26:29], v[196:199], v[164:167], v[26:29]
	v_mfma_f32_16x16x32_f16 v[30:33], v[204:207], v[164:167], v[30:33]
	v_mfma_f32_16x16x32_f16 v[18:21], v[196:199], v[172:175], v[18:21]
	v_mfma_f32_16x16x32_f16 v[22:25], v[204:207], v[172:175], v[22:25]
	v_mfma_f32_16x16x32_f16 v[10:13], v[196:199], v[180:183], v[10:13]
	v_mfma_f32_16x16x32_f16 v[14:17], v[204:207], v[180:183], v[14:17]
	v_mfma_f32_16x16x32_f16 v[6:9], v[196:199], v[188:191], v[6:9]
	v_mfma_f32_16x16x32_f16 v[2:5], v[204:207], v[188:191], v[2:5]
	s_add_u32 s10, s10, 0x100
	s_addc_u32 s11, s11, 0
	s_add_u32 s75, s75, 0x100
	s_addc_u32 s46, s46, 0
	s_cmp_ge_i32 s74, s79
	s_mov_b32 s12, s74
	s_barrier
	s_cbranch_scc0 .LBB0_1718
	s_mov_b32 s93, 0x23fff
	s_movk_i32 s85, 0x800
	s_branch .LBB0_1721

; #define G_STAGE(bufoff, gbase, v0, v1) do { \
;     __builtin_amdgcn_global_load_lds((const unsigned*)((const char*)(gbase) + (v0)), (LAS unsigned*)(lds + (bufoff) + ldsw), 16, 0, 0); \
;     __builtin_amdgcn_global_load_lds((const unsigned*)((const char*)(gbase) + (v1)), (LAS unsigned*)(lds + (bufoff) + ldsw + 8192), 16, 0, 0); } while (0)
; #define G_LDA(dst, b, h) do { _Pragma("unroll") for (int m = 0; m < 4; ++m) _Pragma("unroll") for (int k = 0; k < 2; ++k) dst[m][k] = *(const LAS h8*)(lds + G_SA(b, h) + aoff + m * 2048 + k * 1024); } while (0)
; #define G_LDB(dst, b, h) do { _Pragma("unroll") for (int n = 0; n < 2; ++n) _Pragma("unroll") for (int k = 0; k < 2; ++k) dst[n][k] = *(const LAS h8*)(lds + G_SB(b, h) + boff + n * 2048 + k * 1024); } while (0)
; #define G_MMA(ai, bj, At, Bt) do { __builtin_amdgcn_s_setprio(1); _Pragma("unroll") for (int m = 0; m < 4; ++m) _Pragma("unroll") for (int n = 0; n < 2; ++n) _Pragma("unroll") for (int k = 0; k < 2; ++k) \
;     acc[ai][bj][m][n] = __builtin_amdgcn_mfma_f32_16x16x32_f16(Bt[n][k], At[m][k], acc[ai][bj][m][n], 0, 0, 0); __builtin_amdgcn_s_setprio(0); } while (0)
; #define G_WAIT_L(n) asm volatile("s_waitcnt lgkmcnt(" #n ")" ::: "memory")
; #define G_BAR __builtin_amdgcn_s_barrier()
; #define G_SCHED __builtin_amdgcn_sched_barrier(0)
; template <bool PERM, class Sched, class Epi>
; DI void gemm256(LAS unsigned char* lds, const Sched& S, const Epi& E, int wv_) {
;     ...
;     for (int t = 0; t < nt; t += 2) {
;       const bool last = (t == nt - 2);
;       const char* a1 = cA + (size_t)(t + 1) * kstep;
;       const char* a2 = last ? nA : cA + (size_t)(t + 2) * kstep;
;       const char* b2 = last ? nB : cB + (size_t)(t + 2) * kstep;
;       const char* a3 = a2 + kstep;
;       const char* b3 = b2 + kstep;
;       G_LDB(B0, 0, 0); G_SCHED; G_LDA(At, 0, 0); G_STAGE(G_SA(1, 1), a1 + chA, cvA0, cvA1);
;       G_WAIT_L(8); G_BAR; G_WAIT_L(0); G_MMA(0, 0, At, B0); G_BAR; G_SCHED;
;       G_LDB(B1, 0, 1); G_STAGE(G_SB(0, 0), b2, cvB0, cvB1);
;       G_BAR; G_WAIT_L(0); G_MMA(0, 1, At, B1); G_BAR;
;       G_LDA(At, 0, 1); G_STAGE(G_SA(0, 0), a2, cvA0, cvA1);
;       G_BAR; G_WAIT_L(0); G_MMA(1, 0, At, B0); G_BAR; G_SCHED;
.LBB0_1748:
	s_add_i32 s60, s12, 2
	s_add_u32 s10, s8, 0x100
	s_addc_u32 s11, s9, 0
	v_or_b32_e32 v144, 0x10000, v142
	v_add_u32_e32 v148, 0x10400, v142
	v_add_u32_e32 v152, 0x10800, v142
	v_add_u32_e32 v156, 0x10c00, v142
	s_add_u32 s13, s58, s8
	ds_read_b128 v[144:147], v144
	ds_read_b128 v[148:151], v148
	ds_read_b128 v[152:155], v152
	ds_read_b128 v[156:159], v156
	s_addc_u32 s14, s59, s9
	s_cmp_eq_u32 s56, s12
	s_cselect_b32 s40, 0, s10
	s_cselect_b32 s15, 0, s11
	s_cselect_b32 s12, s4, s13
	s_cselect_b32 s13, s5, s14
	s_add_u32 s14, s2, s40
	s_addc_u32 s15, s3, s15
	v_lshl_add_u64 v[192:193], v[138:139], 0, s[8:9]
	s_add_i32 m0, s17, 0xc000
	ds_read_b128 v[160:163], v1
	ds_read_b128 v[164:167], v1 offset:1024
	ds_read_b128 v[168:171], v1 offset:2048
	ds_read_b128 v[172:175], v1 offset:3072
	ds_read_b128 v[176:179], v1 offset:4096
	ds_read_b128 v[180:183], v1 offset:5120
	ds_read_b128 v[184:187], v1 offset:6144
	ds_read_b128 v[188:191], v1 offset:7168
	global_load_lds_dwordx4 v[192:193], off
	v_lshl_add_u64 v[192:193], v[140:141], 0, s[8:9]
	s_add_i32 m0, s17, 0xe000
	s_nop 0
	global_load_lds_dwordx4 v[192:193], off
	s_waitcnt lgkmcnt(8)
	s_barrier
	s_waitcnt lgkmcnt(0)
	s_waitcnt lgkmcnt(0)
	v_mfma_f32_16x16x32_f16 v[122:125], v[144:147], v[160:163], v[122:125]
	v_mfma_f32_16x16x32_f16 v[126:129], v[152:155], v[160:163], v[126:129]
	v_mfma_f32_16x16x32_f16 v[106:109], v[144:147], v[168:171], v[106:109]
	v_mfma_f32_16x16x32_f16 v[110:113], v[152:155], v[168:171], v[110:113]
	v_mfma_f32_16x16x32_f16 v[90:93], v[144:147], v[176:179], v[90:93]
	v_mfma_f32_16x16x32_f16 v[94:97], v[152:155], v[176:179], v[94:97]
	v_mfma_f32_16x16x32_f16 v[74:77], v[144:147], v[184:187], v[74:77]
	v_mfma_f32_16x16x32_f16 v[78:81], v[152:155], v[184:187], v[78:81]
	v_mfma_f32_16x16x32_f16 v[122:125], v[148:151], v[164:167], v[122:125]
	v_mfma_f32_16x16x32_f16 v[126:129], v[156:159], v[164:167], v[126:129]
	v_mfma_f32_16x16x32_f16 v[106:109], v[148:151], v[172:175], v[106:109]
	v_mfma_f32_16x16x32_f16 v[110:113], v[156:159], v[172:175], v[110:113]
	v_mfma_f32_16x16x32_f16 v[90:93], v[148:151], v[180:183], v[90:93]
	v_mfma_f32_16x16x32_f16 v[94:97], v[156:159], v[180:183], v[94:97]
	v_mfma_f32_16x16x32_f16 v[74:77], v[148:151], v[188:191], v[74:77]
	v_mfma_f32_16x16x32_f16 v[78:81], v[156:159], v[188:191], v[78:81]
	s_barrier
	s_mov_b32 m0, s18
	v_or_b32_e32 v192, 0x14000, v142
	v_add_u32_e32 v196, 0x14400, v142
	v_add_u32_e32 v200, 0x14800, v142
	v_add_u32_e32 v204, 0x14c00, v142
	v_lshl_add_u64 v[208:209], s[12:13], 0, v[134:135]
	ds_read_b128 v[192:195], v192
	ds_read_b128 v[196:199], v196
	ds_read_b128 v[200:203], v200
	ds_read_b128 v[204:207], v204
	global_load_lds_dwordx4 v[208:209], off
	v_lshl_add_u64 v[210:211], s[12:13], 0, v[130:131]
	s_mov_b32 m0, s19
	s_nop 0
	global_load_lds_dwordx4 v[210:211], off
	s_barrier
	s_waitcnt lgkmcnt(0)
	s_waitcnt lgkmcnt(0)
	v_mfma_f32_16x16x32_f16 v[114:117], v[192:195], v[160:163], v[114:117]
	v_mfma_f32_16x16x32_f16 v[118:121], v[200:203], v[160:163], v[118:121]
	v_mfma_f32_16x16x32_f16 v[98:101], v[192:195], v[168:171], v[98:101]
	v_mfma_f32_16x16x32_f16 v[102:105], v[200:203], v[168:171], v[102:105]
	v_mfma_f32_16x16x32_f16 v[82:85], v[192:195], v[176:179], v[82:85]
	v_mfma_f32_16x16x32_f16 v[86:89], v[200:203], v[176:179], v[86:89]
	v_mfma_f32_16x16x32_f16 v[66:69], v[192:195], v[184:187], v[66:69]
	v_mfma_f32_16x16x32_f16 v[70:73], v[200:203], v[184:187], v[70:73]
	v_mfma_f32_16x16x32_f16 v[114:117], v[196:199], v[164:167], v[114:117]
	v_mfma_f32_16x16x32_f16 v[118:121], v[204:207], v[164:167], v[118:121]
	v_mfma_f32_16x16x32_f16 v[98:101], v[196:199], v[172:175], v[98:101]
	v_mfma_f32_16x16x32_f16 v[102:105], v[204:207], v[172:175], v[102:105]
	v_mfma_f32_16x16x32_f16 v[82:85], v[196:199], v[180:183], v[82:85]
	v_mfma_f32_16x16x32_f16 v[86:89], v[204:207], v[180:183], v[86:89]
	v_mfma_f32_16x16x32_f16 v[66:69], v[196:199], v[188:191], v[66:69]
	v_mfma_f32_16x16x32_f16 v[70:73], v[204:207], v[188:191], v[70:73]
	s_mov_b32 m0, s17
	v_lshl_add_u64 v[212:213], s[14:15], 0, v[136:137]
	s_barrier
	ds_read_b128 v[160:163], v1 offset:16384
	ds_read_b128 v[164:167], v1 offset:17408
	ds_read_b128 v[168:171], v1 offset:18432
	ds_read_b128 v[172:175], v1 offset:19456
	ds_read_b128 v[176:179], v1 offset:20480
	ds_read_b128 v[180:183], v1 offset:21504
	ds_read_b128 v[184:187], v1 offset:22528
	ds_read_b128 v[188:191], v1 offset:23552
	global_load_lds_dwordx4 v[212:213], off
	v_lshl_add_u64 v[214:215], s[14:15], 0, v[132:133]
	s_mov_b32 m0, s20
	s_nop 0
	global_load_lds_dwordx4 v[214:215], off
	s_barrier
	s_waitcnt lgkmcnt(0)
	s_waitcnt lgkmcnt(0)
	v_mfma_f32_16x16x32_f16 v[58:61], v[144:147], v[160:163], v[58:61]
	v_mfma_f32_16x16x32_f16 v[62:65], v[152:155], v[160:163], v[62:65]
	v_mfma_f32_16x16x32_f16 v[42:45], v[144:147], v[168:171], v[42:45]
	v_mfma_f32_16x16x32_f16 v[46:49], v[152:155], v[168:171], v[46:49]
	v_mfma_f32_16x16x32_f16 v[26:29], v[144:147], v[176:179], v[26:29]
	v_mfma_f32_16x16x32_f16 v[30:33], v[152:155], v[176:179], v[30:33]
	v_mfma_f32_16x16x32_f16 v[10:13], v[144:147], v[184:187], v[10:13]
	v_mfma_f32_16x16x32_f16 v[14:17], v[152:155], v[184:187], v[14:17]
	v_mfma_f32_16x16x32_f16 v[58:61], v[148:151], v[164:167], v[58:61]
	v_mfma_f32_16x16x32_f16 v[62:65], v[156:159], v[164:167], v[62:65]
	v_mfma_f32_16x16x32_f16 v[42:45], v[148:151], v[172:175], v[42:45]
	v_mfma_f32_16x16x32_f16 v[46:49], v[156:159], v[172:175], v[46:49]
	v_mfma_f32_16x16x32_f16 v[26:29], v[148:151], v[180:183], v[26:29]
	v_mfma_f32_16x16x32_f16 v[30:33], v[156:159], v[180:183], v[30:33]
	v_mfma_f32_16x16x32_f16 v[10:13], v[148:151], v[188:191], v[10:13]
	v_mfma_f32_16x16x32_f16 v[14:17], v[156:159], v[188:191], v[14:17]
	s_barrier
; #define G_STAGE(bufoff, gbase, v0, v1) do { \
;     __builtin_amdgcn_global_load_lds((const unsigned*)((const char*)(gbase) + (v0)), (LAS unsigned*)(lds + (bufoff) + ldsw), 16, 0, 0); \
;     __builtin_amdgcn_global_load_lds((const unsigned*)((const char*)(gbase) + (v1)), (LAS unsigned*)(lds + (bufoff) + ldsw + 8192), 16, 0, 0); } while (0)
; #define G_LDA(dst, b, h) do { _Pragma("unroll") for (int m = 0; m < 4; ++m) _Pragma("unroll") for (int k = 0; k < 2; ++k) dst[m][k] = *(const LAS h8*)(lds + G_SA(b, h) + aoff + m * 2048 + k * 1024); } while (0)
; #define G_LDB(dst, b, h) do { _Pragma("unroll") for (int n = 0; n < 2; ++n) _Pragma("unroll") for (int k = 0; k < 2; ++k) dst[n][k] = *(const LAS h8*)(lds + G_SB(b, h) + boff + n * 2048 + k * 1024); } while (0)
; #define G_MMA(ai, bj, At, Bt) do { __builtin_amdgcn_s_setprio(1); _Pragma("unroll") for (int m = 0; m < 4; ++m) _Pragma("unroll") for (int n = 0; n < 2; ++n) _Pragma("unroll") for (int k = 0; k < 2; ++k) \
;     acc[ai][bj][m][n] = __builtin_amdgcn_mfma_f32_16x16x32_f16(Bt[n][k], At[m][k], acc[ai][bj][m][n], 0, 0, 0); __builtin_amdgcn_s_setprio(0); } while (0)
; #define G_WAIT_V(n) asm volatile("s_waitcnt vmcnt(" #n ")" ::: "memory")
; #define G_WAIT_L(n) asm volatile("s_waitcnt lgkmcnt(" #n ")" ::: "memory")
; #define G_BAR __builtin_amdgcn_s_barrier()
; #define G_SCHED __builtin_amdgcn_sched_barrier(0)
; template <bool PERM, class Sched, class Epi>
; DI void gemm256(LAS unsigned char* lds, const Sched& S, const Epi& E, int wv_) {
;     ...
;       G_STAGE(G_SB(0, 1), b2 + chB, cvB0, cvB1);
;       G_WAIT_V(6); G_BAR; G_MMA(1, 1, At, B1); G_BAR;
;       G_LDB(B0, 1, 0); G_SCHED; G_LDA(At, 1, 0); G_STAGE(G_SA(0, 1), a2 + chA, cvA0, cvA1);
;       G_WAIT_L(8); G_BAR; G_WAIT_L(0); G_MMA(0, 0, At, B0); G_BAR; G_SCHED;
;       G_LDB(B1, 1, 1); G_STAGE(G_SB(1, 0), b3, cvB0, cvB1);
	s_add_u32 s8, s12, 0x16000
	s_addc_u32 s9, s13, 0
	s_mov_b32 m0, s21
	v_lshl_add_u64 v[144:145], s[8:9], 0, v[134:135]
	global_load_lds_dwordx4 v[144:145], off
	v_lshl_add_u64 v[144:145], s[8:9], 0, v[130:131]
	s_mov_b32 m0, s22
	s_nop 0
	global_load_lds_dwordx4 v[144:145], off
	s_waitcnt vmcnt(6)
	s_barrier
	v_mfma_f32_16x16x32_f16 v[50:53], v[192:195], v[160:163], v[50:53]
	v_mfma_f32_16x16x32_f16 v[54:57], v[200:203], v[160:163], v[54:57]
	v_mfma_f32_16x16x32_f16 v[34:37], v[192:195], v[168:171], v[34:37]
	v_mfma_f32_16x16x32_f16 v[38:41], v[200:203], v[168:171], v[38:41]
	v_mfma_f32_16x16x32_f16 v[18:21], v[192:195], v[176:179], v[18:21]
	v_mfma_f32_16x16x32_f16 v[22:25], v[200:203], v[176:179], v[22:25]
	v_mfma_f32_16x16x32_f16 v[6:9], v[192:195], v[184:187], v[6:9]
	v_mfma_f32_16x16x32_f16 v[2:5], v[200:203], v[184:187], v[2:5]
	v_mfma_f32_16x16x32_f16 v[50:53], v[196:199], v[164:167], v[50:53]
	v_mfma_f32_16x16x32_f16 v[54:57], v[204:207], v[164:167], v[54:57]
	v_mfma_f32_16x16x32_f16 v[34:37], v[196:199], v[172:175], v[34:37]
	v_mfma_f32_16x16x32_f16 v[38:41], v[204:207], v[172:175], v[38:41]
	v_mfma_f32_16x16x32_f16 v[18:21], v[196:199], v[180:183], v[18:21]
	v_mfma_f32_16x16x32_f16 v[22:25], v[204:207], v[180:183], v[22:25]
	v_mfma_f32_16x16x32_f16 v[6:9], v[196:199], v[188:191], v[6:9]
	v_mfma_f32_16x16x32_f16 v[2:5], v[204:207], v[188:191], v[2:5]
	v_or_b32_e32 v144, 0x18000, v142
	v_add_u32_e32 v148, 0x18400, v142
	v_add_u32_e32 v152, 0x18800, v142
	v_add_u32_e32 v156, 0x18c00, v142
	s_barrier
	ds_read_b128 v[144:147], v144
	ds_read_b128 v[148:151], v148
	ds_read_b128 v[152:155], v152
	ds_read_b128 v[156:159], v156
	s_add_u32 s8, s14, 0x10000
	s_addc_u32 s9, s15, 0
	s_mov_b32 m0, s23
	v_lshl_add_u64 v[192:193], s[8:9], 0, v[136:137]
	ds_read_b128 v[160:163], v1 offset:32768
	ds_read_b128 v[164:167], v1 offset:33792
	ds_read_b128 v[168:171], v1 offset:34816
	ds_read_b128 v[172:175], v1 offset:35840
	ds_read_b128 v[176:179], v1 offset:36864
	ds_read_b128 v[180:183], v1 offset:37888
	ds_read_b128 v[184:187], v1 offset:38912
	ds_read_b128 v[188:191], v1 offset:39936
	global_load_lds_dwordx4 v[192:193], off
	v_lshl_add_u64 v[192:193], s[8:9], 0, v[132:133]
	s_mov_b32 m0, s24
	s_nop 0
	global_load_lds_dwordx4 v[192:193], off
	s_waitcnt lgkmcnt(8)
	s_barrier
	s_waitcnt lgkmcnt(0)
	s_waitcnt lgkmcnt(0)
	v_mfma_f32_16x16x32_f16 v[122:125], v[144:147], v[160:163], v[122:125]
	v_mfma_f32_16x16x32_f16 v[126:129], v[152:155], v[160:163], v[126:129]
	v_mfma_f32_16x16x32_f16 v[106:109], v[144:147], v[168:171], v[106:109]
	v_mfma_f32_16x16x32_f16 v[110:113], v[152:155], v[168:171], v[110:113]
	v_mfma_f32_16x16x32_f16 v[90:93], v[144:147], v[176:179], v[90:93]
	v_mfma_f32_16x16x32_f16 v[94:97], v[152:155], v[176:179], v[94:97]
	v_mfma_f32_16x16x32_f16 v[74:77], v[144:147], v[184:187], v[74:77]
	v_mfma_f32_16x16x32_f16 v[78:81], v[152:155], v[184:187], v[78:81]
	v_mfma_f32_16x16x32_f16 v[122:125], v[148:151], v[164:167], v[122:125]
	v_mfma_f32_16x16x32_f16 v[126:129], v[156:159], v[164:167], v[126:129]
	v_mfma_f32_16x16x32_f16 v[106:109], v[148:151], v[172:175], v[106:109]
	v_mfma_f32_16x16x32_f16 v[110:113], v[156:159], v[172:175], v[110:113]
	v_mfma_f32_16x16x32_f16 v[90:93], v[148:151], v[180:183], v[90:93]
	v_mfma_f32_16x16x32_f16 v[94:97], v[156:159], v[180:183], v[94:97]
	v_mfma_f32_16x16x32_f16 v[74:77], v[148:151], v[188:191], v[74:77]
	v_mfma_f32_16x16x32_f16 v[78:81], v[156:159], v[188:191], v[78:81]
	s_barrier
	s_mov_b32 m0, s25
	v_or_b32_e32 v192, 0x1c000, v142
	v_add_u32_e32 v196, 0x1c400, v142
	v_add_u32_e32 v200, 0x1c800, v142
	v_add_u32_e32 v204, 0x1cc00, v142
	v_lshl_add_u64 v[208:209], v[208:209], 0, s[86:87]
	ds_read_b128 v[192:195], v192
	ds_read_b128 v[196:199], v196
	ds_read_b128 v[200:203], v200
	ds_read_b128 v[204:207], v204
	global_load_lds_dwordx4 v[208:209], off
	v_lshl_add_u64 v[208:209], v[210:211], 0, s[86:87]
	s_mov_b32 m0, s26
	s_nop 0
	global_load_lds_dwordx4 v[208:209], off
	s_barrier
; #define G_STAGE(bufoff, gbase, v0, v1) do { \
;     __builtin_amdgcn_global_load_lds((const unsigned*)((const char*)(gbase) + (v0)), (LAS unsigned*)(lds + (bufoff) + ldsw), 16, 0, 0); \
;     __builtin_amdgcn_global_load_lds((const unsigned*)((const char*)(gbase) + (v1)), (LAS unsigned*)(lds + (bufoff) + ldsw + 8192), 16, 0, 0); } while (0)
; #define G_LDA(dst, b, h) do { _Pragma("unroll") for (int m = 0; m < 4; ++m) _Pragma("unroll") for (int k = 0; k < 2; ++k) dst[m][k] = *(const LAS h8*)(lds + G_SA(b, h) + aoff + m * 2048 + k * 1024); } while (0)
; #define G_LDB(dst, b, h) do { _Pragma("unroll") for (int n = 0; n < 2; ++n) _Pragma("unroll") for (int k = 0; k < 2; ++k) dst[n][k] = *(const LAS h8*)(lds + G_SB(b, h) + boff + n * 2048 + k * 1024); } while (0)
; #define G_MMA(ai, bj, At, Bt) do { __builtin_amdgcn_s_setprio(1); _Pragma("unroll") for (int m = 0; m < 4; ++m) _Pragma("unroll") for (int n = 0; n < 2; ++n) _Pragma("unroll") for (int k = 0; k < 2; ++k) \
;     acc[ai][bj][m][n] = __builtin_amdgcn_mfma_f32_16x16x32_f16(Bt[n][k], At[m][k], acc[ai][bj][m][n], 0, 0, 0); __builtin_amdgcn_s_setprio(0); } while (0)
; #define G_WAIT_V(n) asm volatile("s_waitcnt vmcnt(" #n ")" ::: "memory")
; #define G_WAIT_L(n) asm volatile("s_waitcnt lgkmcnt(" #n ")" ::: "memory")
; #define G_BAR __builtin_amdgcn_s_barrier()
; #define G_SCHED __builtin_amdgcn_sched_barrier(0)
; template <bool PERM, class Sched, class Epi>
; DI void gemm256(LAS unsigned char* lds, const Sched& S, const Epi& E, int wv_) {
;     ...
;       G_LDB(B1, 1, 1); G_STAGE(G_SB(1, 0), b3, cvB0, cvB1);
;       G_BAR; G_WAIT_L(0); G_MMA(0, 1, At, B1); G_BAR;
;       G_LDA(At, 1, 1); G_STAGE(G_SA(1, 0), a3, cvA0, cvA1);
;       G_BAR; G_WAIT_L(0); G_MMA(1, 0, At, B0); G_BAR; G_SCHED;
;       G_STAGE(G_SB(1, 1), b3 + chB, cvB0, cvB1);
;       G_WAIT_V(6); G_BAR; G_MMA(1, 1, At, B1); G_BAR;
;     }
	s_waitcnt lgkmcnt(0)
	s_waitcnt lgkmcnt(0)
	v_mfma_f32_16x16x32_f16 v[114:117], v[192:195], v[160:163], v[114:117]
	v_mfma_f32_16x16x32_f16 v[118:121], v[200:203], v[160:163], v[118:121]
	v_mfma_f32_16x16x32_f16 v[98:101], v[192:195], v[168:171], v[98:101]
	v_mfma_f32_16x16x32_f16 v[102:105], v[200:203], v[168:171], v[102:105]
	v_mfma_f32_16x16x32_f16 v[82:85], v[192:195], v[176:179], v[82:85]
	v_mfma_f32_16x16x32_f16 v[86:89], v[200:203], v[176:179], v[86:89]
	v_mfma_f32_16x16x32_f16 v[66:69], v[192:195], v[184:187], v[66:69]
	v_mfma_f32_16x16x32_f16 v[70:73], v[200:203], v[184:187], v[70:73]
	v_mfma_f32_16x16x32_f16 v[114:117], v[196:199], v[164:167], v[114:117]
	v_mfma_f32_16x16x32_f16 v[118:121], v[204:207], v[164:167], v[118:121]
	v_mfma_f32_16x16x32_f16 v[98:101], v[196:199], v[172:175], v[98:101]
	v_mfma_f32_16x16x32_f16 v[102:105], v[204:207], v[172:175], v[102:105]
	v_mfma_f32_16x16x32_f16 v[82:85], v[196:199], v[180:183], v[82:85]
	v_mfma_f32_16x16x32_f16 v[86:89], v[204:207], v[180:183], v[86:89]
	v_mfma_f32_16x16x32_f16 v[66:69], v[196:199], v[188:191], v[66:69]
	v_mfma_f32_16x16x32_f16 v[70:73], v[204:207], v[188:191], v[70:73]
	s_mov_b32 m0, s27
	v_lshl_add_u64 v[208:209], v[212:213], 0, s[86:87]
	s_barrier
	ds_read_b128 v[160:163], v1 offset:49152
	ds_read_b128 v[164:167], v1 offset:50176
	ds_read_b128 v[168:171], v1 offset:51200
	ds_read_b128 v[172:175], v1 offset:52224
	ds_read_b128 v[176:179], v1 offset:53248
	ds_read_b128 v[180:183], v1 offset:54272
	ds_read_b128 v[184:187], v1 offset:55296
	ds_read_b128 v[188:191], v1 offset:56320
	global_load_lds_dwordx4 v[208:209], off
	v_lshl_add_u64 v[208:209], v[214:215], 0, s[86:87]
	s_mov_b32 m0, s28
	s_nop 0
	global_load_lds_dwordx4 v[208:209], off
	s_barrier
	s_waitcnt lgkmcnt(0)
	s_waitcnt lgkmcnt(0)
	v_mfma_f32_16x16x32_f16 v[58:61], v[144:147], v[160:163], v[58:61]
	v_mfma_f32_16x16x32_f16 v[62:65], v[152:155], v[160:163], v[62:65]
	v_mfma_f32_16x16x32_f16 v[42:45], v[144:147], v[168:171], v[42:45]
	v_mfma_f32_16x16x32_f16 v[46:49], v[152:155], v[168:171], v[46:49]
	v_mfma_f32_16x16x32_f16 v[26:29], v[144:147], v[176:179], v[26:29]
	v_mfma_f32_16x16x32_f16 v[30:33], v[152:155], v[176:179], v[30:33]
	v_mfma_f32_16x16x32_f16 v[10:13], v[144:147], v[184:187], v[10:13]
	v_mfma_f32_16x16x32_f16 v[14:17], v[152:155], v[184:187], v[14:17]
	v_mfma_f32_16x16x32_f16 v[58:61], v[148:151], v[164:167], v[58:61]
	v_mfma_f32_16x16x32_f16 v[62:65], v[156:159], v[164:167], v[62:65]
	v_mfma_f32_16x16x32_f16 v[42:45], v[148:151], v[172:175], v[42:45]
	v_mfma_f32_16x16x32_f16 v[46:49], v[156:159], v[172:175], v[46:49]
	v_mfma_f32_16x16x32_f16 v[26:29], v[148:151], v[180:183], v[26:29]
	v_mfma_f32_16x16x32_f16 v[30:33], v[156:159], v[180:183], v[30:33]
	v_mfma_f32_16x16x32_f16 v[10:13], v[148:151], v[188:191], v[10:13]
	v_mfma_f32_16x16x32_f16 v[14:17], v[156:159], v[188:191], v[14:17]
	s_barrier
	s_add_u32 s8, s12, 0x16080
	s_addc_u32 s9, s13, 0
	s_mov_b32 m0, s29
	v_lshl_add_u64 v[144:145], s[8:9], 0, v[134:135]
	global_load_lds_dwordx4 v[144:145], off
	v_lshl_add_u64 v[144:145], s[8:9], 0, v[130:131]
	s_mov_b32 m0, s30
	s_nop 0
	global_load_lds_dwordx4 v[144:145], off
	s_waitcnt vmcnt(6)
	s_barrier
	v_mfma_f32_16x16x32_f16 v[50:53], v[192:195], v[160:163], v[50:53]
	v_mfma_f32_16x16x32_f16 v[54:57], v[200:203], v[160:163], v[54:57]
	v_mfma_f32_16x16x32_f16 v[34:37], v[192:195], v[168:171], v[34:37]
	v_mfma_f32_16x16x32_f16 v[38:41], v[200:203], v[168:171], v[38:41]
	v_mfma_f32_16x16x32_f16 v[18:21], v[192:195], v[176:179], v[18:21]
	v_mfma_f32_16x16x32_f16 v[22:25], v[200:203], v[176:179], v[22:25]
	v_mfma_f32_16x16x32_f16 v[6:9], v[192:195], v[184:187], v[6:9]
	v_mfma_f32_16x16x32_f16 v[2:5], v[200:203], v[184:187], v[2:5]
	v_mfma_f32_16x16x32_f16 v[50:53], v[196:199], v[164:167], v[50:53]
	v_mfma_f32_16x16x32_f16 v[54:57], v[204:207], v[164:167], v[54:57]
	v_mfma_f32_16x16x32_f16 v[34:37], v[196:199], v[172:175], v[34:37]
	v_mfma_f32_16x16x32_f16 v[38:41], v[204:207], v[172:175], v[38:41]
	v_mfma_f32_16x16x32_f16 v[18:21], v[196:199], v[180:183], v[18:21]
	v_mfma_f32_16x16x32_f16 v[22:25], v[204:207], v[180:183], v[22:25]
	v_mfma_f32_16x16x32_f16 v[6:9], v[196:199], v[188:191], v[6:9]
	v_mfma_f32_16x16x32_f16 v[2:5], v[204:207], v[188:191], v[2:5]
	s_cmp_ge_i32 s60, s46
	s_mov_b64 s[8:9], s[10:11]
	s_mov_b32 s12, s60
	s_barrier
	s_cbranch_scc0 .LBB0_1748
	s_branch .LBB0_1743

; #define G_STAGE(bufoff, gbase, v0, v1) do { \
;     __builtin_amdgcn_global_load_lds((const unsigned*)((const char*)(gbase) + (v0)), (LAS unsigned*)(lds + (bufoff) + ldsw), 16, 0, 0); \
;     __builtin_amdgcn_global_load_lds((const unsigned*)((const char*)(gbase) + (v1)), (LAS unsigned*)(lds + (bufoff) + ldsw + 8192), 16, 0, 0); } while (0)
; #define G_LDA(dst, b, h) do { _Pragma("unroll") for (int m = 0; m < 4; ++m) _Pragma("unroll") for (int k = 0; k < 2; ++k) dst[m][k] = *(const LAS h8*)(lds + G_SA(b, h) + aoff + m * 2048 + k * 1024); } while (0)
; #define G_LDB(dst, b, h) do { _Pragma("unroll") for (int n = 0; n < 2; ++n) _Pragma("unroll") for (int k = 0; k < 2; ++k) dst[n][k] = *(const LAS h8*)(lds + G_SB(b, h) + boff + n * 2048 + k * 1024); } while (0)
; #define G_MMA(ai, bj, At, Bt) do { __builtin_amdgcn_s_setprio(1); _Pragma("unroll") for (int m = 0; m < 4; ++m) _Pragma("unroll") for (int n = 0; n < 2; ++n) _Pragma("unroll") for (int k = 0; k < 2; ++k) \
;     acc[ai][bj][m][n] = __builtin_amdgcn_mfma_f32_16x16x32_f16(Bt[n][k], At[m][k], acc[ai][bj][m][n], 0, 0, 0); __builtin_amdgcn_s_setprio(0); } while (0)
; #define G_WAIT_L(n) asm volatile("s_waitcnt lgkmcnt(" #n ")" ::: "memory")
; #define G_BAR __builtin_amdgcn_s_barrier()
; #define G_SCHED __builtin_amdgcn_sched_barrier(0)
; template <bool PERM, class Sched, class Epi>
; DI void gemm256(LAS unsigned char* lds, const Sched& S, const Epi& E, int wv_) {
;     ...
;     for (int t = 0; t < nt; t += 2) {
;       const bool last = (t == nt - 2);
;       const char* a1 = cA + (size_t)(t + 1) * kstep;
;       const char* a2 = last ? nA : cA + (size_t)(t + 2) * kstep;
;       const char* b2 = last ? nB : cB + (size_t)(t + 2) * kstep;
;       const char* a3 = a2 + kstep;
;       const char* b3 = b2 + kstep;
;       G_LDB(B0, 0, 0); G_SCHED; G_LDA(At, 0, 0); G_STAGE(G_SA(1, 1), a1 + chA, cvA0, cvA1);
;       G_WAIT_L(8); G_BAR; G_WAIT_L(0); G_MMA(0, 0, At, B0); G_BAR; G_SCHED;
;       G_LDB(B1, 0, 1); G_STAGE(G_SB(0, 0), b2, cvB0, cvB1);
;       G_BAR; G_WAIT_L(0); G_MMA(0, 1, At, B1); G_BAR;
;       G_LDA(At, 0, 1); G_STAGE(G_SA(0, 0), a2, cvA0, cvA1);
;       G_BAR; G_WAIT_L(0); G_MMA(1, 0, At, B0); G_BAR; G_SCHED;
.LBB0_2281:
	v_or_b32_e32 v144, 0x10000, v146
	v_add_u32_e32 v145, 0x10400, v146
	ds_read_b128 v[148:151], v144
	ds_read_b128 v[152:155], v145
	v_add_u32_e32 v144, 0x10800, v146
	s_add_i32 s85, s14, 2
	v_add_u32_e32 v145, 0x10c00, v146
	ds_read_b128 v[156:159], v144
	ds_read_b128 v[160:163], v145
	s_add_u32 s15, s12, 0xfffc0080
	s_addc_u32 s16, s13, -1
	s_cmp_eq_u32 s75, s14
	s_cselect_b32 s14, s8, s46
	s_cselect_b32 s17, s7, s16
	s_cselect_b32 s16, s6, s15
	s_cselect_b32 s15, s9, s74
	v_lshl_add_u64 v[144:145], s[12:13], 0, v[140:141]
	s_add_i32 m0, s20, 0xc000
	ds_read_b128 v[164:167], v1
	ds_read_b128 v[168:171], v1 offset:1024
	ds_read_b128 v[172:175], v1 offset:2048
	ds_read_b128 v[176:179], v1 offset:3072
	ds_read_b128 v[180:183], v1 offset:4096
	ds_read_b128 v[184:187], v1 offset:5120
	ds_read_b128 v[188:191], v1 offset:6144
	ds_read_b128 v[192:195], v1 offset:7168
	global_load_lds_dwordx4 v[144:145], off
	v_lshl_add_u64 v[144:145], s[12:13], 0, v[142:143]
	s_add_i32 m0, s20, 0xe000
	s_nop 0
	global_load_lds_dwordx4 v[144:145], off
	s_waitcnt lgkmcnt(8)
	s_barrier
	s_waitcnt lgkmcnt(0)
	s_waitcnt lgkmcnt(0)
	v_mfma_f32_16x16x32_f16 v[114:117], v[148:151], v[164:167], v[114:117]
	v_mfma_f32_16x16x32_f16 v[126:129], v[156:159], v[164:167], v[126:129]
	v_mfma_f32_16x16x32_f16 v[98:101], v[148:151], v[172:175], v[98:101]
	v_mfma_f32_16x16x32_f16 v[110:113], v[156:159], v[172:175], v[110:113]
	v_mfma_f32_16x16x32_f16 v[82:85], v[148:151], v[180:183], v[82:85]
	v_mfma_f32_16x16x32_f16 v[94:97], v[156:159], v[180:183], v[94:97]
	v_mfma_f32_16x16x32_f16 v[66:69], v[148:151], v[188:191], v[66:69]
	v_mfma_f32_16x16x32_f16 v[78:81], v[156:159], v[188:191], v[78:81]
	v_mfma_f32_16x16x32_f16 v[114:117], v[152:155], v[168:171], v[114:117]
	v_mfma_f32_16x16x32_f16 v[126:129], v[160:163], v[168:171], v[126:129]
	v_mfma_f32_16x16x32_f16 v[98:101], v[152:155], v[176:179], v[98:101]
	v_mfma_f32_16x16x32_f16 v[110:113], v[160:163], v[176:179], v[110:113]
	v_mfma_f32_16x16x32_f16 v[82:85], v[152:155], v[184:187], v[82:85]
	v_mfma_f32_16x16x32_f16 v[94:97], v[160:163], v[184:187], v[94:97]
	v_mfma_f32_16x16x32_f16 v[66:69], v[152:155], v[192:195], v[66:69]
	v_mfma_f32_16x16x32_f16 v[78:81], v[160:163], v[192:195], v[78:81]
	s_barrier
	v_or_b32_e32 v144, 0x14000, v146
	v_add_u32_e32 v145, 0x14400, v146
	ds_read_b128 v[196:199], v144
	ds_read_b128 v[200:203], v145
	v_add_u32_e32 v144, 0x14800, v146
	v_add_u32_e32 v145, 0x14c00, v146
	s_mov_b32 m0, s11
	ds_read_b128 v[204:207], v144
	ds_read_b128 v[208:211], v145
	v_lshl_add_u64 v[144:145], s[14:15], 0, v[132:133]
	global_load_lds_dwordx4 v[144:145], off
	v_lshl_add_u64 v[212:213], s[14:15], 0, v[136:137]
	s_mov_b32 m0, s21
	s_nop 0
	global_load_lds_dwordx4 v[212:213], off
	s_barrier
	s_waitcnt lgkmcnt(0)
	s_waitcnt lgkmcnt(0)
	v_mfma_f32_16x16x32_f16 v[122:125], v[196:199], v[164:167], v[122:125]
	v_mfma_f32_16x16x32_f16 v[118:121], v[204:207], v[164:167], v[118:121]
	v_mfma_f32_16x16x32_f16 v[106:109], v[196:199], v[172:175], v[106:109]
	v_mfma_f32_16x16x32_f16 v[102:105], v[204:207], v[172:175], v[102:105]
	v_mfma_f32_16x16x32_f16 v[90:93], v[196:199], v[180:183], v[90:93]
	v_mfma_f32_16x16x32_f16 v[86:89], v[204:207], v[180:183], v[86:89]
	v_mfma_f32_16x16x32_f16 v[74:77], v[196:199], v[188:191], v[74:77]
	v_mfma_f32_16x16x32_f16 v[70:73], v[204:207], v[188:191], v[70:73]
	v_mfma_f32_16x16x32_f16 v[122:125], v[200:203], v[168:171], v[122:125]
	v_mfma_f32_16x16x32_f16 v[118:121], v[208:211], v[168:171], v[118:121]
	v_mfma_f32_16x16x32_f16 v[106:109], v[200:203], v[176:179], v[106:109]
	v_mfma_f32_16x16x32_f16 v[102:105], v[208:211], v[176:179], v[102:105]
	v_mfma_f32_16x16x32_f16 v[90:93], v[200:203], v[184:187], v[90:93]
	v_mfma_f32_16x16x32_f16 v[86:89], v[208:211], v[184:187], v[86:89]
	v_mfma_f32_16x16x32_f16 v[74:77], v[200:203], v[192:195], v[74:77]
	v_mfma_f32_16x16x32_f16 v[70:73], v[208:211], v[192:195], v[70:73]
	s_mov_b32 m0, s20
	v_lshl_add_u64 v[214:215], s[16:17], 0, v[130:131]
	s_barrier
	ds_read_b128 v[164:167], v1 offset:16384
	ds_read_b128 v[168:171], v1 offset:17408
	ds_read_b128 v[172:175], v1 offset:18432
	ds_read_b128 v[176:179], v1 offset:19456
	ds_read_b128 v[180:183], v1 offset:20480
	ds_read_b128 v[184:187], v1 offset:21504
	ds_read_b128 v[188:191], v1 offset:22528
	ds_read_b128 v[192:195], v1 offset:23552
	global_load_lds_dwordx4 v[214:215], off
	v_lshl_add_u64 v[216:217], s[16:17], 0, v[134:135]
	s_mov_b32 m0, s22
	s_nop 0
	global_load_lds_dwordx4 v[216:217], off
	s_barrier
	s_waitcnt lgkmcnt(0)
	s_waitcnt lgkmcnt(0)
	v_mfma_f32_16x16x32_f16 v[50:53], v[148:151], v[164:167], v[50:53]
	v_mfma_f32_16x16x32_f16 v[62:65], v[156:159], v[164:167], v[62:65]
	v_mfma_f32_16x16x32_f16 v[34:37], v[148:151], v[172:175], v[34:37]
	v_mfma_f32_16x16x32_f16 v[46:49], v[156:159], v[172:175], v[46:49]
	v_mfma_f32_16x16x32_f16 v[18:21], v[148:151], v[180:183], v[18:21]
	v_mfma_f32_16x16x32_f16 v[30:33], v[156:159], v[180:183], v[30:33]
	v_mfma_f32_16x16x32_f16 v[2:5], v[148:151], v[188:191], v[2:5]
	v_mfma_f32_16x16x32_f16 v[14:17], v[156:159], v[188:191], v[14:17]
	v_mfma_f32_16x16x32_f16 v[50:53], v[152:155], v[168:171], v[50:53]
	v_mfma_f32_16x16x32_f16 v[62:65], v[160:163], v[168:171], v[62:65]
	v_mfma_f32_16x16x32_f16 v[34:37], v[152:155], v[176:179], v[34:37]
	v_mfma_f32_16x16x32_f16 v[46:49], v[160:163], v[176:179], v[46:49]
	v_mfma_f32_16x16x32_f16 v[18:21], v[152:155], v[184:187], v[18:21]
	v_mfma_f32_16x16x32_f16 v[30:33], v[160:163], v[184:187], v[30:33]
	v_mfma_f32_16x16x32_f16 v[2:5], v[152:155], v[192:195], v[2:5]
	v_mfma_f32_16x16x32_f16 v[14:17], v[160:163], v[192:195], v[14:17]
	s_barrier
; #define G_STAGE(bufoff, gbase, v0, v1) do { \
;     __builtin_amdgcn_global_load_lds((const unsigned*)((const char*)(gbase) + (v0)), (LAS unsigned*)(lds + (bufoff) + ldsw), 16, 0, 0); \
;     __builtin_amdgcn_global_load_lds((const unsigned*)((const char*)(gbase) + (v1)), (LAS unsigned*)(lds + (bufoff) + ldsw + 8192), 16, 0, 0); } while (0)
; #define G_LDA(dst, b, h) do { _Pragma("unroll") for (int m = 0; m < 4; ++m) _Pragma("unroll") for (int k = 0; k < 2; ++k) dst[m][k] = *(const LAS h8*)(lds + G_SA(b, h) + aoff + m * 2048 + k * 1024); } while (0)
; #define G_LDB(dst, b, h) do { _Pragma("unroll") for (int n = 0; n < 2; ++n) _Pragma("unroll") for (int k = 0; k < 2; ++k) dst[n][k] = *(const LAS h8*)(lds + G_SB(b, h) + boff + n * 2048 + k * 1024); } while (0)
; #define G_MMA(ai, bj, At, Bt) do { __builtin_amdgcn_s_setprio(1); _Pragma("unroll") for (int m = 0; m < 4; ++m) _Pragma("unroll") for (int n = 0; n < 2; ++n) _Pragma("unroll") for (int k = 0; k < 2; ++k) \
;     acc[ai][bj][m][n] = __builtin_amdgcn_mfma_f32_16x16x32_f16(Bt[n][k], At[m][k], acc[ai][bj][m][n], 0, 0, 0); __builtin_amdgcn_s_setprio(0); } while (0)
; #define G_WAIT_V(n) asm volatile("s_waitcnt vmcnt(" #n ")" ::: "memory")
; #define G_WAIT_L(n) asm volatile("s_waitcnt lgkmcnt(" #n ")" ::: "memory")
; #define G_BAR __builtin_amdgcn_s_barrier()
; #define G_SCHED __builtin_amdgcn_sched_barrier(0)
; template <bool PERM, class Sched, class Epi>
; DI void gemm256(LAS unsigned char* lds, const Sched& S, const Epi& E, int wv_) {
;     ...
;       G_STAGE(G_SB(0, 1), b2 + chB, cvB0, cvB1);
;       G_WAIT_V(6); G_BAR; G_MMA(1, 1, At, B1); G_BAR;
;       G_LDB(B0, 1, 0); G_SCHED; G_LDA(At, 1, 0); G_STAGE(G_SA(0, 1), a2 + chA, cvA0, cvA1);
;       G_WAIT_L(8); G_BAR; G_WAIT_L(0); G_MMA(0, 0, At, B0); G_BAR; G_SCHED;
;       G_LDB(B1, 1, 1); G_STAGE(G_SB(1, 0), b3, cvB0, cvB1);
	s_add_u32 s40, s14, 0x400000
	s_addc_u32 s41, s15, 0
	s_mov_b32 m0, s23
	v_lshl_add_u64 v[148:149], s[40:41], 0, v[132:133]
	global_load_lds_dwordx4 v[148:149], off
	v_lshl_add_u64 v[148:149], s[40:41], 0, v[136:137]
	s_mov_b32 m0, s24
	s_nop 0
	global_load_lds_dwordx4 v[148:149], off
	s_waitcnt vmcnt(6)
	s_barrier
	v_mfma_f32_16x16x32_f16 v[58:61], v[196:199], v[164:167], v[58:61]
	v_mfma_f32_16x16x32_f16 v[54:57], v[204:207], v[164:167], v[54:57]
	v_mfma_f32_16x16x32_f16 v[42:45], v[196:199], v[172:175], v[42:45]
	v_mfma_f32_16x16x32_f16 v[38:41], v[204:207], v[172:175], v[38:41]
	v_mfma_f32_16x16x32_f16 v[26:29], v[196:199], v[180:183], v[26:29]
	v_mfma_f32_16x16x32_f16 v[22:25], v[204:207], v[180:183], v[22:25]
	v_mfma_f32_16x16x32_f16 v[10:13], v[196:199], v[188:191], v[10:13]
	v_mfma_f32_16x16x32_f16 v[6:9], v[204:207], v[188:191], v[6:9]
	v_mfma_f32_16x16x32_f16 v[58:61], v[200:203], v[168:171], v[58:61]
	v_mfma_f32_16x16x32_f16 v[54:57], v[208:211], v[168:171], v[54:57]
	v_mfma_f32_16x16x32_f16 v[42:45], v[200:203], v[176:179], v[42:45]
	v_mfma_f32_16x16x32_f16 v[38:41], v[208:211], v[176:179], v[38:41]
	v_mfma_f32_16x16x32_f16 v[26:29], v[200:203], v[184:187], v[26:29]
	v_mfma_f32_16x16x32_f16 v[22:25], v[208:211], v[184:187], v[22:25]
	v_mfma_f32_16x16x32_f16 v[10:13], v[200:203], v[192:195], v[10:13]
	v_mfma_f32_16x16x32_f16 v[6:9], v[208:211], v[192:195], v[6:9]
	v_or_b32_e32 v147, 0x18000, v146
	v_add_u32_e32 v152, 0x18400, v146
	s_barrier
	ds_read_b128 v[148:151], v147
	ds_read_b128 v[152:155], v152
	v_add_u32_e32 v147, 0x18800, v146
	v_add_u32_e32 v160, 0x18c00, v146
	ds_read_b128 v[156:159], v147
	ds_read_b128 v[160:163], v160
	s_add_u32 s16, s16, 0x40000
	s_addc_u32 s17, s17, 0
	s_mov_b32 m0, s25
	v_lshl_add_u64 v[196:197], s[16:17], 0, v[130:131]
	ds_read_b128 v[164:167], v1 offset:32768
	ds_read_b128 v[168:171], v1 offset:33792
	ds_read_b128 v[172:175], v1 offset:34816
	ds_read_b128 v[176:179], v1 offset:35840
	ds_read_b128 v[180:183], v1 offset:36864
	ds_read_b128 v[184:187], v1 offset:37888
	ds_read_b128 v[188:191], v1 offset:38912
	ds_read_b128 v[192:195], v1 offset:39936
	global_load_lds_dwordx4 v[196:197], off
	v_lshl_add_u64 v[196:197], s[16:17], 0, v[134:135]
	s_mov_b32 m0, s26
	s_nop 0
	global_load_lds_dwordx4 v[196:197], off
	s_waitcnt lgkmcnt(8)
	s_barrier
	s_waitcnt lgkmcnt(0)
	s_waitcnt lgkmcnt(0)
	v_mfma_f32_16x16x32_f16 v[114:117], v[148:151], v[164:167], v[114:117]
	v_mfma_f32_16x16x32_f16 v[126:129], v[156:159], v[164:167], v[126:129]
	v_mfma_f32_16x16x32_f16 v[98:101], v[148:151], v[172:175], v[98:101]
	v_mfma_f32_16x16x32_f16 v[110:113], v[156:159], v[172:175], v[110:113]
	v_mfma_f32_16x16x32_f16 v[82:85], v[148:151], v[180:183], v[82:85]
	v_mfma_f32_16x16x32_f16 v[94:97], v[156:159], v[180:183], v[94:97]
	v_mfma_f32_16x16x32_f16 v[66:69], v[148:151], v[188:191], v[66:69]
	v_mfma_f32_16x16x32_f16 v[78:81], v[156:159], v[188:191], v[78:81]
	v_mfma_f32_16x16x32_f16 v[114:117], v[152:155], v[168:171], v[114:117]
	v_mfma_f32_16x16x32_f16 v[126:129], v[160:163], v[168:171], v[126:129]
	v_mfma_f32_16x16x32_f16 v[98:101], v[152:155], v[176:179], v[98:101]
	v_mfma_f32_16x16x32_f16 v[110:113], v[160:163], v[176:179], v[110:113]
	v_mfma_f32_16x16x32_f16 v[82:85], v[152:155], v[184:187], v[82:85]
	v_mfma_f32_16x16x32_f16 v[94:97], v[160:163], v[184:187], v[94:97]
	v_mfma_f32_16x16x32_f16 v[66:69], v[152:155], v[192:195], v[66:69]
	v_mfma_f32_16x16x32_f16 v[78:81], v[160:163], v[192:195], v[78:81]
	s_barrier
	v_or_b32_e32 v147, 0x1c000, v146
	v_add_u32_e32 v200, 0x1c400, v146
	s_mov_b32 m0, s28
	ds_read_b128 v[196:199], v147
	ds_read_b128 v[200:203], v200
	v_add_u32_e32 v147, 0x1c800, v146
	v_add_u32_e32 v208, 0x1cc00, v146
	v_lshl_add_u64 v[144:145], v[144:145], 0, s[86:87]
	ds_read_b128 v[204:207], v147
	ds_read_b128 v[208:211], v208
	global_load_lds_dwordx4 v[144:145], off
	v_lshl_add_u64 v[144:145], v[212:213], 0, s[86:87]
	s_mov_b32 m0, s29
	s_nop 0
	global_load_lds_dwordx4 v[144:145], off
	s_barrier
; #define G_STAGE(bufoff, gbase, v0, v1) do { \
;     __builtin_amdgcn_global_load_lds((const unsigned*)((const char*)(gbase) + (v0)), (LAS unsigned*)(lds + (bufoff) + ldsw), 16, 0, 0); \
;     __builtin_amdgcn_global_load_lds((const unsigned*)((const char*)(gbase) + (v1)), (LAS unsigned*)(lds + (bufoff) + ldsw + 8192), 16, 0, 0); } while (0)
; #define G_LDA(dst, b, h) do { _Pragma("unroll") for (int m = 0; m < 4; ++m) _Pragma("unroll") for (int k = 0; k < 2; ++k) dst[m][k] = *(const LAS h8*)(lds + G_SA(b, h) + aoff + m * 2048 + k * 1024); } while (0)
; #define G_LDB(dst, b, h) do { _Pragma("unroll") for (int n = 0; n < 2; ++n) _Pragma("unroll") for (int k = 0; k < 2; ++k) dst[n][k] = *(const LAS h8*)(lds + G_SB(b, h) + boff + n * 2048 + k * 1024); } while (0)
; #define G_MMA(ai, bj, At, Bt) do { __builtin_amdgcn_s_setprio(1); _Pragma("unroll") for (int m = 0; m < 4; ++m) _Pragma("unroll") for (int n = 0; n < 2; ++n) _Pragma("unroll") for (int k = 0; k < 2; ++k) \
;     acc[ai][bj][m][n] = __builtin_amdgcn_mfma_f32_16x16x32_f16(Bt[n][k], At[m][k], acc[ai][bj][m][n], 0, 0, 0); __builtin_amdgcn_s_setprio(0); } while (0)
; #define G_WAIT_V(n) asm volatile("s_waitcnt vmcnt(" #n ")" ::: "memory")
; #define G_WAIT_L(n) asm volatile("s_waitcnt lgkmcnt(" #n ")" ::: "memory")
; #define G_BAR __builtin_amdgcn_s_barrier()
; #define G_SCHED __builtin_amdgcn_sched_barrier(0)
; template <bool PERM, class Sched, class Epi>
; DI void gemm256(LAS unsigned char* lds, const Sched& S, const Epi& E, int wv_) {
;     ...
;       G_LDB(B1, 1, 1); G_STAGE(G_SB(1, 0), b3, cvB0, cvB1);
;       G_BAR; G_WAIT_L(0); G_MMA(0, 1, At, B1); G_BAR;
;       G_LDA(At, 1, 1); G_STAGE(G_SA(1, 0), a3, cvA0, cvA1);
;       G_BAR; G_WAIT_L(0); G_MMA(1, 0, At, B0); G_BAR; G_SCHED;
;       G_STAGE(G_SB(1, 1), b3 + chB, cvB0, cvB1);
;       G_WAIT_V(6); G_BAR; G_MMA(1, 1, At, B1); G_BAR;
;     }
	s_waitcnt lgkmcnt(0)
	s_waitcnt lgkmcnt(0)
	v_mfma_f32_16x16x32_f16 v[122:125], v[196:199], v[164:167], v[122:125]
	v_mfma_f32_16x16x32_f16 v[118:121], v[204:207], v[164:167], v[118:121]
	v_mfma_f32_16x16x32_f16 v[106:109], v[196:199], v[172:175], v[106:109]
	v_mfma_f32_16x16x32_f16 v[102:105], v[204:207], v[172:175], v[102:105]
	v_mfma_f32_16x16x32_f16 v[90:93], v[196:199], v[180:183], v[90:93]
	v_mfma_f32_16x16x32_f16 v[86:89], v[204:207], v[180:183], v[86:89]
	v_mfma_f32_16x16x32_f16 v[74:77], v[196:199], v[188:191], v[74:77]
	v_mfma_f32_16x16x32_f16 v[70:73], v[204:207], v[188:191], v[70:73]
	v_mfma_f32_16x16x32_f16 v[122:125], v[200:203], v[168:171], v[122:125]
	v_mfma_f32_16x16x32_f16 v[118:121], v[208:211], v[168:171], v[118:121]
	v_mfma_f32_16x16x32_f16 v[106:109], v[200:203], v[176:179], v[106:109]
	v_mfma_f32_16x16x32_f16 v[102:105], v[208:211], v[176:179], v[102:105]
	v_mfma_f32_16x16x32_f16 v[90:93], v[200:203], v[184:187], v[90:93]
	v_mfma_f32_16x16x32_f16 v[86:89], v[208:211], v[184:187], v[86:89]
	v_mfma_f32_16x16x32_f16 v[74:77], v[200:203], v[192:195], v[74:77]
	v_mfma_f32_16x16x32_f16 v[70:73], v[208:211], v[192:195], v[70:73]
	s_mov_b32 m0, s30
	v_lshl_add_u64 v[144:145], v[214:215], 0, s[86:87]
	s_barrier
	ds_read_b128 v[164:167], v1 offset:49152
	ds_read_b128 v[168:171], v1 offset:50176
	ds_read_b128 v[172:175], v1 offset:51200
	ds_read_b128 v[176:179], v1 offset:52224
	ds_read_b128 v[180:183], v1 offset:53248
	ds_read_b128 v[184:187], v1 offset:54272
	ds_read_b128 v[188:191], v1 offset:55296
	ds_read_b128 v[192:195], v1 offset:56320
	global_load_lds_dwordx4 v[144:145], off
	v_lshl_add_u64 v[144:145], v[216:217], 0, s[86:87]
	s_mov_b32 m0, s31
	s_nop 0
	global_load_lds_dwordx4 v[144:145], off
	s_barrier
	s_waitcnt lgkmcnt(0)
	s_waitcnt lgkmcnt(0)
	v_mfma_f32_16x16x32_f16 v[50:53], v[148:151], v[164:167], v[50:53]
	v_mfma_f32_16x16x32_f16 v[62:65], v[156:159], v[164:167], v[62:65]
	v_mfma_f32_16x16x32_f16 v[34:37], v[148:151], v[172:175], v[34:37]
	v_mfma_f32_16x16x32_f16 v[46:49], v[156:159], v[172:175], v[46:49]
	v_mfma_f32_16x16x32_f16 v[18:21], v[148:151], v[180:183], v[18:21]
	v_mfma_f32_16x16x32_f16 v[30:33], v[156:159], v[180:183], v[30:33]
	v_mfma_f32_16x16x32_f16 v[2:5], v[148:151], v[188:191], v[2:5]
	v_mfma_f32_16x16x32_f16 v[14:17], v[156:159], v[188:191], v[14:17]
	v_mfma_f32_16x16x32_f16 v[50:53], v[152:155], v[168:171], v[50:53]
	v_mfma_f32_16x16x32_f16 v[62:65], v[160:163], v[168:171], v[62:65]
	v_mfma_f32_16x16x32_f16 v[34:37], v[152:155], v[176:179], v[34:37]
	v_mfma_f32_16x16x32_f16 v[46:49], v[160:163], v[176:179], v[46:49]
	v_mfma_f32_16x16x32_f16 v[18:21], v[152:155], v[184:187], v[18:21]
	v_mfma_f32_16x16x32_f16 v[30:33], v[160:163], v[184:187], v[30:33]
	v_mfma_f32_16x16x32_f16 v[2:5], v[152:155], v[192:195], v[2:5]
	v_mfma_f32_16x16x32_f16 v[14:17], v[160:163], v[192:195], v[14:17]
	s_barrier
	s_add_u32 s14, s14, 0x400080
	s_addc_u32 s15, s15, 0
	s_mov_b32 m0, s34
	v_lshl_add_u64 v[144:145], s[14:15], 0, v[132:133]
	global_load_lds_dwordx4 v[144:145], off
	v_lshl_add_u64 v[144:145], s[14:15], 0, v[136:137]
	s_mov_b32 m0, s35
	s_nop 0
	global_load_lds_dwordx4 v[144:145], off
	s_waitcnt vmcnt(6)
	s_barrier
	v_mfma_f32_16x16x32_f16 v[58:61], v[196:199], v[164:167], v[58:61]
	v_mfma_f32_16x16x32_f16 v[54:57], v[204:207], v[164:167], v[54:57]
	v_mfma_f32_16x16x32_f16 v[42:45], v[196:199], v[172:175], v[42:45]
	v_mfma_f32_16x16x32_f16 v[38:41], v[204:207], v[172:175], v[38:41]
	v_mfma_f32_16x16x32_f16 v[26:29], v[196:199], v[180:183], v[26:29]
	v_mfma_f32_16x16x32_f16 v[22:25], v[204:207], v[180:183], v[22:25]
	v_mfma_f32_16x16x32_f16 v[10:13], v[196:199], v[188:191], v[10:13]
	v_mfma_f32_16x16x32_f16 v[6:9], v[204:207], v[188:191], v[6:9]
	v_mfma_f32_16x16x32_f16 v[58:61], v[200:203], v[168:171], v[58:61]
	v_mfma_f32_16x16x32_f16 v[54:57], v[208:211], v[168:171], v[54:57]
	v_mfma_f32_16x16x32_f16 v[42:45], v[200:203], v[176:179], v[42:45]
	v_mfma_f32_16x16x32_f16 v[38:41], v[208:211], v[176:179], v[38:41]
	v_mfma_f32_16x16x32_f16 v[26:29], v[200:203], v[184:187], v[26:29]
	v_mfma_f32_16x16x32_f16 v[22:25], v[208:211], v[184:187], v[22:25]
	v_mfma_f32_16x16x32_f16 v[10:13], v[200:203], v[192:195], v[10:13]
	v_mfma_f32_16x16x32_f16 v[6:9], v[208:211], v[192:195], v[6:9]
	s_add_u32 s12, s12, 0x100
	s_addc_u32 s13, s13, 0
	s_add_u32 s46, s46, 0x100
	s_addc_u32 s74, s74, 0
	s_cmp_ge_i32 s85, s5
	s_mov_b32 s14, s85
	s_barrier
	s_cbranch_scc0 .LBB0_2281
	s_branch .LBB0_2268

; #define G_STAGE(bufoff, gbase, v0, v1) do { \
;     __builtin_amdgcn_global_load_lds((const unsigned*)((const char*)(gbase) + (v0)), (LAS unsigned*)(lds + (bufoff) + ldsw), 16, 0, 0); \
;     __builtin_amdgcn_global_load_lds((const unsigned*)((const char*)(gbase) + (v1)), (LAS unsigned*)(lds + (bufoff) + ldsw + 8192), 16, 0, 0); } while (0)
; #define G_LDA(dst, b, h) do { _Pragma("unroll") for (int m = 0; m < 4; ++m) _Pragma("unroll") for (int k = 0; k < 2; ++k) dst[m][k] = *(const LAS h8*)(lds + G_SA(b, h) + aoff + m * 2048 + k * 1024); } while (0)
; #define G_LDB(dst, b, h) do { _Pragma("unroll") for (int n = 0; n < 2; ++n) _Pragma("unroll") for (int k = 0; k < 2; ++k) dst[n][k] = *(const LAS h8*)(lds + G_SB(b, h) + boff + n * 2048 + k * 1024); } while (0)
; #define G_MMA(ai, bj, At, Bt) do { __builtin_amdgcn_s_setprio(1); _Pragma("unroll") for (int m = 0; m < 4; ++m) _Pragma("unroll") for (int n = 0; n < 2; ++n) _Pragma("unroll") for (int k = 0; k < 2; ++k) \
;     acc[ai][bj][m][n] = __builtin_amdgcn_mfma_f32_16x16x32_f16(Bt[n][k], At[m][k], acc[ai][bj][m][n], 0, 0, 0); __builtin_amdgcn_s_setprio(0); } while (0)
; #define G_WAIT_L(n) asm volatile("s_waitcnt lgkmcnt(" #n ")" ::: "memory")
; #define G_BAR __builtin_amdgcn_s_barrier()
; #define G_SCHED __builtin_amdgcn_sched_barrier(0)
; template <bool PERM, class Sched, class Epi>
; DI void gemm256(LAS unsigned char* lds, const Sched& S, const Epi& E, int wv_) {
;     ...
;     for (int t = 0; t < nt; t += 2) {
;       const bool last = (t == nt - 2);
;       const char* a1 = cA + (size_t)(t + 1) * kstep;
;       const char* a2 = last ? nA : cA + (size_t)(t + 2) * kstep;
;       const char* b2 = last ? nB : cB + (size_t)(t + 2) * kstep;
;       const char* a3 = a2 + kstep;
;       const char* b3 = b2 + kstep;
;       G_LDB(B0, 0, 0); G_SCHED; G_LDA(At, 0, 0); G_STAGE(G_SA(1, 1), a1 + chA, cvA0, cvA1);
;       G_WAIT_L(8); G_BAR; G_WAIT_L(0); G_MMA(0, 0, At, B0); G_BAR; G_SCHED;
;       G_LDB(B1, 0, 1); G_STAGE(G_SB(0, 0), b2, cvB0, cvB1);
;       G_BAR; G_WAIT_L(0); G_MMA(0, 1, At, B1); G_BAR;
;       G_LDA(At, 0, 1); G_STAGE(G_SA(0, 0), a2, cvA0, cvA1);
;       G_BAR; G_WAIT_L(0); G_MMA(1, 0, At, B0); G_BAR; G_SCHED;
.LBB0_2355:
	v_or_b32_e32 v1, 0x10000, v185
	v_add_u32_e32 v2, 0x10400, v185
	ds_read_b128 v[132:135], v1
	ds_read_b128 v[136:139], v2
	v_add_u32_e32 v1, 0x10800, v185
	s_add_i32 s85, s10, 2
	v_add_u32_e32 v2, 0x10c00, v185
	ds_read_b128 v[140:143], v1
	ds_read_b128 v[144:147], v2
	s_add_u32 s11, s8, 0xfffc0080
	s_addc_u32 s12, s9, -1
	s_cmp_eq_u32 s69, s10
	s_cselect_b32 s10, s4, s74
	s_cselect_b32 s13, s3, s12
	s_cselect_b32 s12, s2, s11
	s_cselect_b32 s11, s5, s75
	v_lshl_add_u64 v[2:3], s[8:9], 0, v[196:197]
	s_add_i32 m0, s16, 0xc000
	ds_read_b128 v[148:151], v184
	ds_read_b128 v[152:155], v184 offset:1024
	ds_read_b128 v[156:159], v184 offset:2048
	ds_read_b128 v[160:163], v184 offset:3072
	ds_read_b128 v[164:167], v184 offset:4096
	ds_read_b128 v[168:171], v184 offset:5120
	ds_read_b128 v[172:175], v184 offset:6144
	ds_read_b128 v[176:179], v184 offset:7168
	global_load_lds_dwordx4 v[2:3], off
	v_lshl_add_u64 v[2:3], s[8:9], 0, v[198:199]
	s_add_i32 m0, s16, 0xe000
	s_nop 0
	global_load_lds_dwordx4 v[2:3], off
	s_waitcnt lgkmcnt(8)
	s_barrier
	s_waitcnt lgkmcnt(0)
	s_waitcnt lgkmcnt(0)
	v_mfma_f32_16x16x32_f16 v[128:131], v[132:135], v[148:151], v[128:131]
	v_mfma_f32_16x16x32_f16 v[124:127], v[140:143], v[148:151], v[124:127]
	v_mfma_f32_16x16x32_f16 v[120:123], v[132:135], v[156:159], v[120:123]
	v_mfma_f32_16x16x32_f16 v[116:119], v[140:143], v[156:159], v[116:119]
	v_mfma_f32_16x16x32_f16 v[112:115], v[132:135], v[164:167], v[112:115]
	v_mfma_f32_16x16x32_f16 v[108:111], v[140:143], v[164:167], v[108:111]
	v_mfma_f32_16x16x32_f16 v[104:107], v[132:135], v[172:175], v[104:107]
	v_mfma_f32_16x16x32_f16 v[100:103], v[140:143], v[172:175], v[100:103]
	v_mfma_f32_16x16x32_f16 v[128:131], v[136:139], v[152:155], v[128:131]
	v_mfma_f32_16x16x32_f16 v[124:127], v[144:147], v[152:155], v[124:127]
	v_mfma_f32_16x16x32_f16 v[120:123], v[136:139], v[160:163], v[120:123]
	v_mfma_f32_16x16x32_f16 v[116:119], v[144:147], v[160:163], v[116:119]
	v_mfma_f32_16x16x32_f16 v[112:115], v[136:139], v[168:171], v[112:115]
	v_mfma_f32_16x16x32_f16 v[108:111], v[144:147], v[168:171], v[108:111]
	v_mfma_f32_16x16x32_f16 v[104:107], v[136:139], v[176:179], v[104:107]
	v_mfma_f32_16x16x32_f16 v[100:103], v[144:147], v[176:179], v[100:103]
	s_barrier
	v_or_b32_e32 v1, 0x14000, v185
	s_mov_b32 m0, s17
	v_add_u32_e32 v2, 0x14400, v185
	ds_read_b128 v[180:183], v1
	ds_read_b128 v[202:205], v2
	v_add_u32_e32 v1, 0x14800, v185
	v_lshl_add_u64 v[214:215], s[10:11], 0, v[188:189]
	v_add_u32_e32 v2, 0x14c00, v185
	ds_read_b128 v[206:209], v1
	ds_read_b128 v[210:213], v2
	global_load_lds_dwordx4 v[214:215], off
	v_lshl_add_u64 v[216:217], s[10:11], 0, v[192:193]
	s_mov_b32 m0, s18
	s_nop 0
	global_load_lds_dwordx4 v[216:217], off
	s_barrier
	s_waitcnt lgkmcnt(0)
	s_waitcnt lgkmcnt(0)
	v_mfma_f32_16x16x32_f16 v[96:99], v[180:183], v[148:151], v[96:99]
	v_mfma_f32_16x16x32_f16 v[92:95], v[206:209], v[148:151], v[92:95]
	v_mfma_f32_16x16x32_f16 v[88:91], v[180:183], v[156:159], v[88:91]
	v_mfma_f32_16x16x32_f16 v[84:87], v[206:209], v[156:159], v[84:87]
	v_mfma_f32_16x16x32_f16 v[80:83], v[180:183], v[164:167], v[80:83]
	v_mfma_f32_16x16x32_f16 v[76:79], v[206:209], v[164:167], v[76:79]
	v_mfma_f32_16x16x32_f16 v[72:75], v[180:183], v[172:175], v[72:75]
	v_mfma_f32_16x16x32_f16 v[68:71], v[206:209], v[172:175], v[68:71]
	v_mfma_f32_16x16x32_f16 v[96:99], v[202:205], v[152:155], v[96:99]
	v_mfma_f32_16x16x32_f16 v[92:95], v[210:213], v[152:155], v[92:95]
	v_mfma_f32_16x16x32_f16 v[88:91], v[202:205], v[160:163], v[88:91]
	v_mfma_f32_16x16x32_f16 v[84:87], v[210:213], v[160:163], v[84:87]
	v_mfma_f32_16x16x32_f16 v[80:83], v[202:205], v[168:171], v[80:83]
	v_mfma_f32_16x16x32_f16 v[76:79], v[210:213], v[168:171], v[76:79]
	v_mfma_f32_16x16x32_f16 v[72:75], v[202:205], v[176:179], v[72:75]
	v_mfma_f32_16x16x32_f16 v[68:71], v[210:213], v[176:179], v[68:71]
	s_mov_b32 m0, s16
	v_lshl_add_u64 v[218:219], s[12:13], 0, v[186:187]
	s_barrier
	ds_read_b128 v[148:151], v184 offset:16384
	ds_read_b128 v[152:155], v184 offset:17408
	ds_read_b128 v[156:159], v184 offset:18432
	ds_read_b128 v[160:163], v184 offset:19456
	ds_read_b128 v[164:167], v184 offset:20480
	ds_read_b128 v[168:171], v184 offset:21504
	ds_read_b128 v[172:175], v184 offset:22528
	ds_read_b128 v[176:179], v184 offset:23552
	global_load_lds_dwordx4 v[218:219], off
	v_lshl_add_u64 v[220:221], s[12:13], 0, v[190:191]
	s_mov_b32 m0, s19
	s_nop 0
	global_load_lds_dwordx4 v[220:221], off
	s_barrier
	s_waitcnt lgkmcnt(0)
	s_waitcnt lgkmcnt(0)
	v_mfma_f32_16x16x32_f16 v[64:67], v[132:135], v[148:151], v[64:67]
	v_mfma_f32_16x16x32_f16 v[60:63], v[140:143], v[148:151], v[60:63]
	v_mfma_f32_16x16x32_f16 v[56:59], v[132:135], v[156:159], v[56:59]
	v_mfma_f32_16x16x32_f16 v[52:55], v[140:143], v[156:159], v[52:55]
	v_mfma_f32_16x16x32_f16 v[48:51], v[132:135], v[164:167], v[48:51]
	v_mfma_f32_16x16x32_f16 v[44:47], v[140:143], v[164:167], v[44:47]
	v_mfma_f32_16x16x32_f16 v[40:43], v[132:135], v[172:175], v[40:43]
	v_mfma_f32_16x16x32_f16 v[36:39], v[140:143], v[172:175], v[36:39]
	v_mfma_f32_16x16x32_f16 v[64:67], v[136:139], v[152:155], v[64:67]
	v_mfma_f32_16x16x32_f16 v[60:63], v[144:147], v[152:155], v[60:63]
	v_mfma_f32_16x16x32_f16 v[56:59], v[136:139], v[160:163], v[56:59]
	v_mfma_f32_16x16x32_f16 v[52:55], v[144:147], v[160:163], v[52:55]
	v_mfma_f32_16x16x32_f16 v[48:51], v[136:139], v[168:171], v[48:51]
	v_mfma_f32_16x16x32_f16 v[44:47], v[144:147], v[168:171], v[44:47]
	v_mfma_f32_16x16x32_f16 v[40:43], v[136:139], v[176:179], v[40:43]
	v_mfma_f32_16x16x32_f16 v[36:39], v[144:147], v[176:179], v[36:39]
	s_barrier
; #define G_STAGE(bufoff, gbase, v0, v1) do { \
;     __builtin_amdgcn_global_load_lds((const unsigned*)((const char*)(gbase) + (v0)), (LAS unsigned*)(lds + (bufoff) + ldsw), 16, 0, 0); \
;     __builtin_amdgcn_global_load_lds((const unsigned*)((const char*)(gbase) + (v1)), (LAS unsigned*)(lds + (bufoff) + ldsw + 8192), 16, 0, 0); } while (0)
; #define G_LDA(dst, b, h) do { _Pragma("unroll") for (int m = 0; m < 4; ++m) _Pragma("unroll") for (int k = 0; k < 2; ++k) dst[m][k] = *(const LAS h8*)(lds + G_SA(b, h) + aoff + m * 2048 + k * 1024); } while (0)
; #define G_LDB(dst, b, h) do { _Pragma("unroll") for (int n = 0; n < 2; ++n) _Pragma("unroll") for (int k = 0; k < 2; ++k) dst[n][k] = *(const LAS h8*)(lds + G_SB(b, h) + boff + n * 2048 + k * 1024); } while (0)
; #define G_MMA(ai, bj, At, Bt) do { __builtin_amdgcn_s_setprio(1); _Pragma("unroll") for (int m = 0; m < 4; ++m) _Pragma("unroll") for (int n = 0; n < 2; ++n) _Pragma("unroll") for (int k = 0; k < 2; ++k) \
;     acc[ai][bj][m][n] = __builtin_amdgcn_mfma_f32_16x16x32_f16(Bt[n][k], At[m][k], acc[ai][bj][m][n], 0, 0, 0); __builtin_amdgcn_s_setprio(0); } while (0)
; #define G_WAIT_V(n) asm volatile("s_waitcnt vmcnt(" #n ")" ::: "memory")
; #define G_WAIT_L(n) asm volatile("s_waitcnt lgkmcnt(" #n ")" ::: "memory")
; #define G_BAR __builtin_amdgcn_s_barrier()
; #define G_SCHED __builtin_amdgcn_sched_barrier(0)
; template <bool PERM, class Sched, class Epi>
; DI void gemm256(LAS unsigned char* lds, const Sched& S, const Epi& E, int wv_) {
;     ...
;       G_STAGE(G_SB(0, 1), b2 + chB, cvB0, cvB1);
;       G_WAIT_V(6); G_BAR; G_MMA(1, 1, At, B1); G_BAR;
;       G_LDB(B0, 1, 0); G_SCHED; G_LDA(At, 1, 0); G_STAGE(G_SA(0, 1), a2 + chA, cvA0, cvA1);
;       G_WAIT_L(8); G_BAR; G_WAIT_L(0); G_MMA(0, 0, At, B0); G_BAR; G_SCHED;
;       G_LDB(B1, 1, 1); G_STAGE(G_SB(1, 0), b3, cvB0, cvB1);
	s_add_u32 s40, s10, 0x10000
	s_addc_u32 s41, s11, 0
	s_mov_b32 m0, s20
	v_lshl_add_u64 v[2:3], s[40:41], 0, v[188:189]
	global_load_lds_dwordx4 v[2:3], off
	v_lshl_add_u64 v[2:3], s[40:41], 0, v[192:193]
	s_mov_b32 m0, s21
	s_nop 0
	global_load_lds_dwordx4 v[2:3], off
	s_waitcnt vmcnt(6)
	s_barrier
	v_mfma_f32_16x16x32_f16 v[32:35], v[180:183], v[148:151], v[32:35]
	v_mfma_f32_16x16x32_f16 v[28:31], v[206:209], v[148:151], v[28:31]
	v_mfma_f32_16x16x32_f16 v[24:27], v[180:183], v[156:159], v[24:27]
	v_mfma_f32_16x16x32_f16 v[20:23], v[206:209], v[156:159], v[20:23]
	v_mfma_f32_16x16x32_f16 v[16:19], v[180:183], v[164:167], v[16:19]
	v_mfma_f32_16x16x32_f16 v[12:15], v[206:209], v[164:167], v[12:15]
	v_mfma_f32_16x16x32_f16 v[8:11], v[180:183], v[172:175], v[8:11]
	v_mfma_f32_16x16x32_f16 v[2:5], v[206:209], v[172:175], v[4:7]
	v_mfma_f32_16x16x32_f16 v[32:35], v[202:205], v[152:155], v[32:35]
	v_mfma_f32_16x16x32_f16 v[28:31], v[210:213], v[152:155], v[28:31]
	v_mfma_f32_16x16x32_f16 v[24:27], v[202:205], v[160:163], v[24:27]
	v_mfma_f32_16x16x32_f16 v[20:23], v[210:213], v[160:163], v[20:23]
	v_mfma_f32_16x16x32_f16 v[16:19], v[202:205], v[168:171], v[16:19]
	v_mfma_f32_16x16x32_f16 v[12:15], v[210:213], v[168:171], v[12:15]
	v_mfma_f32_16x16x32_f16 v[8:11], v[202:205], v[176:179], v[8:11]
	v_mfma_f32_16x16x32_f16 v[2:5], v[210:213], v[176:179], v[2:5]
	v_or_b32_e32 v1, 0x18000, v185
	s_barrier
	v_add_u32_e32 v6, 0x18400, v185
	ds_read_b128 v[132:135], v1
	ds_read_b128 v[136:139], v6
	v_add_u32_e32 v1, 0x18800, v185
	v_add_u32_e32 v6, 0x18c00, v185
	ds_read_b128 v[140:143], v1
	ds_read_b128 v[144:147], v6
	s_add_u32 s12, s12, 0x40000
	s_addc_u32 s13, s13, 0
	s_mov_b32 m0, s22
	v_lshl_add_u64 v[6:7], s[12:13], 0, v[186:187]
	ds_read_b128 v[148:151], v184 offset:32768
	ds_read_b128 v[152:155], v184 offset:33792
	ds_read_b128 v[156:159], v184 offset:34816
	ds_read_b128 v[160:163], v184 offset:35840
	ds_read_b128 v[164:167], v184 offset:36864
	ds_read_b128 v[168:171], v184 offset:37888
	ds_read_b128 v[172:175], v184 offset:38912
	ds_read_b128 v[176:179], v184 offset:39936
	global_load_lds_dwordx4 v[6:7], off
	v_lshl_add_u64 v[6:7], s[12:13], 0, v[190:191]
	s_mov_b32 m0, s23
	s_nop 0
	global_load_lds_dwordx4 v[6:7], off
	s_waitcnt lgkmcnt(8)
	s_barrier
	s_waitcnt lgkmcnt(0)
	s_waitcnt lgkmcnt(0)
	v_mfma_f32_16x16x32_f16 v[128:131], v[132:135], v[148:151], v[128:131]
	v_mfma_f32_16x16x32_f16 v[124:127], v[140:143], v[148:151], v[124:127]
	v_mfma_f32_16x16x32_f16 v[120:123], v[132:135], v[156:159], v[120:123]
	v_mfma_f32_16x16x32_f16 v[116:119], v[140:143], v[156:159], v[116:119]
	v_mfma_f32_16x16x32_f16 v[112:115], v[132:135], v[164:167], v[112:115]
	v_mfma_f32_16x16x32_f16 v[108:111], v[140:143], v[164:167], v[108:111]
	v_mfma_f32_16x16x32_f16 v[104:107], v[132:135], v[172:175], v[104:107]
	v_mfma_f32_16x16x32_f16 v[100:103], v[140:143], v[172:175], v[100:103]
	v_mfma_f32_16x16x32_f16 v[128:131], v[136:139], v[152:155], v[128:131]
	v_mfma_f32_16x16x32_f16 v[124:127], v[144:147], v[152:155], v[124:127]
	v_mfma_f32_16x16x32_f16 v[120:123], v[136:139], v[160:163], v[120:123]
	v_mfma_f32_16x16x32_f16 v[116:119], v[144:147], v[160:163], v[116:119]
	v_mfma_f32_16x16x32_f16 v[112:115], v[136:139], v[168:171], v[112:115]
	v_mfma_f32_16x16x32_f16 v[108:111], v[144:147], v[168:171], v[108:111]
	v_mfma_f32_16x16x32_f16 v[104:107], v[136:139], v[176:179], v[104:107]
	v_mfma_f32_16x16x32_f16 v[100:103], v[144:147], v[176:179], v[100:103]
	s_barrier
	v_or_b32_e32 v1, 0x1c000, v185
	v_add_u32_e32 v6, 0x1c400, v185
	ds_read_b128 v[180:183], v1
	ds_read_b128 v[202:205], v6
	v_add_u32_e32 v1, 0x1c800, v185
	v_add_u32_e32 v6, 0x1cc00, v185
	s_mov_b32 m0, s26
	ds_read_b128 v[206:209], v1
	ds_read_b128 v[210:213], v6
	v_lshl_add_u64 v[6:7], v[214:215], 0, s[86:87]
	global_load_lds_dwordx4 v[6:7], off
	v_lshl_add_u64 v[6:7], v[216:217], 0, s[86:87]
	s_mov_b32 m0, s27
	s_nop 0
	global_load_lds_dwordx4 v[6:7], off
	s_barrier
; #define G_STAGE(bufoff, gbase, v0, v1) do { \
;     __builtin_amdgcn_global_load_lds((const unsigned*)((const char*)(gbase) + (v0)), (LAS unsigned*)(lds + (bufoff) + ldsw), 16, 0, 0); \
;     __builtin_amdgcn_global_load_lds((const unsigned*)((const char*)(gbase) + (v1)), (LAS unsigned*)(lds + (bufoff) + ldsw + 8192), 16, 0, 0); } while (0)
; #define G_LDA(dst, b, h) do { _Pragma("unroll") for (int m = 0; m < 4; ++m) _Pragma("unroll") for (int k = 0; k < 2; ++k) dst[m][k] = *(const LAS h8*)(lds + G_SA(b, h) + aoff + m * 2048 + k * 1024); } while (0)
; #define G_LDB(dst, b, h) do { _Pragma("unroll") for (int n = 0; n < 2; ++n) _Pragma("unroll") for (int k = 0; k < 2; ++k) dst[n][k] = *(const LAS h8*)(lds + G_SB(b, h) + boff + n * 2048 + k * 1024); } while (0)
; #define G_MMA(ai, bj, At, Bt) do { __builtin_amdgcn_s_setprio(1); _Pragma("unroll") for (int m = 0; m < 4; ++m) _Pragma("unroll") for (int n = 0; n < 2; ++n) _Pragma("unroll") for (int k = 0; k < 2; ++k) \
;     acc[ai][bj][m][n] = __builtin_amdgcn_mfma_f32_16x16x32_f16(Bt[n][k], At[m][k], acc[ai][bj][m][n], 0, 0, 0); __builtin_amdgcn_s_setprio(0); } while (0)
; #define G_WAIT_V(n) asm volatile("s_waitcnt vmcnt(" #n ")" ::: "memory")
; #define G_WAIT_L(n) asm volatile("s_waitcnt lgkmcnt(" #n ")" ::: "memory")
; #define G_BAR __builtin_amdgcn_s_barrier()
; #define G_SCHED __builtin_amdgcn_sched_barrier(0)
; template <bool PERM, class Sched, class Epi>
; DI void gemm256(LAS unsigned char* lds, const Sched& S, const Epi& E, int wv_) {
;     ...
;       G_LDB(B1, 1, 1); G_STAGE(G_SB(1, 0), b3, cvB0, cvB1);
;       G_BAR; G_WAIT_L(0); G_MMA(0, 1, At, B1); G_BAR;
;       G_LDA(At, 1, 1); G_STAGE(G_SA(1, 0), a3, cvA0, cvA1);
;       G_BAR; G_WAIT_L(0); G_MMA(1, 0, At, B0); G_BAR; G_SCHED;
;       G_STAGE(G_SB(1, 1), b3 + chB, cvB0, cvB1);
;       G_WAIT_V(6); G_BAR; G_MMA(1, 1, At, B1); G_BAR;
;     }
	s_waitcnt lgkmcnt(0)
	s_waitcnt lgkmcnt(0)
	v_mfma_f32_16x16x32_f16 v[96:99], v[180:183], v[148:151], v[96:99]
	v_mfma_f32_16x16x32_f16 v[92:95], v[206:209], v[148:151], v[92:95]
	v_mfma_f32_16x16x32_f16 v[88:91], v[180:183], v[156:159], v[88:91]
	v_mfma_f32_16x16x32_f16 v[84:87], v[206:209], v[156:159], v[84:87]
	v_mfma_f32_16x16x32_f16 v[80:83], v[180:183], v[164:167], v[80:83]
	v_mfma_f32_16x16x32_f16 v[76:79], v[206:209], v[164:167], v[76:79]
	v_mfma_f32_16x16x32_f16 v[72:75], v[180:183], v[172:175], v[72:75]
	v_mfma_f32_16x16x32_f16 v[68:71], v[206:209], v[172:175], v[68:71]
	v_mfma_f32_16x16x32_f16 v[96:99], v[202:205], v[152:155], v[96:99]
	v_mfma_f32_16x16x32_f16 v[92:95], v[210:213], v[152:155], v[92:95]
	v_mfma_f32_16x16x32_f16 v[88:91], v[202:205], v[160:163], v[88:91]
	v_mfma_f32_16x16x32_f16 v[84:87], v[210:213], v[160:163], v[84:87]
	v_mfma_f32_16x16x32_f16 v[80:83], v[202:205], v[168:171], v[80:83]
	v_mfma_f32_16x16x32_f16 v[76:79], v[210:213], v[168:171], v[76:79]
	v_mfma_f32_16x16x32_f16 v[72:75], v[202:205], v[176:179], v[72:75]
	v_mfma_f32_16x16x32_f16 v[68:71], v[210:213], v[176:179], v[68:71]
	s_mov_b32 m0, s28
	v_lshl_add_u64 v[6:7], v[218:219], 0, s[86:87]
	s_barrier
	ds_read_b128 v[148:151], v184 offset:49152
	ds_read_b128 v[152:155], v184 offset:50176
	ds_read_b128 v[156:159], v184 offset:51200
	ds_read_b128 v[160:163], v184 offset:52224
	ds_read_b128 v[164:167], v184 offset:53248
	ds_read_b128 v[168:171], v184 offset:54272
	ds_read_b128 v[172:175], v184 offset:55296
	ds_read_b128 v[176:179], v184 offset:56320
	global_load_lds_dwordx4 v[6:7], off
	v_lshl_add_u64 v[6:7], v[220:221], 0, s[86:87]
	s_mov_b32 m0, s29
	s_nop 0
	global_load_lds_dwordx4 v[6:7], off
	s_barrier
	s_waitcnt lgkmcnt(0)
	s_waitcnt lgkmcnt(0)
	v_mfma_f32_16x16x32_f16 v[64:67], v[132:135], v[148:151], v[64:67]
	v_mfma_f32_16x16x32_f16 v[60:63], v[140:143], v[148:151], v[60:63]
	v_mfma_f32_16x16x32_f16 v[56:59], v[132:135], v[156:159], v[56:59]
	v_mfma_f32_16x16x32_f16 v[52:55], v[140:143], v[156:159], v[52:55]
	v_mfma_f32_16x16x32_f16 v[48:51], v[132:135], v[164:167], v[48:51]
	v_mfma_f32_16x16x32_f16 v[44:47], v[140:143], v[164:167], v[44:47]
	v_mfma_f32_16x16x32_f16 v[40:43], v[132:135], v[172:175], v[40:43]
	v_mfma_f32_16x16x32_f16 v[36:39], v[140:143], v[172:175], v[36:39]
	v_mfma_f32_16x16x32_f16 v[64:67], v[136:139], v[152:155], v[64:67]
	v_mfma_f32_16x16x32_f16 v[60:63], v[144:147], v[152:155], v[60:63]
	v_mfma_f32_16x16x32_f16 v[56:59], v[136:139], v[160:163], v[56:59]
	v_mfma_f32_16x16x32_f16 v[52:55], v[144:147], v[160:163], v[52:55]
	v_mfma_f32_16x16x32_f16 v[48:51], v[136:139], v[168:171], v[48:51]
	v_mfma_f32_16x16x32_f16 v[44:47], v[144:147], v[168:171], v[44:47]
	v_mfma_f32_16x16x32_f16 v[40:43], v[136:139], v[176:179], v[40:43]
	v_mfma_f32_16x16x32_f16 v[36:39], v[144:147], v[176:179], v[36:39]
	s_barrier
	s_add_u32 s10, s10, 0x10080
	s_addc_u32 s11, s11, 0
	s_mov_b32 m0, s30
	v_lshl_add_u64 v[6:7], s[10:11], 0, v[188:189]
	global_load_lds_dwordx4 v[6:7], off
	v_lshl_add_u64 v[6:7], s[10:11], 0, v[192:193]
	s_mov_b32 m0, s31
	s_nop 0
	global_load_lds_dwordx4 v[6:7], off
	s_waitcnt vmcnt(6)
	s_barrier
	v_mfma_f32_16x16x32_f16 v[32:35], v[180:183], v[148:151], v[32:35]
	v_mfma_f32_16x16x32_f16 v[28:31], v[206:209], v[148:151], v[28:31]
	v_mfma_f32_16x16x32_f16 v[24:27], v[180:183], v[156:159], v[24:27]
	v_mfma_f32_16x16x32_f16 v[20:23], v[206:209], v[156:159], v[20:23]
	v_mfma_f32_16x16x32_f16 v[16:19], v[180:183], v[164:167], v[16:19]
	v_mfma_f32_16x16x32_f16 v[12:15], v[206:209], v[164:167], v[12:15]
	v_mfma_f32_16x16x32_f16 v[6:9], v[180:183], v[172:175], v[8:11]
	v_mfma_f32_16x16x32_f16 v[2:5], v[206:209], v[172:175], v[2:5]
	v_mfma_f32_16x16x32_f16 v[32:35], v[202:205], v[152:155], v[32:35]
	v_mfma_f32_16x16x32_f16 v[28:31], v[210:213], v[152:155], v[28:31]
	v_mfma_f32_16x16x32_f16 v[24:27], v[202:205], v[160:163], v[24:27]
	v_mfma_f32_16x16x32_f16 v[20:23], v[210:213], v[160:163], v[20:23]
	v_mfma_f32_16x16x32_f16 v[16:19], v[202:205], v[168:171], v[16:19]
	v_mfma_f32_16x16x32_f16 v[12:15], v[210:213], v[168:171], v[12:15]
	v_mfma_f32_16x16x32_f16 v[8:11], v[202:205], v[176:179], v[6:9]
	v_mfma_f32_16x16x32_f16 v[4:7], v[210:213], v[176:179], v[2:5]
	s_add_u32 s8, s8, 0x100
	s_addc_u32 s9, s9, 0
	s_add_u32 s74, s74, 0x100
	s_addc_u32 s75, s75, 0
	s_cmp_ge_i32 s85, s46
	s_mov_b32 s10, s85
	s_barrier
	s_cbranch_scc0 .LBB0_2355

; #define G_STAGE(bufoff, gbase, v0, v1) do { \
;     __builtin_amdgcn_global_load_lds((const unsigned*)((const char*)(gbase) + (v0)), (LAS unsigned*)(lds + (bufoff) + ldsw), 16, 0, 0); \
;     __builtin_amdgcn_global_load_lds((const unsigned*)((const char*)(gbase) + (v1)), (LAS unsigned*)(lds + (bufoff) + ldsw + 8192), 16, 0, 0); } while (0)
; #define G_LDA(dst, b, h) do { _Pragma("unroll") for (int m = 0; m < 4; ++m) _Pragma("unroll") for (int k = 0; k < 2; ++k) dst[m][k] = *(const LAS h8*)(lds + G_SA(b, h) + aoff + m * 2048 + k * 1024); } while (0)
; #define G_LDB(dst, b, h) do { _Pragma("unroll") for (int n = 0; n < 2; ++n) _Pragma("unroll") for (int k = 0; k < 2; ++k) dst[n][k] = *(const LAS h8*)(lds + G_SB(b, h) + boff + n * 2048 + k * 1024); } while (0)
; #define G_MMA(ai, bj, At, Bt) do { __builtin_amdgcn_s_setprio(1); _Pragma("unroll") for (int m = 0; m < 4; ++m) _Pragma("unroll") for (int n = 0; n < 2; ++n) _Pragma("unroll") for (int k = 0; k < 2; ++k) \
;     acc[ai][bj][m][n] = __builtin_amdgcn_mfma_f32_16x16x32_f16(Bt[n][k], At[m][k], acc[ai][bj][m][n], 0, 0, 0); __builtin_amdgcn_s_setprio(0); } while (0)
; #define G_WAIT_L(n) asm volatile("s_waitcnt lgkmcnt(" #n ")" ::: "memory")
; #define G_BAR __builtin_amdgcn_s_barrier()
; #define G_SCHED __builtin_amdgcn_sched_barrier(0)
; template <bool PERM, class Sched, class Epi>
; DI void gemm256(LAS unsigned char* lds, const Sched& S, const Epi& E, int wv_) {
;     ...
;     for (int t = 0; t < nt; t += 2) {
;       const bool last = (t == nt - 2);
;       const char* a1 = cA + (size_t)(t + 1) * kstep;
;       const char* a2 = last ? nA : cA + (size_t)(t + 2) * kstep;
;       const char* b2 = last ? nB : cB + (size_t)(t + 2) * kstep;
;       const char* a3 = a2 + kstep;
;       const char* b3 = b2 + kstep;
;       G_LDB(B0, 0, 0); G_SCHED; G_LDA(At, 0, 0); G_STAGE(G_SA(1, 1), a1 + chA, cvA0, cvA1);
;       G_WAIT_L(8); G_BAR; G_WAIT_L(0); G_MMA(0, 0, At, B0); G_BAR; G_SCHED;
;       G_LDB(B1, 0, 1); G_STAGE(G_SB(0, 0), b2, cvB0, cvB1);
;       G_BAR; G_WAIT_L(0); G_MMA(0, 1, At, B1); G_BAR;
;       G_LDA(At, 0, 1); G_STAGE(G_SA(0, 0), a2, cvA0, cvA1);
;       G_BAR; G_WAIT_L(0); G_MMA(1, 0, At, B0); G_BAR; G_SCHED;
.LBB0_2433:
	s_waitcnt vmcnt(0)
	v_or_b32_e32 v130, 0x10000, v162
	v_add_u32_e32 v134, 0x10400, v162
	v_add_u32_e32 v138, 0x10800, v162
	v_add_u32_e32 v142, 0x10c00, v162
	s_add_i32 s74, s20, 2
	ds_read_b128 v[130:133], v130
	ds_read_b128 v[134:137], v134
	ds_read_b128 v[138:141], v138
	ds_read_b128 v[142:145], v142
	s_add_u32 s21, s18, 0xfffc0080
	s_addc_u32 s22, s19, -1
	s_cmp_eq_u32 vcc_lo, s20
	s_cselect_b32 s20, s85, s75
	s_cselect_b32 s23, s9, s22
	s_cselect_b32 s22, s27, s21
	s_cselect_b32 s21, s56, s46
	v_lshl_add_u64 v[192:193], s[18:19], 0, v[158:159]
	s_add_i32 m0, s31, 0xc000
	ds_read_b128 v[146:149], v1
	ds_read_b128 v[164:167], v1 offset:1024
	ds_read_b128 v[168:171], v1 offset:2048
	ds_read_b128 v[172:175], v1 offset:3072
	ds_read_b128 v[176:179], v1 offset:4096
	ds_read_b128 v[180:183], v1 offset:5120
	ds_read_b128 v[184:187], v1 offset:6144
	ds_read_b128 v[188:191], v1 offset:7168
	global_load_lds_dwordx4 v[192:193], off
	v_lshl_add_u64 v[192:193], s[18:19], 0, v[160:161]
	s_add_i32 m0, s31, 0xe000
	s_nop 0
	global_load_lds_dwordx4 v[192:193], off
	s_waitcnt lgkmcnt(8)
	s_barrier
	s_waitcnt lgkmcnt(0)
	s_waitcnt lgkmcnt(0)
	v_mfma_f32_16x16x32_f16 v[126:129], v[130:133], v[146:149], v[126:129]
	v_mfma_f32_16x16x32_f16 v[122:125], v[138:141], v[146:149], v[122:125]
	v_mfma_f32_16x16x32_f16 v[110:113], v[130:133], v[168:171], v[110:113]
	v_mfma_f32_16x16x32_f16 v[106:109], v[138:141], v[168:171], v[106:109]
	v_mfma_f32_16x16x32_f16 v[94:97], v[130:133], v[176:179], v[94:97]
	v_mfma_f32_16x16x32_f16 v[90:93], v[138:141], v[176:179], v[90:93]
	v_mfma_f32_16x16x32_f16 v[78:81], v[130:133], v[184:187], v[78:81]
	v_mfma_f32_16x16x32_f16 v[74:77], v[138:141], v[184:187], v[74:77]
	v_mfma_f32_16x16x32_f16 v[126:129], v[134:137], v[164:167], v[126:129]
	v_mfma_f32_16x16x32_f16 v[122:125], v[142:145], v[164:167], v[122:125]
	v_mfma_f32_16x16x32_f16 v[110:113], v[134:137], v[172:175], v[110:113]
	v_mfma_f32_16x16x32_f16 v[106:109], v[142:145], v[172:175], v[106:109]
	v_mfma_f32_16x16x32_f16 v[94:97], v[134:137], v[180:183], v[94:97]
	v_mfma_f32_16x16x32_f16 v[90:93], v[142:145], v[180:183], v[90:93]
	v_mfma_f32_16x16x32_f16 v[78:81], v[134:137], v[188:191], v[78:81]
	v_mfma_f32_16x16x32_f16 v[74:77], v[142:145], v[188:191], v[74:77]
	s_barrier
	v_or_b32_e32 v163, 0x14000, v162
	v_add_u32_e32 v196, 0x14400, v162
	s_mov_b32 m0, s34
	ds_read_b128 v[192:195], v163
	ds_read_b128 v[196:199], v196
	v_add_u32_e32 v163, 0x14800, v162
	v_add_u32_e32 v204, 0x14c00, v162
	v_lshl_add_u64 v[208:209], s[20:21], 0, v[150:151]
	ds_read_b128 v[200:203], v163
	ds_read_b128 v[204:207], v204
	global_load_lds_dwordx4 v[208:209], off
	v_lshl_add_u64 v[210:211], s[20:21], 0, v[152:153]
	s_mov_b32 m0, s35
	s_nop 0
	global_load_lds_dwordx4 v[210:211], off
	s_barrier
	s_waitcnt lgkmcnt(0)
	s_waitcnt lgkmcnt(0)
	v_mfma_f32_16x16x32_f16 v[118:121], v[192:195], v[146:149], v[118:121]
	v_mfma_f32_16x16x32_f16 v[114:117], v[200:203], v[146:149], v[114:117]
	v_mfma_f32_16x16x32_f16 v[102:105], v[192:195], v[168:171], v[102:105]
	v_mfma_f32_16x16x32_f16 v[98:101], v[200:203], v[168:171], v[98:101]
	v_mfma_f32_16x16x32_f16 v[86:89], v[192:195], v[176:179], v[86:89]
	v_mfma_f32_16x16x32_f16 v[82:85], v[200:203], v[176:179], v[82:85]
	v_mfma_f32_16x16x32_f16 v[70:73], v[192:195], v[184:187], v[70:73]
	v_mfma_f32_16x16x32_f16 v[66:69], v[200:203], v[184:187], v[66:69]
	v_mfma_f32_16x16x32_f16 v[118:121], v[196:199], v[164:167], v[118:121]
	v_mfma_f32_16x16x32_f16 v[114:117], v[204:207], v[164:167], v[114:117]
	v_mfma_f32_16x16x32_f16 v[102:105], v[196:199], v[172:175], v[102:105]
	v_mfma_f32_16x16x32_f16 v[98:101], v[204:207], v[172:175], v[98:101]
	v_mfma_f32_16x16x32_f16 v[86:89], v[196:199], v[180:183], v[86:89]
	v_mfma_f32_16x16x32_f16 v[82:85], v[204:207], v[180:183], v[82:85]
	v_mfma_f32_16x16x32_f16 v[70:73], v[196:199], v[188:191], v[70:73]
	v_mfma_f32_16x16x32_f16 v[66:69], v[204:207], v[188:191], v[66:69]
	s_mov_b32 m0, s31
	v_lshl_add_u64 v[212:213], s[22:23], 0, v[150:151]
	s_barrier
	ds_read_b128 v[146:149], v1 offset:16384
	ds_read_b128 v[164:167], v1 offset:17408
	ds_read_b128 v[168:171], v1 offset:18432
	ds_read_b128 v[172:175], v1 offset:19456
	ds_read_b128 v[176:179], v1 offset:20480
	ds_read_b128 v[180:183], v1 offset:21504
	ds_read_b128 v[184:187], v1 offset:22528
	ds_read_b128 v[188:191], v1 offset:23552
	global_load_lds_dwordx4 v[212:213], off
	v_lshl_add_u64 v[214:215], s[22:23], 0, v[152:153]
	s_mov_b32 m0, s36
	s_nop 0
	global_load_lds_dwordx4 v[214:215], off
	s_barrier
	s_waitcnt lgkmcnt(0)
	s_waitcnt lgkmcnt(0)
	v_mfma_f32_16x16x32_f16 v[62:65], v[130:133], v[146:149], v[62:65]
	v_mfma_f32_16x16x32_f16 v[58:61], v[138:141], v[146:149], v[58:61]
	v_mfma_f32_16x16x32_f16 v[46:49], v[130:133], v[168:171], v[46:49]
	v_mfma_f32_16x16x32_f16 v[42:45], v[138:141], v[168:171], v[42:45]
	v_mfma_f32_16x16x32_f16 v[30:33], v[130:133], v[176:179], v[30:33]
	v_mfma_f32_16x16x32_f16 v[26:29], v[138:141], v[176:179], v[26:29]
	v_mfma_f32_16x16x32_f16 v[14:17], v[130:133], v[184:187], v[14:17]
	v_mfma_f32_16x16x32_f16 v[10:13], v[138:141], v[184:187], v[10:13]
	v_mfma_f32_16x16x32_f16 v[62:65], v[134:137], v[164:167], v[62:65]
	v_mfma_f32_16x16x32_f16 v[58:61], v[142:145], v[164:167], v[58:61]
	v_mfma_f32_16x16x32_f16 v[46:49], v[134:137], v[172:175], v[46:49]
	v_mfma_f32_16x16x32_f16 v[42:45], v[142:145], v[172:175], v[42:45]
	v_mfma_f32_16x16x32_f16 v[30:33], v[134:137], v[180:183], v[30:33]
	v_mfma_f32_16x16x32_f16 v[26:29], v[142:145], v[180:183], v[26:29]
	v_mfma_f32_16x16x32_f16 v[14:17], v[134:137], v[188:191], v[14:17]
	v_mfma_f32_16x16x32_f16 v[10:13], v[142:145], v[188:191], v[10:13]
	s_barrier
; #define G_STAGE(bufoff, gbase, v0, v1) do { \
;     __builtin_amdgcn_global_load_lds((const unsigned*)((const char*)(gbase) + (v0)), (LAS unsigned*)(lds + (bufoff) + ldsw), 16, 0, 0); \
;     __builtin_amdgcn_global_load_lds((const unsigned*)((const char*)(gbase) + (v1)), (LAS unsigned*)(lds + (bufoff) + ldsw + 8192), 16, 0, 0); } while (0)
; #define G_LDA(dst, b, h) do { _Pragma("unroll") for (int m = 0; m < 4; ++m) _Pragma("unroll") for (int k = 0; k < 2; ++k) dst[m][k] = *(const LAS h8*)(lds + G_SA(b, h) + aoff + m * 2048 + k * 1024); } while (0)
; #define G_LDB(dst, b, h) do { _Pragma("unroll") for (int n = 0; n < 2; ++n) _Pragma("unroll") for (int k = 0; k < 2; ++k) dst[n][k] = *(const LAS h8*)(lds + G_SB(b, h) + boff + n * 2048 + k * 1024); } while (0)
; #define G_MMA(ai, bj, At, Bt) do { __builtin_amdgcn_s_setprio(1); _Pragma("unroll") for (int m = 0; m < 4; ++m) _Pragma("unroll") for (int n = 0; n < 2; ++n) _Pragma("unroll") for (int k = 0; k < 2; ++k) \
;     acc[ai][bj][m][n] = __builtin_amdgcn_mfma_f32_16x16x32_f16(Bt[n][k], At[m][k], acc[ai][bj][m][n], 0, 0, 0); __builtin_amdgcn_s_setprio(0); } while (0)
; #define G_WAIT_V(n) asm volatile("s_waitcnt vmcnt(" #n ")" ::: "memory")
; #define G_WAIT_L(n) asm volatile("s_waitcnt lgkmcnt(" #n ")" ::: "memory")
; #define G_BAR __builtin_amdgcn_s_barrier()
; #define G_SCHED __builtin_amdgcn_sched_barrier(0)
; template <bool PERM, class Sched, class Epi>
; DI void gemm256(LAS unsigned char* lds, const Sched& S, const Epi& E, int wv_) {
;     ...
;       G_STAGE(G_SB(0, 1), b2 + chB, cvB0, cvB1);
;       G_WAIT_V(6); G_BAR; G_MMA(1, 1, At, B1); G_BAR;
;       G_LDB(B0, 1, 0); G_SCHED; G_LDA(At, 1, 0); G_STAGE(G_SA(0, 1), a2 + chA, cvA0, cvA1);
;       G_WAIT_L(8); G_BAR; G_WAIT_L(0); G_MMA(0, 0, At, B0); G_BAR; G_SCHED;
;       G_LDB(B1, 1, 1); G_STAGE(G_SB(1, 0), b3, cvB0, cvB1);
	s_add_u32 s40, s20, 0x40000
	s_addc_u32 s41, s21, 0
	s_mov_b32 m0, s37
	v_lshl_add_u64 v[130:131], s[40:41], 0, v[150:151]
	global_load_lds_dwordx4 v[130:131], off
	v_lshl_add_u64 v[130:131], s[40:41], 0, v[152:153]
	s_mov_b32 m0, s58
	s_nop 0
	global_load_lds_dwordx4 v[130:131], off
	s_waitcnt vmcnt(6)
	s_barrier
	v_mfma_f32_16x16x32_f16 v[54:57], v[192:195], v[146:149], v[54:57]
	v_mfma_f32_16x16x32_f16 v[50:53], v[200:203], v[146:149], v[50:53]
	v_mfma_f32_16x16x32_f16 v[38:41], v[192:195], v[168:171], v[38:41]
	v_mfma_f32_16x16x32_f16 v[34:37], v[200:203], v[168:171], v[34:37]
	v_mfma_f32_16x16x32_f16 v[22:25], v[192:195], v[176:179], v[22:25]
	v_mfma_f32_16x16x32_f16 v[18:21], v[200:203], v[176:179], v[18:21]
	v_mfma_f32_16x16x32_f16 v[6:9], v[192:195], v[184:187], v[6:9]
	v_mfma_f32_16x16x32_f16 v[2:5], v[200:203], v[184:187], v[2:5]
	v_mfma_f32_16x16x32_f16 v[54:57], v[196:199], v[164:167], v[54:57]
	v_mfma_f32_16x16x32_f16 v[50:53], v[204:207], v[164:167], v[50:53]
	v_mfma_f32_16x16x32_f16 v[38:41], v[196:199], v[172:175], v[38:41]
	v_mfma_f32_16x16x32_f16 v[34:37], v[204:207], v[172:175], v[34:37]
	v_mfma_f32_16x16x32_f16 v[22:25], v[196:199], v[180:183], v[22:25]
	v_mfma_f32_16x16x32_f16 v[18:21], v[204:207], v[180:183], v[18:21]
	v_mfma_f32_16x16x32_f16 v[6:9], v[196:199], v[188:191], v[6:9]
	v_mfma_f32_16x16x32_f16 v[2:5], v[204:207], v[188:191], v[2:5]
	v_or_b32_e32 v130, 0x18000, v162
	v_add_u32_e32 v134, 0x18400, v162
	v_add_u32_e32 v138, 0x18800, v162
	v_add_u32_e32 v142, 0x18c00, v162
	s_barrier
	ds_read_b128 v[130:133], v130
	ds_read_b128 v[134:137], v134
	ds_read_b128 v[138:141], v138
	ds_read_b128 v[142:145], v142
	s_add_u32 s22, s22, 0x40000
	s_addc_u32 s23, s23, 0
	s_mov_b32 m0, s59
	v_lshl_add_u64 v[192:193], s[22:23], 0, v[150:151]
	ds_read_b128 v[146:149], v1 offset:32768
	ds_read_b128 v[164:167], v1 offset:33792
	ds_read_b128 v[168:171], v1 offset:34816
	ds_read_b128 v[172:175], v1 offset:35840
	ds_read_b128 v[176:179], v1 offset:36864
	ds_read_b128 v[180:183], v1 offset:37888
	ds_read_b128 v[184:187], v1 offset:38912
	ds_read_b128 v[188:191], v1 offset:39936
	global_load_lds_dwordx4 v[192:193], off
	v_lshl_add_u64 v[192:193], s[22:23], 0, v[152:153]
	s_mov_b32 m0, s61
	s_nop 0
	global_load_lds_dwordx4 v[192:193], off
	s_waitcnt lgkmcnt(8)
	s_barrier
	s_waitcnt lgkmcnt(0)
	s_waitcnt lgkmcnt(0)
	v_mfma_f32_16x16x32_f16 v[126:129], v[130:133], v[146:149], v[126:129]
	v_mfma_f32_16x16x32_f16 v[122:125], v[138:141], v[146:149], v[122:125]
	v_mfma_f32_16x16x32_f16 v[110:113], v[130:133], v[168:171], v[110:113]
	v_mfma_f32_16x16x32_f16 v[106:109], v[138:141], v[168:171], v[106:109]
	v_mfma_f32_16x16x32_f16 v[94:97], v[130:133], v[176:179], v[94:97]
	v_mfma_f32_16x16x32_f16 v[90:93], v[138:141], v[176:179], v[90:93]
	v_mfma_f32_16x16x32_f16 v[78:81], v[130:133], v[184:187], v[78:81]
	v_mfma_f32_16x16x32_f16 v[74:77], v[138:141], v[184:187], v[74:77]
	v_mfma_f32_16x16x32_f16 v[126:129], v[134:137], v[164:167], v[126:129]
	v_mfma_f32_16x16x32_f16 v[122:125], v[142:145], v[164:167], v[122:125]
	v_mfma_f32_16x16x32_f16 v[110:113], v[134:137], v[172:175], v[110:113]
	v_mfma_f32_16x16x32_f16 v[106:109], v[142:145], v[172:175], v[106:109]
	v_mfma_f32_16x16x32_f16 v[94:97], v[134:137], v[180:183], v[94:97]
	v_mfma_f32_16x16x32_f16 v[90:93], v[142:145], v[180:183], v[90:93]
	v_mfma_f32_16x16x32_f16 v[78:81], v[134:137], v[188:191], v[78:81]
	v_mfma_f32_16x16x32_f16 v[74:77], v[142:145], v[188:191], v[74:77]
	s_barrier
	v_or_b32_e32 v163, 0x1c000, v162
	v_add_u32_e32 v196, 0x1c400, v162
	s_mov_b32 m0, s69
	ds_read_b128 v[192:195], v163
	ds_read_b128 v[196:199], v196
	v_add_u32_e32 v163, 0x1c800, v162
	v_add_u32_e32 v204, 0x1cc00, v162
	v_lshl_add_u64 v[208:209], v[208:209], 0, s[86:87]
	ds_read_b128 v[200:203], v163
	ds_read_b128 v[204:207], v204
	global_load_lds_dwordx4 v[208:209], off
	v_lshl_add_u64 v[208:209], v[210:211], 0, s[86:87]
	s_mov_b32 m0, s78
	s_nop 0
	global_load_lds_dwordx4 v[208:209], off
	s_barrier
; #define G_STAGE(bufoff, gbase, v0, v1) do { \
;     __builtin_amdgcn_global_load_lds((const unsigned*)((const char*)(gbase) + (v0)), (LAS unsigned*)(lds + (bufoff) + ldsw), 16, 0, 0); \
;     __builtin_amdgcn_global_load_lds((const unsigned*)((const char*)(gbase) + (v1)), (LAS unsigned*)(lds + (bufoff) + ldsw + 8192), 16, 0, 0); } while (0)
; #define G_LDA(dst, b, h) do { _Pragma("unroll") for (int m = 0; m < 4; ++m) _Pragma("unroll") for (int k = 0; k < 2; ++k) dst[m][k] = *(const LAS h8*)(lds + G_SA(b, h) + aoff + m * 2048 + k * 1024); } while (0)
; #define G_LDB(dst, b, h) do { _Pragma("unroll") for (int n = 0; n < 2; ++n) _Pragma("unroll") for (int k = 0; k < 2; ++k) dst[n][k] = *(const LAS h8*)(lds + G_SB(b, h) + boff + n * 2048 + k * 1024); } while (0)
; #define G_MMA(ai, bj, At, Bt) do { __builtin_amdgcn_s_setprio(1); _Pragma("unroll") for (int m = 0; m < 4; ++m) _Pragma("unroll") for (int n = 0; n < 2; ++n) _Pragma("unroll") for (int k = 0; k < 2; ++k) \
;     acc[ai][bj][m][n] = __builtin_amdgcn_mfma_f32_16x16x32_f16(Bt[n][k], At[m][k], acc[ai][bj][m][n], 0, 0, 0); __builtin_amdgcn_s_setprio(0); } while (0)
; #define G_WAIT_V(n) asm volatile("s_waitcnt vmcnt(" #n ")" ::: "memory")
; #define G_WAIT_L(n) asm volatile("s_waitcnt lgkmcnt(" #n ")" ::: "memory")
; #define G_BAR __builtin_amdgcn_s_barrier()
; #define G_SCHED __builtin_amdgcn_sched_barrier(0)
; template <bool PERM, class Sched, class Epi>
; DI void gemm256(LAS unsigned char* lds, const Sched& S, const Epi& E, int wv_) {
;     ...
;       G_LDB(B1, 1, 1); G_STAGE(G_SB(1, 0), b3, cvB0, cvB1);
;       G_BAR; G_WAIT_L(0); G_MMA(0, 1, At, B1); G_BAR;
;       G_LDA(At, 1, 1); G_STAGE(G_SA(1, 0), a3, cvA0, cvA1);
;       G_BAR; G_WAIT_L(0); G_MMA(1, 0, At, B0); G_BAR; G_SCHED;
;       G_STAGE(G_SB(1, 1), b3 + chB, cvB0, cvB1);
;       G_WAIT_V(6); G_BAR; G_MMA(1, 1, At, B1); G_BAR;
;     }
	s_waitcnt lgkmcnt(0)
	s_waitcnt lgkmcnt(0)
	v_mfma_f32_16x16x32_f16 v[118:121], v[192:195], v[146:149], v[118:121]
	v_mfma_f32_16x16x32_f16 v[114:117], v[200:203], v[146:149], v[114:117]
	v_mfma_f32_16x16x32_f16 v[102:105], v[192:195], v[168:171], v[102:105]
	v_mfma_f32_16x16x32_f16 v[98:101], v[200:203], v[168:171], v[98:101]
	v_mfma_f32_16x16x32_f16 v[86:89], v[192:195], v[176:179], v[86:89]
	v_mfma_f32_16x16x32_f16 v[82:85], v[200:203], v[176:179], v[82:85]
	v_mfma_f32_16x16x32_f16 v[70:73], v[192:195], v[184:187], v[70:73]
	v_mfma_f32_16x16x32_f16 v[66:69], v[200:203], v[184:187], v[66:69]
	v_mfma_f32_16x16x32_f16 v[118:121], v[196:199], v[164:167], v[118:121]
	v_mfma_f32_16x16x32_f16 v[114:117], v[204:207], v[164:167], v[114:117]
	v_mfma_f32_16x16x32_f16 v[102:105], v[196:199], v[172:175], v[102:105]
	v_mfma_f32_16x16x32_f16 v[98:101], v[204:207], v[172:175], v[98:101]
	v_mfma_f32_16x16x32_f16 v[86:89], v[196:199], v[180:183], v[86:89]
	v_mfma_f32_16x16x32_f16 v[82:85], v[204:207], v[180:183], v[82:85]
	v_mfma_f32_16x16x32_f16 v[70:73], v[196:199], v[188:191], v[70:73]
	v_mfma_f32_16x16x32_f16 v[66:69], v[204:207], v[188:191], v[66:69]
	s_mov_b32 m0, s79
	v_lshl_add_u64 v[208:209], v[212:213], 0, s[86:87]
	s_barrier
	ds_read_b128 v[146:149], v1 offset:49152
	ds_read_b128 v[164:167], v1 offset:50176
	ds_read_b128 v[168:171], v1 offset:51200
	ds_read_b128 v[172:175], v1 offset:52224
	ds_read_b128 v[176:179], v1 offset:53248
	ds_read_b128 v[180:183], v1 offset:54272
	ds_read_b128 v[184:187], v1 offset:55296
	ds_read_b128 v[188:191], v1 offset:56320
	global_load_lds_dwordx4 v[208:209], off
	v_lshl_add_u64 v[208:209], v[214:215], 0, s[86:87]
	s_mov_b32 m0, s83
	s_nop 0
	global_load_lds_dwordx4 v[208:209], off
	s_barrier
	s_waitcnt lgkmcnt(0)
	s_waitcnt lgkmcnt(0)
	v_mfma_f32_16x16x32_f16 v[62:65], v[130:133], v[146:149], v[62:65]
	v_mfma_f32_16x16x32_f16 v[58:61], v[138:141], v[146:149], v[58:61]
	v_mfma_f32_16x16x32_f16 v[46:49], v[130:133], v[168:171], v[46:49]
	v_mfma_f32_16x16x32_f16 v[42:45], v[138:141], v[168:171], v[42:45]
	v_mfma_f32_16x16x32_f16 v[30:33], v[130:133], v[176:179], v[30:33]
	v_mfma_f32_16x16x32_f16 v[26:29], v[138:141], v[176:179], v[26:29]
	v_mfma_f32_16x16x32_f16 v[14:17], v[130:133], v[184:187], v[14:17]
	v_mfma_f32_16x16x32_f16 v[10:13], v[138:141], v[184:187], v[10:13]
	v_mfma_f32_16x16x32_f16 v[62:65], v[134:137], v[164:167], v[62:65]
	v_mfma_f32_16x16x32_f16 v[58:61], v[142:145], v[164:167], v[58:61]
	v_mfma_f32_16x16x32_f16 v[46:49], v[134:137], v[172:175], v[46:49]
	v_mfma_f32_16x16x32_f16 v[42:45], v[142:145], v[172:175], v[42:45]
	v_mfma_f32_16x16x32_f16 v[30:33], v[134:137], v[180:183], v[30:33]
	v_mfma_f32_16x16x32_f16 v[26:29], v[142:145], v[180:183], v[26:29]
	v_mfma_f32_16x16x32_f16 v[14:17], v[134:137], v[188:191], v[14:17]
	v_mfma_f32_16x16x32_f16 v[10:13], v[142:145], v[188:191], v[10:13]
	s_barrier
	s_add_u32 s20, s20, 0x40080
	s_addc_u32 s21, s21, 0
	s_mov_b32 m0, s90
	v_lshl_add_u64 v[130:131], s[20:21], 0, v[150:151]
	global_load_lds_dwordx4 v[130:131], off
	v_lshl_add_u64 v[130:131], s[20:21], 0, v[152:153]
	s_mov_b32 m0, s93
	s_nop 0
	global_load_lds_dwordx4 v[130:131], off
	s_waitcnt vmcnt(6)
	s_barrier
	v_mfma_f32_16x16x32_f16 v[54:57], v[192:195], v[146:149], v[54:57]
	v_mfma_f32_16x16x32_f16 v[50:53], v[200:203], v[146:149], v[50:53]
	v_mfma_f32_16x16x32_f16 v[38:41], v[192:195], v[168:171], v[38:41]
	v_mfma_f32_16x16x32_f16 v[34:37], v[200:203], v[168:171], v[34:37]
	v_mfma_f32_16x16x32_f16 v[22:25], v[192:195], v[176:179], v[22:25]
	v_mfma_f32_16x16x32_f16 v[18:21], v[200:203], v[176:179], v[18:21]
	v_mfma_f32_16x16x32_f16 v[6:9], v[192:195], v[184:187], v[6:9]
	v_mfma_f32_16x16x32_f16 v[2:5], v[200:203], v[184:187], v[2:5]
	v_mfma_f32_16x16x32_f16 v[54:57], v[196:199], v[164:167], v[54:57]
	v_mfma_f32_16x16x32_f16 v[50:53], v[204:207], v[164:167], v[50:53]
	v_mfma_f32_16x16x32_f16 v[38:41], v[196:199], v[172:175], v[38:41]
	v_mfma_f32_16x16x32_f16 v[34:37], v[204:207], v[172:175], v[34:37]
	v_mfma_f32_16x16x32_f16 v[22:25], v[196:199], v[180:183], v[22:25]
	v_mfma_f32_16x16x32_f16 v[18:21], v[204:207], v[180:183], v[18:21]
	v_mfma_f32_16x16x32_f16 v[6:9], v[196:199], v[188:191], v[6:9]
	v_mfma_f32_16x16x32_f16 v[2:5], v[204:207], v[188:191], v[2:5]
	s_add_u32 s18, s18, 0x100
	s_addc_u32 s19, s19, 0
	s_add_u32 s75, s75, 0x100
	s_addc_u32 s46, s46, 0
	s_cmp_ge_i32 s74, s25
	s_mov_b32 s20, s74
	s_barrier
	s_cbranch_scc0 .LBB0_2433
	s_mov_b32 s56, 0x8fff
	s_branch .LBB0_2436

; #define G_STAGE(bufoff, gbase, v0, v1) do { \
;     __builtin_amdgcn_global_load_lds((const unsigned*)((const char*)(gbase) + (v0)), (LAS unsigned*)(lds + (bufoff) + ldsw), 16, 0, 0); \
;     __builtin_amdgcn_global_load_lds((const unsigned*)((const char*)(gbase) + (v1)), (LAS unsigned*)(lds + (bufoff) + ldsw + 8192), 16, 0, 0); } while (0)
; #define G_LDA(dst, b, h) do { _Pragma("unroll") for (int m = 0; m < 4; ++m) _Pragma("unroll") for (int k = 0; k < 2; ++k) dst[m][k] = *(const LAS h8*)(lds + G_SA(b, h) + aoff + m * 2048 + k * 1024); } while (0)
; #define G_LDB(dst, b, h) do { _Pragma("unroll") for (int n = 0; n < 2; ++n) _Pragma("unroll") for (int k = 0; k < 2; ++k) dst[n][k] = *(const LAS h8*)(lds + G_SB(b, h) + boff + n * 2048 + k * 1024); } while (0)
; #define G_MMA(ai, bj, At, Bt) do { __builtin_amdgcn_s_setprio(1); _Pragma("unroll") for (int m = 0; m < 4; ++m) _Pragma("unroll") for (int n = 0; n < 2; ++n) _Pragma("unroll") for (int k = 0; k < 2; ++k) \
;     acc[ai][bj][m][n] = __builtin_amdgcn_mfma_f32_16x16x32_f16(Bt[n][k], At[m][k], acc[ai][bj][m][n], 0, 0, 0); __builtin_amdgcn_s_setprio(0); } while (0)
; #define G_WAIT_V(n) asm volatile("s_waitcnt vmcnt(" #n ")" ::: "memory")
; #define G_WAIT_L(n) asm volatile("s_waitcnt lgkmcnt(" #n ")" ::: "memory")
; #define G_BAR __builtin_amdgcn_s_barrier()
; #define G_SCHED __builtin_amdgcn_sched_barrier(0)
; template <bool PERM, class Sched, class Epi>
; DI void gemm256(LAS unsigned char* lds, const Sched& S, const Epi& E, int wv_) {
;     ...
;       G_LDB(B0, 0, 0); G_SCHED; G_LDA(At, 0, 0); G_STAGE(G_SA(1, 1), a1 + chA, cvA0, cvA1);
;       G_WAIT_L(8); G_BAR; G_WAIT_L(0); G_MMA(0, 0, At, B0); G_BAR; G_SCHED;
;       G_LDB(B1, 0, 1); G_STAGE(G_SB(0, 0), b2, cvB0, cvB1);
;       G_BAR; G_WAIT_L(0); G_MMA(0, 1, At, B1); G_BAR;
;       G_LDA(At, 0, 1); G_STAGE(G_SA(0, 0), a2, cvA0, cvA1);
;       G_BAR; G_WAIT_L(0); G_MMA(1, 0, At, B0); G_BAR; G_SCHED;
;       G_STAGE(G_SB(0, 1), b2 + chB, cvB0, cvB1);
;       G_WAIT_V(6); G_BAR; G_MMA(1, 1, At, B1); G_BAR;
.LBB0_2581:
	v_or_b32_e32 v144, 0x10000, v142
	v_add_u32_e32 v148, 0x10400, v142
	v_add_u32_e32 v152, 0x10800, v142
	v_add_u32_e32 v156, 0x10c00, v142
	s_add_i32 s68, s14, 2
	ds_read_b128 v[144:147], v144
	ds_read_b128 v[148:151], v148
	ds_read_b128 v[152:155], v152
	ds_read_b128 v[156:159], v156
	s_add_u32 s15, s12, 0xfffc0080
	s_addc_u32 s16, s13, -1
	s_cmp_eq_u32 s11, s14
	s_cselect_b32 s14, s8, s66
	s_cselect_b32 s17, s7, s16
	s_cselect_b32 s16, s6, s15
	s_cselect_b32 s15, s9, s46
	v_lshl_add_u64 v[192:193], s[12:13], 0, v[138:139]
	s_add_i32 m0, s24, 0xc000
	ds_read_b128 v[160:163], v1
	ds_read_b128 v[164:167], v1 offset:1024
	ds_read_b128 v[168:171], v1 offset:2048
	ds_read_b128 v[172:175], v1 offset:3072
	ds_read_b128 v[176:179], v1 offset:4096
	ds_read_b128 v[180:183], v1 offset:5120
	ds_read_b128 v[184:187], v1 offset:6144
	ds_read_b128 v[188:191], v1 offset:7168
	global_load_lds_dwordx4 v[192:193], off
	v_lshl_add_u64 v[192:193], s[12:13], 0, v[140:141]
	s_add_i32 m0, s24, 0xe000
	s_nop 0
	global_load_lds_dwordx4 v[192:193], off
	s_waitcnt lgkmcnt(8)
	s_barrier
	s_waitcnt lgkmcnt(0)
	s_waitcnt lgkmcnt(0)
	v_mfma_f32_16x16x32_f16 v[126:129], v[144:147], v[160:163], v[126:129]
	v_mfma_f32_16x16x32_f16 v[122:125], v[152:155], v[160:163], v[122:125]
	v_mfma_f32_16x16x32_f16 v[110:113], v[144:147], v[168:171], v[110:113]
	v_mfma_f32_16x16x32_f16 v[106:109], v[152:155], v[168:171], v[106:109]
	v_mfma_f32_16x16x32_f16 v[94:97], v[144:147], v[176:179], v[94:97]
	v_mfma_f32_16x16x32_f16 v[90:93], v[152:155], v[176:179], v[90:93]
	v_mfma_f32_16x16x32_f16 v[78:81], v[144:147], v[184:187], v[78:81]
	v_mfma_f32_16x16x32_f16 v[74:77], v[152:155], v[184:187], v[74:77]
	v_mfma_f32_16x16x32_f16 v[126:129], v[148:151], v[164:167], v[126:129]
	v_mfma_f32_16x16x32_f16 v[122:125], v[156:159], v[164:167], v[122:125]
	v_mfma_f32_16x16x32_f16 v[110:113], v[148:151], v[172:175], v[110:113]
	v_mfma_f32_16x16x32_f16 v[106:109], v[156:159], v[172:175], v[106:109]
	v_mfma_f32_16x16x32_f16 v[94:97], v[148:151], v[180:183], v[94:97]
	v_mfma_f32_16x16x32_f16 v[90:93], v[156:159], v[180:183], v[90:93]
	v_mfma_f32_16x16x32_f16 v[78:81], v[148:151], v[188:191], v[78:81]
	v_mfma_f32_16x16x32_f16 v[74:77], v[156:159], v[188:191], v[74:77]
	s_barrier
	s_mov_b32 m0, s25
	v_or_b32_e32 v192, 0x14000, v142
	v_add_u32_e32 v196, 0x14400, v142
	v_add_u32_e32 v200, 0x14800, v142
	v_add_u32_e32 v204, 0x14c00, v142
	v_lshl_add_u64 v[208:209], s[14:15], 0, v[132:133]
	ds_read_b128 v[192:195], v192
	ds_read_b128 v[196:199], v196
	ds_read_b128 v[200:203], v200
	ds_read_b128 v[204:207], v204
	global_load_lds_dwordx4 v[208:209], off
	v_lshl_add_u64 v[210:211], s[14:15], 0, v[136:137]
	s_mov_b32 m0, s26
	s_nop 0
	global_load_lds_dwordx4 v[210:211], off
	s_barrier
	s_waitcnt lgkmcnt(0)
	s_waitcnt lgkmcnt(0)
	v_mfma_f32_16x16x32_f16 v[118:121], v[192:195], v[160:163], v[118:121]
	v_mfma_f32_16x16x32_f16 v[114:117], v[200:203], v[160:163], v[114:117]
	v_mfma_f32_16x16x32_f16 v[102:105], v[192:195], v[168:171], v[102:105]
	v_mfma_f32_16x16x32_f16 v[98:101], v[200:203], v[168:171], v[98:101]
	v_mfma_f32_16x16x32_f16 v[86:89], v[192:195], v[176:179], v[86:89]
	v_mfma_f32_16x16x32_f16 v[82:85], v[200:203], v[176:179], v[82:85]
	v_mfma_f32_16x16x32_f16 v[70:73], v[192:195], v[184:187], v[70:73]
	v_mfma_f32_16x16x32_f16 v[66:69], v[200:203], v[184:187], v[66:69]
	v_mfma_f32_16x16x32_f16 v[118:121], v[196:199], v[164:167], v[118:121]
	v_mfma_f32_16x16x32_f16 v[114:117], v[204:207], v[164:167], v[114:117]
	v_mfma_f32_16x16x32_f16 v[102:105], v[196:199], v[172:175], v[102:105]
	v_mfma_f32_16x16x32_f16 v[98:101], v[204:207], v[172:175], v[98:101]
	v_mfma_f32_16x16x32_f16 v[86:89], v[196:199], v[180:183], v[86:89]
	v_mfma_f32_16x16x32_f16 v[82:85], v[204:207], v[180:183], v[82:85]
	v_mfma_f32_16x16x32_f16 v[70:73], v[196:199], v[188:191], v[70:73]
	v_mfma_f32_16x16x32_f16 v[66:69], v[204:207], v[188:191], v[66:69]
	s_mov_b32 m0, s24
	v_lshl_add_u64 v[212:213], s[16:17], 0, v[130:131]
	s_barrier
	ds_read_b128 v[160:163], v1 offset:16384
	ds_read_b128 v[164:167], v1 offset:17408
	ds_read_b128 v[168:171], v1 offset:18432
	ds_read_b128 v[172:175], v1 offset:19456
	ds_read_b128 v[176:179], v1 offset:20480
	ds_read_b128 v[180:183], v1 offset:21504
	ds_read_b128 v[184:187], v1 offset:22528
	ds_read_b128 v[188:191], v1 offset:23552
	global_load_lds_dwordx4 v[212:213], off
	v_lshl_add_u64 v[214:215], s[16:17], 0, v[134:135]
	s_mov_b32 m0, s27
	s_nop 0
	global_load_lds_dwordx4 v[214:215], off
	s_barrier
	s_waitcnt lgkmcnt(0)
	s_waitcnt lgkmcnt(0)
	v_mfma_f32_16x16x32_f16 v[62:65], v[144:147], v[160:163], v[62:65]
	v_mfma_f32_16x16x32_f16 v[58:61], v[152:155], v[160:163], v[58:61]
	v_mfma_f32_16x16x32_f16 v[46:49], v[144:147], v[168:171], v[46:49]
	v_mfma_f32_16x16x32_f16 v[42:45], v[152:155], v[168:171], v[42:45]
	v_mfma_f32_16x16x32_f16 v[30:33], v[144:147], v[176:179], v[30:33]
	v_mfma_f32_16x16x32_f16 v[26:29], v[152:155], v[176:179], v[26:29]
	v_mfma_f32_16x16x32_f16 v[14:17], v[144:147], v[184:187], v[14:17]
	v_mfma_f32_16x16x32_f16 v[10:13], v[152:155], v[184:187], v[10:13]
	v_mfma_f32_16x16x32_f16 v[62:65], v[148:151], v[164:167], v[62:65]
	v_mfma_f32_16x16x32_f16 v[58:61], v[156:159], v[164:167], v[58:61]
	v_mfma_f32_16x16x32_f16 v[46:49], v[148:151], v[172:175], v[46:49]
	v_mfma_f32_16x16x32_f16 v[42:45], v[156:159], v[172:175], v[42:45]
	v_mfma_f32_16x16x32_f16 v[30:33], v[148:151], v[180:183], v[30:33]
	v_mfma_f32_16x16x32_f16 v[26:29], v[156:159], v[180:183], v[26:29]
	v_mfma_f32_16x16x32_f16 v[14:17], v[148:151], v[188:191], v[14:17]
	v_mfma_f32_16x16x32_f16 v[10:13], v[156:159], v[188:191], v[10:13]
	s_barrier
; #define G_STAGE(bufoff, gbase, v0, v1) do { \
;     __builtin_amdgcn_global_load_lds((const unsigned*)((const char*)(gbase) + (v0)), (LAS unsigned*)(lds + (bufoff) + ldsw), 16, 0, 0); \
;     __builtin_amdgcn_global_load_lds((const unsigned*)((const char*)(gbase) + (v1)), (LAS unsigned*)(lds + (bufoff) + ldsw + 8192), 16, 0, 0); } while (0)
; #define G_LDA(dst, b, h) do { _Pragma("unroll") for (int m = 0; m < 4; ++m) _Pragma("unroll") for (int k = 0; k < 2; ++k) dst[m][k] = *(const LAS h8*)(lds + G_SA(b, h) + aoff + m * 2048 + k * 1024); } while (0)
; #define G_LDB(dst, b, h) do { _Pragma("unroll") for (int n = 0; n < 2; ++n) _Pragma("unroll") for (int k = 0; k < 2; ++k) dst[n][k] = *(const LAS h8*)(lds + G_SB(b, h) + boff + n * 2048 + k * 1024); } while (0)
; #define G_MMA(ai, bj, At, Bt) do { __builtin_amdgcn_s_setprio(1); _Pragma("unroll") for (int m = 0; m < 4; ++m) _Pragma("unroll") for (int n = 0; n < 2; ++n) _Pragma("unroll") for (int k = 0; k < 2; ++k) \
;     acc[ai][bj][m][n] = __builtin_amdgcn_mfma_f32_16x16x32_f16(Bt[n][k], At[m][k], acc[ai][bj][m][n], 0, 0, 0); __builtin_amdgcn_s_setprio(0); } while (0)
; #define G_WAIT_V(n) asm volatile("s_waitcnt vmcnt(" #n ")" ::: "memory")
; #define G_WAIT_L(n) asm volatile("s_waitcnt lgkmcnt(" #n ")" ::: "memory")
; #define G_BAR __builtin_amdgcn_s_barrier()
; #define G_SCHED __builtin_amdgcn_sched_barrier(0)
; template <bool PERM, class Sched, class Epi>
; DI void gemm256(LAS unsigned char* lds, const Sched& S, const Epi& E, int wv_) {
;     ...
;       G_STAGE(G_SB(0, 1), b2 + chB, cvB0, cvB1);
;       G_WAIT_V(6); G_BAR; G_MMA(1, 1, At, B1); G_BAR;
;       G_LDB(B0, 1, 0); G_SCHED; G_LDA(At, 1, 0); G_STAGE(G_SA(0, 1), a2 + chA, cvA0, cvA1);
;       G_WAIT_L(8); G_BAR; G_WAIT_L(0); G_MMA(0, 0, At, B0); G_BAR; G_SCHED;
;       G_LDB(B1, 1, 1); G_STAGE(G_SB(1, 0), b3, cvB0, cvB1);
;       G_BAR; G_WAIT_L(0); G_MMA(0, 1, At, B1); G_BAR;
;       G_LDA(At, 1, 1); G_STAGE(G_SA(1, 0), a3, cvA0, cvA1);
;       G_BAR; G_WAIT_L(0); G_MMA(1, 0, At, B0); G_BAR; G_SCHED;
	s_add_u32 s40, s14, 0x40000
	s_addc_u32 s41, s15, 0
	s_mov_b32 m0, s28
	v_lshl_add_u64 v[144:145], s[40:41], 0, v[132:133]
	global_load_lds_dwordx4 v[144:145], off
	v_lshl_add_u64 v[144:145], s[40:41], 0, v[136:137]
	s_mov_b32 m0, s29
	s_nop 0
	global_load_lds_dwordx4 v[144:145], off
	s_waitcnt vmcnt(6)
	s_barrier
	v_mfma_f32_16x16x32_f16 v[54:57], v[192:195], v[160:163], v[54:57]
	v_mfma_f32_16x16x32_f16 v[50:53], v[200:203], v[160:163], v[50:53]
	v_mfma_f32_16x16x32_f16 v[38:41], v[192:195], v[168:171], v[38:41]
	v_mfma_f32_16x16x32_f16 v[34:37], v[200:203], v[168:171], v[34:37]
	v_mfma_f32_16x16x32_f16 v[22:25], v[192:195], v[176:179], v[22:25]
	v_mfma_f32_16x16x32_f16 v[18:21], v[200:203], v[176:179], v[18:21]
	v_mfma_f32_16x16x32_f16 v[6:9], v[192:195], v[184:187], v[6:9]
	v_mfma_f32_16x16x32_f16 v[2:5], v[200:203], v[184:187], v[2:5]
	v_mfma_f32_16x16x32_f16 v[54:57], v[196:199], v[164:167], v[54:57]
	v_mfma_f32_16x16x32_f16 v[50:53], v[204:207], v[164:167], v[50:53]
	v_mfma_f32_16x16x32_f16 v[38:41], v[196:199], v[172:175], v[38:41]
	v_mfma_f32_16x16x32_f16 v[34:37], v[204:207], v[172:175], v[34:37]
	v_mfma_f32_16x16x32_f16 v[22:25], v[196:199], v[180:183], v[22:25]
	v_mfma_f32_16x16x32_f16 v[18:21], v[204:207], v[180:183], v[18:21]
	v_mfma_f32_16x16x32_f16 v[6:9], v[196:199], v[188:191], v[6:9]
	v_mfma_f32_16x16x32_f16 v[2:5], v[204:207], v[188:191], v[2:5]
	v_or_b32_e32 v144, 0x18000, v142
	v_add_u32_e32 v148, 0x18400, v142
	v_add_u32_e32 v152, 0x18800, v142
	v_add_u32_e32 v156, 0x18c00, v142
	s_barrier
	ds_read_b128 v[144:147], v144
	ds_read_b128 v[148:151], v148
	ds_read_b128 v[152:155], v152
	ds_read_b128 v[156:159], v156
	s_add_u32 s16, s16, 0x40000
	s_addc_u32 s17, s17, 0
	s_mov_b32 m0, s30
	v_lshl_add_u64 v[192:193], s[16:17], 0, v[130:131]
	ds_read_b128 v[160:163], v1 offset:32768
	ds_read_b128 v[164:167], v1 offset:33792
	ds_read_b128 v[168:171], v1 offset:34816
	ds_read_b128 v[172:175], v1 offset:35840
	ds_read_b128 v[176:179], v1 offset:36864
	ds_read_b128 v[180:183], v1 offset:37888
	ds_read_b128 v[184:187], v1 offset:38912
	ds_read_b128 v[188:191], v1 offset:39936
	global_load_lds_dwordx4 v[192:193], off
	v_lshl_add_u64 v[192:193], s[16:17], 0, v[134:135]
	s_mov_b32 m0, s31
	s_nop 0
	global_load_lds_dwordx4 v[192:193], off
	s_waitcnt lgkmcnt(8)
	s_barrier
	s_waitcnt lgkmcnt(0)
	s_waitcnt lgkmcnt(0)
	v_mfma_f32_16x16x32_f16 v[126:129], v[144:147], v[160:163], v[126:129]
	v_mfma_f32_16x16x32_f16 v[122:125], v[152:155], v[160:163], v[122:125]
	v_mfma_f32_16x16x32_f16 v[110:113], v[144:147], v[168:171], v[110:113]
	v_mfma_f32_16x16x32_f16 v[106:109], v[152:155], v[168:171], v[106:109]
	v_mfma_f32_16x16x32_f16 v[94:97], v[144:147], v[176:179], v[94:97]
	v_mfma_f32_16x16x32_f16 v[90:93], v[152:155], v[176:179], v[90:93]
	v_mfma_f32_16x16x32_f16 v[78:81], v[144:147], v[184:187], v[78:81]
	v_mfma_f32_16x16x32_f16 v[74:77], v[152:155], v[184:187], v[74:77]
	v_mfma_f32_16x16x32_f16 v[126:129], v[148:151], v[164:167], v[126:129]
	v_mfma_f32_16x16x32_f16 v[122:125], v[156:159], v[164:167], v[122:125]
	v_mfma_f32_16x16x32_f16 v[110:113], v[148:151], v[172:175], v[110:113]
	v_mfma_f32_16x16x32_f16 v[106:109], v[156:159], v[172:175], v[106:109]
	v_mfma_f32_16x16x32_f16 v[94:97], v[148:151], v[180:183], v[94:97]
	v_mfma_f32_16x16x32_f16 v[90:93], v[156:159], v[180:183], v[90:93]
	v_mfma_f32_16x16x32_f16 v[78:81], v[148:151], v[188:191], v[78:81]
	v_mfma_f32_16x16x32_f16 v[74:77], v[156:159], v[188:191], v[74:77]
	s_barrier
	s_mov_b32 m0, s35
	v_or_b32_e32 v192, 0x1c000, v142
	v_add_u32_e32 v196, 0x1c400, v142
	v_add_u32_e32 v200, 0x1c800, v142
	v_add_u32_e32 v204, 0x1cc00, v142
	v_lshl_add_u64 v[208:209], v[208:209], 0, s[86:87]
	ds_read_b128 v[192:195], v192
	ds_read_b128 v[196:199], v196
	ds_read_b128 v[200:203], v200
	ds_read_b128 v[204:207], v204
	global_load_lds_dwordx4 v[208:209], off
	v_lshl_add_u64 v[208:209], v[210:211], 0, s[86:87]
	s_mov_b32 m0, s36
	s_nop 0
	global_load_lds_dwordx4 v[208:209], off
	s_barrier
; #define G_STAGE(bufoff, gbase, v0, v1) do { \
;     __builtin_amdgcn_global_load_lds((const unsigned*)((const char*)(gbase) + (v0)), (LAS unsigned*)(lds + (bufoff) + ldsw), 16, 0, 0); \
;     __builtin_amdgcn_global_load_lds((const unsigned*)((const char*)(gbase) + (v1)), (LAS unsigned*)(lds + (bufoff) + ldsw + 8192), 16, 0, 0); } while (0)
; #define G_LDA(dst, b, h) do { _Pragma("unroll") for (int m = 0; m < 4; ++m) _Pragma("unroll") for (int k = 0; k < 2; ++k) dst[m][k] = *(const LAS h8*)(lds + G_SA(b, h) + aoff + m * 2048 + k * 1024); } while (0)
; #define G_MMA(ai, bj, At, Bt) do { __builtin_amdgcn_s_setprio(1); _Pragma("unroll") for (int m = 0; m < 4; ++m) _Pragma("unroll") for (int n = 0; n < 2; ++n) _Pragma("unroll") for (int k = 0; k < 2; ++k) \
;     acc[ai][bj][m][n] = __builtin_amdgcn_mfma_f32_16x16x32_f16(Bt[n][k], At[m][k], acc[ai][bj][m][n], 0, 0, 0); __builtin_amdgcn_s_setprio(0); } while (0)
; #define G_WAIT_V(n) asm volatile("s_waitcnt vmcnt(" #n ")" ::: "memory")
; #define G_WAIT_L(n) asm volatile("s_waitcnt lgkmcnt(" #n ")" ::: "memory")
; #define G_BAR __builtin_amdgcn_s_barrier()
; #define G_SCHED __builtin_amdgcn_sched_barrier(0)
; template <bool PERM, class Sched, class Epi>
; DI void gemm256(LAS unsigned char* lds, const Sched& S, const Epi& E, int wv_) {
;     ...
;       G_LDA(At, 1, 1); G_STAGE(G_SA(1, 0), a3, cvA0, cvA1);
;       G_BAR; G_WAIT_L(0); G_MMA(1, 0, At, B0); G_BAR; G_SCHED;
;       G_STAGE(G_SB(1, 1), b3 + chB, cvB0, cvB1);
;       G_WAIT_V(6); G_BAR; G_MMA(1, 1, At, B1); G_BAR;
;     }
	s_waitcnt lgkmcnt(0)
	s_waitcnt lgkmcnt(0)
	v_mfma_f32_16x16x32_f16 v[118:121], v[192:195], v[160:163], v[118:121]
	v_mfma_f32_16x16x32_f16 v[114:117], v[200:203], v[160:163], v[114:117]
	v_mfma_f32_16x16x32_f16 v[102:105], v[192:195], v[168:171], v[102:105]
	v_mfma_f32_16x16x32_f16 v[98:101], v[200:203], v[168:171], v[98:101]
	v_mfma_f32_16x16x32_f16 v[86:89], v[192:195], v[176:179], v[86:89]
	v_mfma_f32_16x16x32_f16 v[82:85], v[200:203], v[176:179], v[82:85]
	v_mfma_f32_16x16x32_f16 v[70:73], v[192:195], v[184:187], v[70:73]
	v_mfma_f32_16x16x32_f16 v[66:69], v[200:203], v[184:187], v[66:69]
	v_mfma_f32_16x16x32_f16 v[118:121], v[196:199], v[164:167], v[118:121]
	v_mfma_f32_16x16x32_f16 v[114:117], v[204:207], v[164:167], v[114:117]
	v_mfma_f32_16x16x32_f16 v[102:105], v[196:199], v[172:175], v[102:105]
	v_mfma_f32_16x16x32_f16 v[98:101], v[204:207], v[172:175], v[98:101]
	v_mfma_f32_16x16x32_f16 v[86:89], v[196:199], v[180:183], v[86:89]
	v_mfma_f32_16x16x32_f16 v[82:85], v[204:207], v[180:183], v[82:85]
	v_mfma_f32_16x16x32_f16 v[70:73], v[196:199], v[188:191], v[70:73]
	v_mfma_f32_16x16x32_f16 v[66:69], v[204:207], v[188:191], v[66:69]
	s_mov_b32 m0, s37
	v_lshl_add_u64 v[208:209], v[212:213], 0, s[86:87]
	s_barrier
	ds_read_b128 v[160:163], v1 offset:49152
	ds_read_b128 v[164:167], v1 offset:50176
	ds_read_b128 v[168:171], v1 offset:51200
	ds_read_b128 v[172:175], v1 offset:52224
	ds_read_b128 v[176:179], v1 offset:53248
	ds_read_b128 v[180:183], v1 offset:54272
	ds_read_b128 v[184:187], v1 offset:55296
	ds_read_b128 v[188:191], v1 offset:56320
	global_load_lds_dwordx4 v[208:209], off
	v_lshl_add_u64 v[208:209], v[214:215], 0, s[86:87]
	s_mov_b32 m0, s52
	s_nop 0
	global_load_lds_dwordx4 v[208:209], off
	s_barrier
	s_waitcnt lgkmcnt(0)
	s_waitcnt lgkmcnt(0)
	v_mfma_f32_16x16x32_f16 v[62:65], v[144:147], v[160:163], v[62:65]
	v_mfma_f32_16x16x32_f16 v[58:61], v[152:155], v[160:163], v[58:61]
	v_mfma_f32_16x16x32_f16 v[46:49], v[144:147], v[168:171], v[46:49]
	v_mfma_f32_16x16x32_f16 v[42:45], v[152:155], v[168:171], v[42:45]
	v_mfma_f32_16x16x32_f16 v[30:33], v[144:147], v[176:179], v[30:33]
	v_mfma_f32_16x16x32_f16 v[26:29], v[152:155], v[176:179], v[26:29]
	v_mfma_f32_16x16x32_f16 v[14:17], v[144:147], v[184:187], v[14:17]
	v_mfma_f32_16x16x32_f16 v[10:13], v[152:155], v[184:187], v[10:13]
	v_mfma_f32_16x16x32_f16 v[62:65], v[148:151], v[164:167], v[62:65]
	v_mfma_f32_16x16x32_f16 v[58:61], v[156:159], v[164:167], v[58:61]
	v_mfma_f32_16x16x32_f16 v[46:49], v[148:151], v[172:175], v[46:49]
	v_mfma_f32_16x16x32_f16 v[42:45], v[156:159], v[172:175], v[42:45]
	v_mfma_f32_16x16x32_f16 v[30:33], v[148:151], v[180:183], v[30:33]
	v_mfma_f32_16x16x32_f16 v[26:29], v[156:159], v[180:183], v[26:29]
	v_mfma_f32_16x16x32_f16 v[14:17], v[148:151], v[188:191], v[14:17]
	v_mfma_f32_16x16x32_f16 v[10:13], v[156:159], v[188:191], v[10:13]
	s_barrier
	s_add_u32 s14, s14, 0x40080
	s_addc_u32 s15, s15, 0
	s_mov_b32 m0, s53
	v_lshl_add_u64 v[144:145], s[14:15], 0, v[132:133]
	global_load_lds_dwordx4 v[144:145], off
	v_lshl_add_u64 v[144:145], s[14:15], 0, v[136:137]
	s_mov_b32 m0, s56
	s_nop 0
	global_load_lds_dwordx4 v[144:145], off
	s_waitcnt vmcnt(6)
	s_barrier
	v_mfma_f32_16x16x32_f16 v[54:57], v[192:195], v[160:163], v[54:57]
	v_mfma_f32_16x16x32_f16 v[50:53], v[200:203], v[160:163], v[50:53]
	v_mfma_f32_16x16x32_f16 v[38:41], v[192:195], v[168:171], v[38:41]
	v_mfma_f32_16x16x32_f16 v[34:37], v[200:203], v[168:171], v[34:37]
	v_mfma_f32_16x16x32_f16 v[22:25], v[192:195], v[176:179], v[22:25]
	v_mfma_f32_16x16x32_f16 v[18:21], v[200:203], v[176:179], v[18:21]
	v_mfma_f32_16x16x32_f16 v[6:9], v[192:195], v[184:187], v[6:9]
	v_mfma_f32_16x16x32_f16 v[2:5], v[200:203], v[184:187], v[2:5]
	v_mfma_f32_16x16x32_f16 v[54:57], v[196:199], v[164:167], v[54:57]
	v_mfma_f32_16x16x32_f16 v[50:53], v[204:207], v[164:167], v[50:53]
	v_mfma_f32_16x16x32_f16 v[38:41], v[196:199], v[172:175], v[38:41]
	v_mfma_f32_16x16x32_f16 v[34:37], v[204:207], v[172:175], v[34:37]
	v_mfma_f32_16x16x32_f16 v[22:25], v[196:199], v[180:183], v[22:25]
	v_mfma_f32_16x16x32_f16 v[18:21], v[204:207], v[180:183], v[18:21]
	v_mfma_f32_16x16x32_f16 v[6:9], v[196:199], v[188:191], v[6:9]
	v_mfma_f32_16x16x32_f16 v[2:5], v[204:207], v[188:191], v[2:5]
	s_add_u32 s12, s12, 0x100
	s_addc_u32 s13, s13, 0
	s_add_u32 s66, s66, 0x100
	s_addc_u32 s46, s46, 0
	s_cmp_ge_i32 s68, s5
	s_mov_b32 s14, s68
	s_barrier
	s_cbranch_scc0 .LBB0_2581
	s_branch .LBB0_2583

; #define G_STAGE(bufoff, gbase, v0, v1) do { \
;     __builtin_amdgcn_global_load_lds((const unsigned*)((const char*)(gbase) + (v0)), (LAS unsigned*)(lds + (bufoff) + ldsw), 16, 0, 0); \
;     __builtin_amdgcn_global_load_lds((const unsigned*)((const char*)(gbase) + (v1)), (LAS unsigned*)(lds + (bufoff) + ldsw + 8192), 16, 0, 0); } while (0)
; #define G_LDA(dst, b, h) do { _Pragma("unroll") for (int m = 0; m < 4; ++m) _Pragma("unroll") for (int k = 0; k < 2; ++k) dst[m][k] = *(const LAS h8*)(lds + G_SA(b, h) + aoff + m * 2048 + k * 1024); } while (0)
; #define G_LDB(dst, b, h) do { _Pragma("unroll") for (int n = 0; n < 2; ++n) _Pragma("unroll") for (int k = 0; k < 2; ++k) dst[n][k] = *(const LAS h8*)(lds + G_SB(b, h) + boff + n * 2048 + k * 1024); } while (0)
; #define G_MMA(ai, bj, At, Bt) do { __builtin_amdgcn_s_setprio(1); _Pragma("unroll") for (int m = 0; m < 4; ++m) _Pragma("unroll") for (int n = 0; n < 2; ++n) _Pragma("unroll") for (int k = 0; k < 2; ++k) \
;     acc[ai][bj][m][n] = __builtin_amdgcn_mfma_f32_16x16x32_f16(Bt[n][k], At[m][k], acc[ai][bj][m][n], 0, 0, 0); __builtin_amdgcn_s_setprio(0); } while (0)
; #define G_WAIT_V(n) asm volatile("s_waitcnt vmcnt(" #n ")" ::: "memory")
; #define G_WAIT_L(n) asm volatile("s_waitcnt lgkmcnt(" #n ")" ::: "memory")
; #define G_BAR __builtin_amdgcn_s_barrier()
; #define G_SCHED __builtin_amdgcn_sched_barrier(0)
; template <bool PERM, class Sched, class Epi>
; DI void gemm256(LAS unsigned char* lds, const Sched& S, const Epi& E, int wv_) {
;     ...
;       G_LDB(B0, 0, 0); G_SCHED; G_LDA(At, 0, 0); G_STAGE(G_SA(1, 1), a1 + chA, cvA0, cvA1);
;       G_WAIT_L(8); G_BAR; G_WAIT_L(0); G_MMA(0, 0, At, B0); G_BAR; G_SCHED;
;       G_LDB(B1, 0, 1); G_STAGE(G_SB(0, 0), b2, cvB0, cvB1);
;       G_BAR; G_WAIT_L(0); G_MMA(0, 1, At, B1); G_BAR;
;       G_LDA(At, 0, 1); G_STAGE(G_SA(0, 0), a2, cvA0, cvA1);
;       G_BAR; G_WAIT_L(0); G_MMA(1, 0, At, B0); G_BAR; G_SCHED;
;       G_STAGE(G_SB(0, 1), b2 + chB, cvB0, cvB1);
;       G_WAIT_V(6); G_BAR; G_MMA(1, 1, At, B1); G_BAR;
.LBB0_2656:
	s_waitcnt vmcnt(0)
	v_or_b32_e32 v130, 0x10000, v162
	v_add_u32_e32 v134, 0x10400, v162
	v_add_u32_e32 v138, 0x10800, v162
	v_add_u32_e32 v142, 0x10c00, v162
	s_add_i32 s91, s22, 2
	ds_read_b128 v[130:133], v130
	ds_read_b128 v[134:137], v134
	ds_read_b128 v[138:141], v138
	ds_read_b128 v[142:145], v142
	s_add_u32 s23, s20, 0xfff00080
	s_addc_u32 s24, s21, -1
	s_cmp_eq_u32 s27, s22
	s_cselect_b32 s22, vcc_hi, s46
	s_cselect_b32 s25, s29, s24
	s_cselect_b32 s24, s56, s23
	s_cselect_b32 s23, vcc_lo, s74
	v_lshl_add_u64 v[192:193], s[20:21], 0, v[158:159]
	s_add_i32 m0, s35, 0xc000
	ds_read_b128 v[146:149], v1
	ds_read_b128 v[164:167], v1 offset:1024
	ds_read_b128 v[168:171], v1 offset:2048
	ds_read_b128 v[172:175], v1 offset:3072
	ds_read_b128 v[176:179], v1 offset:4096
	ds_read_b128 v[180:183], v1 offset:5120
	ds_read_b128 v[184:187], v1 offset:6144
	ds_read_b128 v[188:191], v1 offset:7168
	global_load_lds_dwordx4 v[192:193], off
	v_lshl_add_u64 v[192:193], s[20:21], 0, v[160:161]
	s_add_i32 m0, s35, 0xe000
	s_nop 0
	global_load_lds_dwordx4 v[192:193], off
	s_waitcnt lgkmcnt(8)
	s_barrier
	s_waitcnt lgkmcnt(0)
	s_waitcnt lgkmcnt(0)
	v_mfma_f32_16x16x32_f16 v[126:129], v[130:133], v[146:149], v[126:129]
	v_mfma_f32_16x16x32_f16 v[122:125], v[138:141], v[146:149], v[122:125]
	v_mfma_f32_16x16x32_f16 v[110:113], v[130:133], v[168:171], v[110:113]
	v_mfma_f32_16x16x32_f16 v[106:109], v[138:141], v[168:171], v[106:109]
	v_mfma_f32_16x16x32_f16 v[94:97], v[130:133], v[176:179], v[94:97]
	v_mfma_f32_16x16x32_f16 v[90:93], v[138:141], v[176:179], v[90:93]
	v_mfma_f32_16x16x32_f16 v[78:81], v[130:133], v[184:187], v[78:81]
	v_mfma_f32_16x16x32_f16 v[74:77], v[138:141], v[184:187], v[74:77]
	v_mfma_f32_16x16x32_f16 v[126:129], v[134:137], v[164:167], v[126:129]
	v_mfma_f32_16x16x32_f16 v[122:125], v[142:145], v[164:167], v[122:125]
	v_mfma_f32_16x16x32_f16 v[110:113], v[134:137], v[172:175], v[110:113]
	v_mfma_f32_16x16x32_f16 v[106:109], v[142:145], v[172:175], v[106:109]
	v_mfma_f32_16x16x32_f16 v[94:97], v[134:137], v[180:183], v[94:97]
	v_mfma_f32_16x16x32_f16 v[90:93], v[142:145], v[180:183], v[90:93]
	v_mfma_f32_16x16x32_f16 v[78:81], v[134:137], v[188:191], v[78:81]
	v_mfma_f32_16x16x32_f16 v[74:77], v[142:145], v[188:191], v[74:77]
	s_barrier
	v_or_b32_e32 v163, 0x14000, v162
	v_add_u32_e32 v196, 0x14400, v162
	s_mov_b32 m0, s36
	ds_read_b128 v[192:195], v163
	ds_read_b128 v[196:199], v196
	v_add_u32_e32 v163, 0x14800, v162
	v_add_u32_e32 v204, 0x14c00, v162
	v_lshl_add_u64 v[208:209], s[22:23], 0, v[150:151]
	ds_read_b128 v[200:203], v163
	ds_read_b128 v[204:207], v204
	global_load_lds_dwordx4 v[208:209], off
	v_lshl_add_u64 v[210:211], s[22:23], 0, v[152:153]
	s_mov_b32 m0, s37
	s_nop 0
	global_load_lds_dwordx4 v[210:211], off
	s_barrier
	s_waitcnt lgkmcnt(0)
	s_waitcnt lgkmcnt(0)
	v_mfma_f32_16x16x32_f16 v[118:121], v[192:195], v[146:149], v[118:121]
	v_mfma_f32_16x16x32_f16 v[114:117], v[200:203], v[146:149], v[114:117]
	v_mfma_f32_16x16x32_f16 v[102:105], v[192:195], v[168:171], v[102:105]
	v_mfma_f32_16x16x32_f16 v[98:101], v[200:203], v[168:171], v[98:101]
	v_mfma_f32_16x16x32_f16 v[86:89], v[192:195], v[176:179], v[86:89]
	v_mfma_f32_16x16x32_f16 v[82:85], v[200:203], v[176:179], v[82:85]
	v_mfma_f32_16x16x32_f16 v[70:73], v[192:195], v[184:187], v[70:73]
	v_mfma_f32_16x16x32_f16 v[66:69], v[200:203], v[184:187], v[66:69]
	v_mfma_f32_16x16x32_f16 v[118:121], v[196:199], v[164:167], v[118:121]
	v_mfma_f32_16x16x32_f16 v[114:117], v[204:207], v[164:167], v[114:117]
	v_mfma_f32_16x16x32_f16 v[102:105], v[196:199], v[172:175], v[102:105]
	v_mfma_f32_16x16x32_f16 v[98:101], v[204:207], v[172:175], v[98:101]
	v_mfma_f32_16x16x32_f16 v[86:89], v[196:199], v[180:183], v[86:89]
	v_mfma_f32_16x16x32_f16 v[82:85], v[204:207], v[180:183], v[82:85]
	v_mfma_f32_16x16x32_f16 v[70:73], v[196:199], v[188:191], v[70:73]
	v_mfma_f32_16x16x32_f16 v[66:69], v[204:207], v[188:191], v[66:69]
	s_mov_b32 m0, s35
	v_lshl_add_u64 v[212:213], s[24:25], 0, v[150:151]
	s_barrier
	ds_read_b128 v[146:149], v1 offset:16384
	ds_read_b128 v[164:167], v1 offset:17408
	ds_read_b128 v[168:171], v1 offset:18432
	ds_read_b128 v[172:175], v1 offset:19456
	ds_read_b128 v[176:179], v1 offset:20480
	ds_read_b128 v[180:183], v1 offset:21504
	ds_read_b128 v[184:187], v1 offset:22528
	ds_read_b128 v[188:191], v1 offset:23552
	global_load_lds_dwordx4 v[212:213], off
	v_lshl_add_u64 v[214:215], s[24:25], 0, v[152:153]
	s_mov_b32 m0, s52
	s_nop 0
	global_load_lds_dwordx4 v[214:215], off
	s_barrier
	s_waitcnt lgkmcnt(0)
	s_waitcnt lgkmcnt(0)
	v_mfma_f32_16x16x32_f16 v[62:65], v[130:133], v[146:149], v[62:65]
	v_mfma_f32_16x16x32_f16 v[58:61], v[138:141], v[146:149], v[58:61]
	v_mfma_f32_16x16x32_f16 v[46:49], v[130:133], v[168:171], v[46:49]
	v_mfma_f32_16x16x32_f16 v[42:45], v[138:141], v[168:171], v[42:45]
	v_mfma_f32_16x16x32_f16 v[30:33], v[130:133], v[176:179], v[30:33]
	v_mfma_f32_16x16x32_f16 v[26:29], v[138:141], v[176:179], v[26:29]
	v_mfma_f32_16x16x32_f16 v[14:17], v[130:133], v[184:187], v[14:17]
	v_mfma_f32_16x16x32_f16 v[10:13], v[138:141], v[184:187], v[10:13]
	v_mfma_f32_16x16x32_f16 v[62:65], v[134:137], v[164:167], v[62:65]
	v_mfma_f32_16x16x32_f16 v[58:61], v[142:145], v[164:167], v[58:61]
	v_mfma_f32_16x16x32_f16 v[46:49], v[134:137], v[172:175], v[46:49]
	v_mfma_f32_16x16x32_f16 v[42:45], v[142:145], v[172:175], v[42:45]
	v_mfma_f32_16x16x32_f16 v[30:33], v[134:137], v[180:183], v[30:33]
	v_mfma_f32_16x16x32_f16 v[26:29], v[142:145], v[180:183], v[26:29]
	v_mfma_f32_16x16x32_f16 v[14:17], v[134:137], v[188:191], v[14:17]
	v_mfma_f32_16x16x32_f16 v[10:13], v[142:145], v[188:191], v[10:13]
	s_barrier
; #define G_STAGE(bufoff, gbase, v0, v1) do { \
;     __builtin_amdgcn_global_load_lds((const unsigned*)((const char*)(gbase) + (v0)), (LAS unsigned*)(lds + (bufoff) + ldsw), 16, 0, 0); \
;     __builtin_amdgcn_global_load_lds((const unsigned*)((const char*)(gbase) + (v1)), (LAS unsigned*)(lds + (bufoff) + ldsw + 8192), 16, 0, 0); } while (0)
; #define G_LDA(dst, b, h) do { _Pragma("unroll") for (int m = 0; m < 4; ++m) _Pragma("unroll") for (int k = 0; k < 2; ++k) dst[m][k] = *(const LAS h8*)(lds + G_SA(b, h) + aoff + m * 2048 + k * 1024); } while (0)
; #define G_LDB(dst, b, h) do { _Pragma("unroll") for (int n = 0; n < 2; ++n) _Pragma("unroll") for (int k = 0; k < 2; ++k) dst[n][k] = *(const LAS h8*)(lds + G_SB(b, h) + boff + n * 2048 + k * 1024); } while (0)
; #define G_MMA(ai, bj, At, Bt) do { __builtin_amdgcn_s_setprio(1); _Pragma("unroll") for (int m = 0; m < 4; ++m) _Pragma("unroll") for (int n = 0; n < 2; ++n) _Pragma("unroll") for (int k = 0; k < 2; ++k) \
;     acc[ai][bj][m][n] = __builtin_amdgcn_mfma_f32_16x16x32_f16(Bt[n][k], At[m][k], acc[ai][bj][m][n], 0, 0, 0); __builtin_amdgcn_s_setprio(0); } while (0)
; #define G_WAIT_V(n) asm volatile("s_waitcnt vmcnt(" #n ")" ::: "memory")
; #define G_WAIT_L(n) asm volatile("s_waitcnt lgkmcnt(" #n ")" ::: "memory")
; #define G_BAR __builtin_amdgcn_s_barrier()
; #define G_SCHED __builtin_amdgcn_sched_barrier(0)
; template <bool PERM, class Sched, class Epi>
; DI void gemm256(LAS unsigned char* lds, const Sched& S, const Epi& E, int wv_) {
;     ...
;       G_STAGE(G_SB(0, 1), b2 + chB, cvB0, cvB1);
;       G_WAIT_V(6); G_BAR; G_MMA(1, 1, At, B1); G_BAR;
;       G_LDB(B0, 1, 0); G_SCHED; G_LDA(At, 1, 0); G_STAGE(G_SA(0, 1), a2 + chA, cvA0, cvA1);
;       G_WAIT_L(8); G_BAR; G_WAIT_L(0); G_MMA(0, 0, At, B0); G_BAR; G_SCHED;
;       G_LDB(B1, 1, 1); G_STAGE(G_SB(1, 0), b3, cvB0, cvB1);
;       G_BAR; G_WAIT_L(0); G_MMA(0, 1, At, B1); G_BAR;
;       G_LDA(At, 1, 1); G_STAGE(G_SA(1, 0), a3, cvA0, cvA1);
;       G_BAR; G_WAIT_L(0); G_MMA(1, 0, At, B0); G_BAR; G_SCHED;
	s_add_u32 s40, s22, 0x100000
	s_addc_u32 s41, s23, 0
	s_mov_b32 m0, s53
	v_lshl_add_u64 v[130:131], s[40:41], 0, v[150:151]
	global_load_lds_dwordx4 v[130:131], off
	v_lshl_add_u64 v[130:131], s[40:41], 0, v[152:153]
	s_mov_b32 m0, s58
	s_nop 0
	global_load_lds_dwordx4 v[130:131], off
	s_waitcnt vmcnt(6)
	s_barrier
	v_mfma_f32_16x16x32_f16 v[54:57], v[192:195], v[146:149], v[54:57]
	v_mfma_f32_16x16x32_f16 v[50:53], v[200:203], v[146:149], v[50:53]
	v_mfma_f32_16x16x32_f16 v[38:41], v[192:195], v[168:171], v[38:41]
	v_mfma_f32_16x16x32_f16 v[34:37], v[200:203], v[168:171], v[34:37]
	v_mfma_f32_16x16x32_f16 v[22:25], v[192:195], v[176:179], v[22:25]
	v_mfma_f32_16x16x32_f16 v[18:21], v[200:203], v[176:179], v[18:21]
	v_mfma_f32_16x16x32_f16 v[6:9], v[192:195], v[184:187], v[6:9]
	v_mfma_f32_16x16x32_f16 v[2:5], v[200:203], v[184:187], v[2:5]
	v_mfma_f32_16x16x32_f16 v[54:57], v[196:199], v[164:167], v[54:57]
	v_mfma_f32_16x16x32_f16 v[50:53], v[204:207], v[164:167], v[50:53]
	v_mfma_f32_16x16x32_f16 v[38:41], v[196:199], v[172:175], v[38:41]
	v_mfma_f32_16x16x32_f16 v[34:37], v[204:207], v[172:175], v[34:37]
	v_mfma_f32_16x16x32_f16 v[22:25], v[196:199], v[180:183], v[22:25]
	v_mfma_f32_16x16x32_f16 v[18:21], v[204:207], v[180:183], v[18:21]
	v_mfma_f32_16x16x32_f16 v[6:9], v[196:199], v[188:191], v[6:9]
	v_mfma_f32_16x16x32_f16 v[2:5], v[204:207], v[188:191], v[2:5]
	v_or_b32_e32 v130, 0x18000, v162
	v_add_u32_e32 v134, 0x18400, v162
	v_add_u32_e32 v138, 0x18800, v162
	v_add_u32_e32 v142, 0x18c00, v162
	s_barrier
	ds_read_b128 v[130:133], v130
	ds_read_b128 v[134:137], v134
	ds_read_b128 v[138:141], v138
	ds_read_b128 v[142:145], v142
	s_add_u32 s24, s24, 0x100000
	s_addc_u32 s25, s25, 0
	s_mov_b32 m0, s59
	v_lshl_add_u64 v[192:193], s[24:25], 0, v[150:151]
	ds_read_b128 v[146:149], v1 offset:32768
	ds_read_b128 v[164:167], v1 offset:33792
	ds_read_b128 v[168:171], v1 offset:34816
	ds_read_b128 v[172:175], v1 offset:35840
	ds_read_b128 v[176:179], v1 offset:36864
	ds_read_b128 v[180:183], v1 offset:37888
	ds_read_b128 v[184:187], v1 offset:38912
	ds_read_b128 v[188:191], v1 offset:39936
	global_load_lds_dwordx4 v[192:193], off
	v_lshl_add_u64 v[192:193], s[24:25], 0, v[152:153]
	s_mov_b32 m0, s61
	s_nop 0
	global_load_lds_dwordx4 v[192:193], off
	s_waitcnt lgkmcnt(8)
	s_barrier
	s_waitcnt lgkmcnt(0)
	s_waitcnt lgkmcnt(0)
	v_mfma_f32_16x16x32_f16 v[126:129], v[130:133], v[146:149], v[126:129]
	v_mfma_f32_16x16x32_f16 v[122:125], v[138:141], v[146:149], v[122:125]
	v_mfma_f32_16x16x32_f16 v[110:113], v[130:133], v[168:171], v[110:113]
	v_mfma_f32_16x16x32_f16 v[106:109], v[138:141], v[168:171], v[106:109]
	v_mfma_f32_16x16x32_f16 v[94:97], v[130:133], v[176:179], v[94:97]
	v_mfma_f32_16x16x32_f16 v[90:93], v[138:141], v[176:179], v[90:93]
	v_mfma_f32_16x16x32_f16 v[78:81], v[130:133], v[184:187], v[78:81]
	v_mfma_f32_16x16x32_f16 v[74:77], v[138:141], v[184:187], v[74:77]
	v_mfma_f32_16x16x32_f16 v[126:129], v[134:137], v[164:167], v[126:129]
	v_mfma_f32_16x16x32_f16 v[122:125], v[142:145], v[164:167], v[122:125]
	v_mfma_f32_16x16x32_f16 v[110:113], v[134:137], v[172:175], v[110:113]
	v_mfma_f32_16x16x32_f16 v[106:109], v[142:145], v[172:175], v[106:109]
	v_mfma_f32_16x16x32_f16 v[94:97], v[134:137], v[180:183], v[94:97]
	v_mfma_f32_16x16x32_f16 v[90:93], v[142:145], v[180:183], v[90:93]
	v_mfma_f32_16x16x32_f16 v[78:81], v[134:137], v[188:191], v[78:81]
	v_mfma_f32_16x16x32_f16 v[74:77], v[142:145], v[188:191], v[74:77]
	s_barrier
	v_or_b32_e32 v163, 0x1c000, v162
	v_add_u32_e32 v196, 0x1c400, v162
	s_mov_b32 m0, s69
	ds_read_b128 v[192:195], v163
	ds_read_b128 v[196:199], v196
	v_add_u32_e32 v163, 0x1c800, v162
	v_add_u32_e32 v204, 0x1cc00, v162
	v_lshl_add_u64 v[208:209], v[208:209], 0, s[86:87]
	ds_read_b128 v[200:203], v163
	ds_read_b128 v[204:207], v204
	global_load_lds_dwordx4 v[208:209], off
	v_lshl_add_u64 v[208:209], v[210:211], 0, s[86:87]
	s_mov_b32 m0, s78
	s_nop 0
	global_load_lds_dwordx4 v[208:209], off
	s_barrier
; #define G_STAGE(bufoff, gbase, v0, v1) do { \
;     __builtin_amdgcn_global_load_lds((const unsigned*)((const char*)(gbase) + (v0)), (LAS unsigned*)(lds + (bufoff) + ldsw), 16, 0, 0); \
;     __builtin_amdgcn_global_load_lds((const unsigned*)((const char*)(gbase) + (v1)), (LAS unsigned*)(lds + (bufoff) + ldsw + 8192), 16, 0, 0); } while (0)
; #define G_LDA(dst, b, h) do { _Pragma("unroll") for (int m = 0; m < 4; ++m) _Pragma("unroll") for (int k = 0; k < 2; ++k) dst[m][k] = *(const LAS h8*)(lds + G_SA(b, h) + aoff + m * 2048 + k * 1024); } while (0)
; #define G_MMA(ai, bj, At, Bt) do { __builtin_amdgcn_s_setprio(1); _Pragma("unroll") for (int m = 0; m < 4; ++m) _Pragma("unroll") for (int n = 0; n < 2; ++n) _Pragma("unroll") for (int k = 0; k < 2; ++k) \
;     acc[ai][bj][m][n] = __builtin_amdgcn_mfma_f32_16x16x32_f16(Bt[n][k], At[m][k], acc[ai][bj][m][n], 0, 0, 0); __builtin_amdgcn_s_setprio(0); } while (0)
; #define G_WAIT_V(n) asm volatile("s_waitcnt vmcnt(" #n ")" ::: "memory")
; #define G_WAIT_L(n) asm volatile("s_waitcnt lgkmcnt(" #n ")" ::: "memory")
; #define G_BAR __builtin_amdgcn_s_barrier()
; #define G_SCHED __builtin_amdgcn_sched_barrier(0)
; template <bool PERM, class Sched, class Epi>
; DI void gemm256(LAS unsigned char* lds, const Sched& S, const Epi& E, int wv_) {
;     ...
;       G_LDA(At, 1, 1); G_STAGE(G_SA(1, 0), a3, cvA0, cvA1);
;       G_BAR; G_WAIT_L(0); G_MMA(1, 0, At, B0); G_BAR; G_SCHED;
;       G_STAGE(G_SB(1, 1), b3 + chB, cvB0, cvB1);
;       G_WAIT_V(6); G_BAR; G_MMA(1, 1, At, B1); G_BAR;
;     }
	s_waitcnt lgkmcnt(0)
	s_waitcnt lgkmcnt(0)
	v_mfma_f32_16x16x32_f16 v[118:121], v[192:195], v[146:149], v[118:121]
	v_mfma_f32_16x16x32_f16 v[114:117], v[200:203], v[146:149], v[114:117]
	v_mfma_f32_16x16x32_f16 v[102:105], v[192:195], v[168:171], v[102:105]
	v_mfma_f32_16x16x32_f16 v[98:101], v[200:203], v[168:171], v[98:101]
	v_mfma_f32_16x16x32_f16 v[86:89], v[192:195], v[176:179], v[86:89]
	v_mfma_f32_16x16x32_f16 v[82:85], v[200:203], v[176:179], v[82:85]
	v_mfma_f32_16x16x32_f16 v[70:73], v[192:195], v[184:187], v[70:73]
	v_mfma_f32_16x16x32_f16 v[66:69], v[200:203], v[184:187], v[66:69]
	v_mfma_f32_16x16x32_f16 v[118:121], v[196:199], v[164:167], v[118:121]
	v_mfma_f32_16x16x32_f16 v[114:117], v[204:207], v[164:167], v[114:117]
	v_mfma_f32_16x16x32_f16 v[102:105], v[196:199], v[172:175], v[102:105]
	v_mfma_f32_16x16x32_f16 v[98:101], v[204:207], v[172:175], v[98:101]
	v_mfma_f32_16x16x32_f16 v[86:89], v[196:199], v[180:183], v[86:89]
	v_mfma_f32_16x16x32_f16 v[82:85], v[204:207], v[180:183], v[82:85]
	v_mfma_f32_16x16x32_f16 v[70:73], v[196:199], v[188:191], v[70:73]
	v_mfma_f32_16x16x32_f16 v[66:69], v[204:207], v[188:191], v[66:69]
	s_mov_b32 m0, s79
	v_lshl_add_u64 v[208:209], v[212:213], 0, s[86:87]
	s_barrier
	ds_read_b128 v[146:149], v1 offset:49152
	ds_read_b128 v[164:167], v1 offset:50176
	ds_read_b128 v[168:171], v1 offset:51200
	ds_read_b128 v[172:175], v1 offset:52224
	ds_read_b128 v[176:179], v1 offset:53248
	ds_read_b128 v[180:183], v1 offset:54272
	ds_read_b128 v[184:187], v1 offset:55296
	ds_read_b128 v[188:191], v1 offset:56320
	global_load_lds_dwordx4 v[208:209], off
	v_lshl_add_u64 v[208:209], v[214:215], 0, s[86:87]
	s_mov_b32 m0, s83
	s_nop 0
	global_load_lds_dwordx4 v[208:209], off
	s_barrier
	s_waitcnt lgkmcnt(0)
	s_waitcnt lgkmcnt(0)
	v_mfma_f32_16x16x32_f16 v[62:65], v[130:133], v[146:149], v[62:65]
	v_mfma_f32_16x16x32_f16 v[58:61], v[138:141], v[146:149], v[58:61]
	v_mfma_f32_16x16x32_f16 v[46:49], v[130:133], v[168:171], v[46:49]
	v_mfma_f32_16x16x32_f16 v[42:45], v[138:141], v[168:171], v[42:45]
	v_mfma_f32_16x16x32_f16 v[30:33], v[130:133], v[176:179], v[30:33]
	v_mfma_f32_16x16x32_f16 v[26:29], v[138:141], v[176:179], v[26:29]
	v_mfma_f32_16x16x32_f16 v[14:17], v[130:133], v[184:187], v[14:17]
	v_mfma_f32_16x16x32_f16 v[10:13], v[138:141], v[184:187], v[10:13]
	v_mfma_f32_16x16x32_f16 v[62:65], v[134:137], v[164:167], v[62:65]
	v_mfma_f32_16x16x32_f16 v[58:61], v[142:145], v[164:167], v[58:61]
	v_mfma_f32_16x16x32_f16 v[46:49], v[134:137], v[172:175], v[46:49]
	v_mfma_f32_16x16x32_f16 v[42:45], v[142:145], v[172:175], v[42:45]
	v_mfma_f32_16x16x32_f16 v[30:33], v[134:137], v[180:183], v[30:33]
	v_mfma_f32_16x16x32_f16 v[26:29], v[142:145], v[180:183], v[26:29]
	v_mfma_f32_16x16x32_f16 v[14:17], v[134:137], v[188:191], v[14:17]
	v_mfma_f32_16x16x32_f16 v[10:13], v[142:145], v[188:191], v[10:13]
	s_barrier
	s_add_u32 s22, s22, 0x100080
	s_addc_u32 s23, s23, 0
	s_mov_b32 m0, s84
	v_lshl_add_u64 v[130:131], s[22:23], 0, v[150:151]
	global_load_lds_dwordx4 v[130:131], off
	v_lshl_add_u64 v[130:131], s[22:23], 0, v[152:153]
	s_mov_b32 m0, s85
	s_nop 0
	global_load_lds_dwordx4 v[130:131], off
	s_waitcnt vmcnt(6)
	s_barrier
	v_mfma_f32_16x16x32_f16 v[54:57], v[192:195], v[146:149], v[54:57]
	v_mfma_f32_16x16x32_f16 v[50:53], v[200:203], v[146:149], v[50:53]
	v_mfma_f32_16x16x32_f16 v[38:41], v[192:195], v[168:171], v[38:41]
	v_mfma_f32_16x16x32_f16 v[34:37], v[200:203], v[168:171], v[34:37]
	v_mfma_f32_16x16x32_f16 v[22:25], v[192:195], v[176:179], v[22:25]
	v_mfma_f32_16x16x32_f16 v[18:21], v[200:203], v[176:179], v[18:21]
	v_mfma_f32_16x16x32_f16 v[6:9], v[192:195], v[184:187], v[6:9]
	v_mfma_f32_16x16x32_f16 v[2:5], v[200:203], v[184:187], v[2:5]
	v_mfma_f32_16x16x32_f16 v[54:57], v[196:199], v[164:167], v[54:57]
	v_mfma_f32_16x16x32_f16 v[50:53], v[204:207], v[164:167], v[50:53]
	v_mfma_f32_16x16x32_f16 v[38:41], v[196:199], v[172:175], v[38:41]
	v_mfma_f32_16x16x32_f16 v[34:37], v[204:207], v[172:175], v[34:37]
	v_mfma_f32_16x16x32_f16 v[22:25], v[196:199], v[180:183], v[22:25]
	v_mfma_f32_16x16x32_f16 v[18:21], v[204:207], v[180:183], v[18:21]
	v_mfma_f32_16x16x32_f16 v[6:9], v[196:199], v[188:191], v[6:9]
	v_mfma_f32_16x16x32_f16 v[2:5], v[204:207], v[188:191], v[2:5]
	s_add_u32 s20, s20, 0x100
	s_addc_u32 s21, s21, 0
	s_add_u32 s46, s46, 0x100
	s_addc_u32 s74, s74, 0
	s_cmp_ge_i32 s91, s75
	s_mov_b32 s22, s91
	s_barrier
	s_cbranch_scc0 .LBB0_2656
	v_readlane_b32 s91, v254, 47
	s_mov_b32 s56, 0x8fff
	s_branch .LBB0_2659
